# combined small edits: V/T helper load addressing hoisted, QKROPE head sums and DNT solve reads rescheduled (DPP / earlier issue), pre-packed state operands
# baseline (speedup 1.0000x reference)
; #define BAR_LDS() do { asm volatile("s_waitcnt lgkmcnt(0)" ::: "memory"); __builtin_amdgcn_s_barrier(); asm volatile("" ::: "memory"); } while (0)
; template <int W> __device__ __forceinline__ void dn_solve(const LAS float* Mf, float (&t)[16], int lane) {
;     const int j = 16 * W + (lane >> 2), q = lane & 3;
; #pragma unroll
;     for (int s = 0; s < 16; ++s) t[s] = 0.f;
; #pragma unroll
;     for (int i = 16 * W; i < 64; ++i) {
;         float acc = 0.f;
; #pragma unroll
;         for (int s = 4 * W; s <= (i - 1) / 4 && i > 16 * W; ++s) acc += Mf[i * 64 + 4 * s + q] * t[s];
;         acc += __shfl_xor(acc, 1); acc += __shfl_xor(acc, 2);
;         const float val = (i == j ? 1.f : 0.f) - acc;
;         if (q == (i & 3)) t[i >> 2] = val;
;         asm volatile("" : "+v"(t[0]), "+v"(t[1]), "+v"(t[2]), "+v"(t[3]), "+v"(t[4]), "+v"(t[5]), "+v"(t[6]), "+v"(t[7]), "+v"(t[8]), "+v"(t[9]), "+v"(t[10]), "+v"(t[11]), "+v"(t[12]), "+v"(t[13]), "+v"(t[14]), "+v"(t[15]));
; __device__ __forceinline__ void dn_t_phase(LAS unsigned char* lds, const bf16_t* P, float* AB, bf16_t* TP, const float* a_log, const float* dt_bias, int G) {
;     ...
;                 Mf[i * 64 + j] = (i > j) ? sc_beta[i] * acc[x] * __expf(sc_gc[i] - gj) : 0.f; }
;         }
;         BAR_LDS();
;         float tc[16];
;         if (w == 0) dn_solve<0>(Mf, tc, lane); else if (w == 1) dn_solve<1>(Mf, tc, lane); else if (w == 2) dn_solve<2>(Mf, tc, lane); else dn_solve<3>(Mf, tc, lane);
.LBB0_108:
	s_or_b64 exec, exec, s[0:1]
	v_lshl_add_u32 v3, v3, 8, v36
	ds_write_b32 v3, v2 offset:17408
	v_and_b32_e32 v3, 64, v190
	v_xor_b32_e32 v2, 1, v190
	v_add_u32_e32 v3, 64, v3
	v_cmp_lt_i32_e32 vcc, v2, v3
	v_and_b32_e32 v52, 3, v49
	s_waitcnt lgkmcnt(0)
	s_barrier
	v_cndmask_b32_e32 v2, v190, v2, vcc
	v_lshlrev_b32_e32 v54, 2, v2
	v_xor_b32_e32 v2, 2, v190
	v_cmp_lt_i32_e32 vcc, v2, v3
	v_cmp_eq_u32_e64 s[42:43], 0, v52
	v_lshrrev_b32_e32 v53, 2, v34
	v_cndmask_b32_e32 v2, v190, v2, vcc
	v_cmp_gt_u32_e32 vcc, 4, v34
	s_and_b64 s[0:1], s[42:43], vcc
	v_lshl_add_u32 v56, v52, 2, s19
	v_lshlrev_b32_e32 v55, 2, v2
	v_cndmask_b32_e64 v57, 0, 1.0, s[0:1]
	s_cmp_lt_i32 s80, 2
	s_mov_b64 s[0:1], -1
	s_cbranch_scc1 .LBB0_114
	s_cmp_gt_i32 s80, 2
	s_cbranch_scc0 .LBB0_111
	v_mov_b32_e32 v2, v1
	v_mov_b32_e32 v4, v1
	v_mov_b32_e32 v6, v1
	v_mov_b32_e32 v8, v1
	v_mov_b32_e32 v10, v1
	v_mov_b32_e32 v12, v1
	v_mov_b32_e32 v14, v1
	v_mov_b32_e32 v16, v1
	v_mov_b32_e32 v34, v1
	v_mov_b32_e32 v36, v1
	v_mov_b32_e32 v38, v1
	v_mov_b32_e32 v40, v1
	v_mov_b32_e32 v5, v1
	v_mov_b32_e32 v7, v1
	v_mov_b32_e32 v3, v1
	v_mov_b32_e32 v9, v57
	ds_read_b32 v11, v56 offset:30144
	v_cmp_eq_u32_e32 vcc, 1, v53
	v_cmp_eq_u32_e64 s[44:45], 1, v52
	v_cmp_eq_u32_e64 s[0:1], 2, v52
	v_cndmask_b32_e64 v15, 0, 1.0, vcc
	s_waitcnt lgkmcnt(0)
	v_fma_f32 v11, v11, v9, 0
	v_cmp_eq_u32_e32 vcc, 2, v53
	v_cmp_eq_u32_e64 s[46:47], 4, v53
	s_waitcnt lgkmcnt(0)
	s_nop 1
	v_add_f32_dpp v11, v11, v11 quad_perm:[1,0,3,2] row_mask:0xf bank_mask:0xf
	s_nop 1
	v_add_f32_dpp v11, v11, v11 quad_perm:[2,3,0,1] row_mask:0xf bank_mask:0xf
	v_sub_f32_e32 v11, v15, v11
	v_cndmask_b32_e64 v9, v9, v11, s[44:45]
	ds_read_b32 v11, v56 offset:30400
	v_cndmask_b32_e64 v15, 0, 1.0, vcc
	v_cmp_eq_u32_e32 vcc, 3, v53
	s_waitcnt lgkmcnt(0)
	v_fma_f32 v11, v11, v9, 0
	s_nop 1
	v_add_f32_dpp v11, v11, v11 quad_perm:[1,0,3,2] row_mask:0xf bank_mask:0xf
	s_nop 1
	v_add_f32_dpp v11, v11, v11 quad_perm:[2,3,0,1] row_mask:0xf bank_mask:0xf
	v_sub_f32_e32 v11, v15, v11
	v_cndmask_b32_e64 v9, v9, v11, s[0:1]
	ds_read_b32 v11, v56 offset:30656
	v_cndmask_b32_e64 v15, 0, 1.0, vcc
	v_cmp_eq_u32_e32 vcc, 3, v52
	s_waitcnt lgkmcnt(0)
	v_fma_f32 v11, v11, v9, 0
	s_nop 1
	v_add_f32_dpp v11, v11, v11 quad_perm:[1,0,3,2] row_mask:0xf bank_mask:0xf
	s_nop 1
	v_add_f32_dpp v11, v11, v11 quad_perm:[2,3,0,1] row_mask:0xf bank_mask:0xf
	v_sub_f32_e32 v11, v15, v11
	v_cndmask_b32_e32 v42, v9, v11, vcc
	ds_read_b32 v9, v56 offset:30912
	v_cndmask_b32_e64 v13, 0, 1.0, s[46:47]
	v_add_u32_e32 v15, 0x7800, v56
	v_cmp_eq_u32_e64 s[46:47], 5, v53
	s_waitcnt lgkmcnt(0)
	ds_read2_b32 v[44:45], v15 offset0:112 offset1:116
	v_fma_f32 v9, v9, v42, 0
	s_nop 1
	v_add_f32_dpp v9, v9, v9 quad_perm:[1,0,3,2] row_mask:0xf bank_mask:0xf
	s_nop 1
	v_add_f32_dpp v9, v9, v9 quad_perm:[2,3,0,1] row_mask:0xf bank_mask:0xf
	v_sub_f32_e32 v9, v13, v9
	v_cndmask_b32_e64 v43, v5, v9, s[42:43]
	v_cndmask_b32_e64 v11, 0, 1.0, s[46:47]
	v_cmp_eq_u32_e64 s[46:47], 6, v53
	v_add_u32_e32 v13, 0x7c00, v56
	s_waitcnt lgkmcnt(0)
	v_pk_mul_f32 v[44:45], v[44:45], v[42:43]
	s_nop 0
	v_add_f32_e32 v5, 0, v44
	v_add_f32_e32 v5, v5, v45
	ds_read2_b32 v[44:45], v15 offset0:176 offset1:180
	s_nop 1
	v_add_f32_dpp v5, v5, v5 quad_perm:[1,0,3,2] row_mask:0xf bank_mask:0xf
	s_nop 1
	v_add_f32_dpp v5, v5, v5 quad_perm:[2,3,0,1] row_mask:0xf bank_mask:0xf
	v_sub_f32_e32 v5, v11, v5
	v_cndmask_b32_e64 v43, v43, v5, s[44:45]
	v_cndmask_b32_e64 v11, 0, 1.0, s[46:47]
	v_cmp_eq_u32_e64 s[46:47], 7, v53
	s_waitcnt lgkmcnt(0)
	v_pk_mul_f32 v[44:45], v[44:45], v[42:43]
	s_nop 0
	v_add_f32_e32 v5, 0, v44
	v_add_f32_e32 v5, v5, v45
	ds_read2_b32 v[44:45], v15 offset0:240 offset1:244
	s_nop 1
	v_add_f32_dpp v5, v5, v5 quad_perm:[1,0,3,2] row_mask:0xf bank_mask:0xf
	s_nop 1
	v_add_f32_dpp v5, v5, v5 quad_perm:[2,3,0,1] row_mask:0xf bank_mask:0xf
	v_sub_f32_e32 v5, v11, v5
	v_cndmask_b32_e64 v43, v43, v5, s[0:1]
	v_cndmask_b32_e64 v11, 0, 1.0, s[46:47]
	v_cmp_eq_u32_e64 s[46:47], 8, v53
	s_waitcnt lgkmcnt(0)
	ds_read2_b32 v[46:47], v13 offset0:48 offset1:52
	v_pk_mul_f32 v[44:45], v[44:45], v[42:43]
	s_nop 0
	v_add_f32_e32 v5, 0, v44
	v_add_f32_e32 v5, v5, v45
	s_nop 1
	v_add_f32_dpp v5, v5, v5 quad_perm:[1,0,3,2] row_mask:0xf bank_mask:0xf
	s_nop 1
	v_add_f32_dpp v5, v5, v5 quad_perm:[2,3,0,1] row_mask:0xf bank_mask:0xf
	v_sub_f32_e32 v5, v11, v5
	v_cndmask_b32_e32 v44, v43, v5, vcc
	v_mov_b32_e32 v43, v44
	v_cndmask_b32_e64 v11, 0, 1.0, s[46:47]
	v_cmp_eq_u32_e64 s[46:47], 9, v53
	s_waitcnt lgkmcnt(0)
	v_pk_mul_f32 v[46:47], v[46:47], v[42:43]
	s_nop 0
	v_add_f32_e32 v5, 0, v46
	v_add_f32_e32 v5, v5, v47
	ds_read2_b32 v[46:47], v13 offset0:112 offset1:116
	ds_read_b32 v59, v56 offset:32224
	s_nop 1
	v_add_f32_dpp v5, v5, v5 quad_perm:[1,0,3,2] row_mask:0xf bank_mask:0xf
	s_nop 1
	v_add_f32_dpp v5, v5, v5 quad_perm:[2,3,0,1] row_mask:0xf bank_mask:0xf
	v_sub_f32_e32 v5, v11, v5
	v_cndmask_b32_e64 v45, v7, v5, s[42:43]
	v_cndmask_b32_e64 v9, 0, 1.0, s[46:47]
	v_cmp_eq_u32_e64 s[46:47], 10, v53
	v_add_u32_e32 v11, 0x8000, v56
	s_waitcnt lgkmcnt(1)
	v_mov_b32_e32 v58, v47
	v_fma_f32 v5, v46, v42, 0
	s_waitcnt lgkmcnt(0)
	v_pk_mul_f32 v[46:47], v[44:45], v[58:59]
	s_nop 0
	v_add_f32_e32 v5, v5, v46
	v_add_f32_e32 v5, v5, v47
	ds_read2_b32 v[46:47], v13 offset0:176 offset1:180
	ds_read_b32 v59, v56 offset:32480
	s_nop 1
	v_add_f32_dpp v5, v5, v5 quad_perm:[1,0,3,2] row_mask:0xf bank_mask:0xf
	s_nop 1
	v_add_f32_dpp v5, v5, v5 quad_perm:[2,3,0,1] row_mask:0xf bank_mask:0xf
	v_sub_f32_e32 v5, v9, v5
	v_cndmask_b32_e64 v45, v45, v5, s[44:45]
	v_cndmask_b32_e64 v9, 0, 1.0, s[46:47]
	v_cmp_eq_u32_e64 s[46:47], 11, v53
	s_waitcnt lgkmcnt(1)
; template <int W> __device__ __forceinline__ void dn_solve(const LAS float* Mf, float (&t)[16], int lane) {
;     const int j = 16 * W + (lane >> 2), q = lane & 3;
; #pragma unroll
;     for (int s = 0; s < 16; ++s) t[s] = 0.f;
; #pragma unroll
;     for (int i = 16 * W; i < 64; ++i) {
;         float acc = 0.f;
; #pragma unroll
;         for (int s = 4 * W; s <= (i - 1) / 4 && i > 16 * W; ++s) acc += Mf[i * 64 + 4 * s + q] * t[s];
;         acc += __shfl_xor(acc, 1); acc += __shfl_xor(acc, 2);
;         const float val = (i == j ? 1.f : 0.f) - acc;
;         if (q == (i & 3)) t[i >> 2] = val;
;         asm volatile("" : "+v"(t[0]), "+v"(t[1]), "+v"(t[2]), "+v"(t[3]), "+v"(t[4]), "+v"(t[5]), "+v"(t[6]), "+v"(t[7]), "+v"(t[8]), "+v"(t[9]), "+v"(t[10]), "+v"(t[11]), "+v"(t[12]), "+v"(t[13]), "+v"(t[14]), "+v"(t[15]));
; __device__ __forceinline__ void dn_t_phase(LAS unsigned char* lds, const bf16_t* P, float* AB, bf16_t* TP, const float* a_log, const float* dt_bias, int G) {
;     ...
;         if (w == 0) dn_solve<0>(Mf, tc, lane); else if (w == 1) dn_solve<1>(Mf, tc, lane); else if (w == 2) dn_solve<2>(Mf, tc, lane); else dn_solve<3>(Mf, tc, lane);
	v_mov_b32_e32 v58, v47
	v_fma_f32 v5, v46, v42, 0
	s_waitcnt lgkmcnt(0)
	v_pk_mul_f32 v[46:47], v[44:45], v[58:59]
	s_nop 0
	v_add_f32_e32 v5, v5, v46
	v_add_f32_e32 v5, v5, v47
	ds_read2_b32 v[46:47], v13 offset0:240 offset1:244
	ds_read_b32 v59, v56 offset:32736
	s_nop 1
	v_add_f32_dpp v5, v5, v5 quad_perm:[1,0,3,2] row_mask:0xf bank_mask:0xf
	s_nop 1
	v_add_f32_dpp v5, v5, v5 quad_perm:[2,3,0,1] row_mask:0xf bank_mask:0xf
	v_sub_f32_e32 v5, v9, v5
	v_cndmask_b32_e64 v45, v45, v5, s[0:1]
	v_cndmask_b32_e64 v9, 0, 1.0, s[46:47]
	v_cmp_eq_u32_e64 s[46:47], 12, v53
	s_waitcnt lgkmcnt(1)
	v_mov_b32_e32 v58, v47
	v_fma_f32 v5, v46, v42, 0
	s_waitcnt lgkmcnt(0)
	v_pk_mul_f32 v[46:47], v[44:45], v[58:59]
	ds_read2_b32 v[58:59], v11 offset0:48 offset1:52
	ds_read_b32 v61, v56 offset:32992
	s_nop 0
	v_add_f32_e32 v5, v5, v46
	v_add_f32_e32 v5, v5, v47
	s_nop 1
	v_add_f32_dpp v5, v5, v5 quad_perm:[1,0,3,2] row_mask:0xf bank_mask:0xf
	s_nop 1
	v_add_f32_dpp v5, v5, v5 quad_perm:[2,3,0,1] row_mask:0xf bank_mask:0xf
	v_sub_f32_e32 v5, v9, v5
	v_cndmask_b32_e32 v46, v45, v5, vcc
	v_mov_b32_e32 v45, v46
	v_cndmask_b32_e64 v9, 0, 1.0, s[46:47]
	v_cmp_eq_u32_e64 s[46:47], 13, v53
	s_waitcnt lgkmcnt(1)
	v_mov_b32_e32 v60, v59
	v_fma_f32 v5, v58, v42, 0
	s_waitcnt lgkmcnt(0)
	v_pk_mul_f32 v[58:59], v[44:45], v[60:61]
	s_nop 0
	v_add_f32_e32 v5, v5, v58
	v_add_f32_e32 v5, v5, v59
	ds_read2_b32 v[58:59], v11 offset0:112 offset1:116
	ds_read2_b32 v[60:61], v11 offset0:120 offset1:124
	s_nop 1
	v_add_f32_dpp v5, v5, v5 quad_perm:[1,0,3,2] row_mask:0xf bank_mask:0xf
	s_nop 1
	v_add_f32_dpp v5, v5, v5 quad_perm:[2,3,0,1] row_mask:0xf bank_mask:0xf
	v_sub_f32_e32 v5, v9, v5
	v_cndmask_b32_e64 v47, v3, v5, s[42:43]
	v_mov_b32_e32 v43, v44
	v_cndmask_b32_e64 v7, 0, 1.0, s[46:47]
	s_waitcnt lgkmcnt(1)
	v_pk_mul_f32 v[58:59], v[58:59], v[42:43]
	s_nop 0
	v_add_f32_e32 v3, 0, v58
	s_waitcnt lgkmcnt(0)
	v_pk_mul_f32 v[60:61], v[46:47], v[60:61]
	v_add_f32_e32 v3, v3, v59
	v_add_f32_e32 v3, v3, v60
	v_add_f32_e32 v3, v3, v61
	ds_read2_b32 v[58:59], v11 offset0:176 offset1:180
	ds_read2_b32 v[60:61], v11 offset0:184 offset1:188
	s_nop 1
	v_add_f32_dpp v3, v3, v3 quad_perm:[1,0,3,2] row_mask:0xf bank_mask:0xf
	s_nop 1
	v_add_f32_dpp v3, v3, v3 quad_perm:[2,3,0,1] row_mask:0xf bank_mask:0xf
	v_sub_f32_e32 v3, v7, v3
	v_cndmask_b32_e64 v47, v47, v3, s[44:45]
	v_mov_b32_e32 v43, v44
	v_cmp_eq_u32_e64 s[44:45], 14, v53
	s_waitcnt lgkmcnt(1)
	v_pk_mul_f32 v[58:59], v[58:59], v[42:43]
	s_nop 0
	v_add_f32_e32 v3, 0, v58
	s_waitcnt lgkmcnt(0)
	v_pk_mul_f32 v[60:61], v[46:47], v[60:61]
	v_add_f32_e32 v3, v3, v59
	v_add_f32_e32 v3, v3, v60
	v_add_f32_e32 v3, v3, v61
	v_cndmask_b32_e64 v7, 0, 1.0, s[44:45]
	s_waitcnt lgkmcnt(0)
	ds_read2_b32 v[58:59], v11 offset0:240 offset1:244
	ds_read2_b32 v[60:61], v11 offset0:248 offset1:252
	s_nop 1
	v_add_f32_dpp v3, v3, v3 quad_perm:[1,0,3,2] row_mask:0xf bank_mask:0xf
	s_nop 1
	v_add_f32_dpp v3, v3, v3 quad_perm:[2,3,0,1] row_mask:0xf bank_mask:0xf
	v_sub_f32_e32 v3, v7, v3
	v_cndmask_b32_e64 v47, v47, v3, s[0:1]
	v_mov_b32_e32 v43, v44
	v_cmp_eq_u32_e64 s[0:1], 15, v53
	s_waitcnt lgkmcnt(1)
	v_pk_mul_f32 v[58:59], v[58:59], v[42:43]
	s_nop 0
	v_add_f32_e32 v3, 0, v58
	s_waitcnt lgkmcnt(0)
	v_pk_mul_f32 v[60:61], v[46:47], v[60:61]
	v_add_f32_e32 v3, v3, v59
	v_add_f32_e32 v3, v3, v60
	v_add_f32_e32 v3, v3, v61
	v_cndmask_b32_e64 v7, 0, 1.0, s[0:1]
	s_mov_b64 s[0:1], 0
	s_waitcnt lgkmcnt(0)
	s_nop 1
	v_add_f32_dpp v3, v3, v3 quad_perm:[1,0,3,2] row_mask:0xf bank_mask:0xf
	s_nop 1
	v_add_f32_dpp v3, v3, v3 quad_perm:[2,3,0,1] row_mask:0xf bank_mask:0xf
	v_sub_f32_e32 v3, v7, v3
	v_cndmask_b32_e32 v3, v47, v3, vcc
.LBB0_111:
	s_andn2_b64 vcc, exec, s[0:1]
	s_cbranch_vccnz .LBB0_113
	ds_read_b32 v34, v56 offset:25984
	v_mov_b32_e32 v2, v1
	v_mov_b32_e32 v4, v1
	v_mov_b32_e32 v6, v1
	v_mov_b32_e32 v8, v1
	v_mov_b32_e32 v10, v1
	v_mov_b32_e32 v12, v1
	v_mov_b32_e32 v14, v1
	v_mov_b32_e32 v16, v1
	v_mov_b32_e32 v13, v1
	v_mov_b32_e32 v15, v1
	v_mov_b32_e32 v11, v1
	v_mov_b32_e32 v9, v1
	v_mov_b32_e32 v7, v1
	v_mov_b32_e32 v5, v1
	v_mov_b32_e32 v3, v1
	v_mov_b32_e32 v17, v57
	v_cmp_eq_u32_e32 vcc, 1, v53
	v_cmp_eq_u32_e64 s[46:47], 1, v52
	v_cmp_eq_u32_e64 s[44:45], 2, v52
	v_cndmask_b32_e64 v36, 0, 1.0, vcc
	s_waitcnt lgkmcnt(0)
	v_fma_f32 v34, v34, v17, 0
	v_cmp_eq_u32_e32 vcc, 2, v53
	v_cmp_eq_u32_e64 s[0:1], 4, v53
	v_add_u32_e32 v38, 0x6800, v56
	v_add_u32_e32 v42, 0x6c00, v56
	s_waitcnt lgkmcnt(0)
	s_nop 1
	v_add_f32_dpp v34, v34, v34 quad_perm:[1,0,3,2] row_mask:0xf bank_mask:0xf
	v_add_u32_e32 v44, 0x7000, v56
	s_waitcnt lgkmcnt(0)
	s_nop 1
	v_add_f32_dpp v34, v34, v34 quad_perm:[2,3,0,1] row_mask:0xf bank_mask:0xf
	v_sub_f32_e32 v34, v36, v34
	v_cndmask_b32_e64 v17, v17, v34, s[46:47]
	ds_read_b32 v34, v56 offset:26240
	v_cndmask_b32_e64 v36, 0, 1.0, vcc
	v_cmp_eq_u32_e32 vcc, 3, v53
	s_waitcnt lgkmcnt(0)
	v_fma_f32 v34, v34, v17, 0
	s_nop 1
	v_add_f32_dpp v34, v34, v34 quad_perm:[1,0,3,2] row_mask:0xf bank_mask:0xf
	s_nop 1
	v_add_f32_dpp v34, v34, v34 quad_perm:[2,3,0,1] row_mask:0xf bank_mask:0xf
	v_sub_f32_e32 v34, v36, v34
	v_cndmask_b32_e64 v17, v17, v34, s[44:45]
	ds_read_b32 v34, v56 offset:26496
	v_cndmask_b32_e64 v36, 0, 1.0, vcc
	v_cmp_eq_u32_e32 vcc, 3, v52
	s_waitcnt lgkmcnt(0)
	v_fma_f32 v34, v34, v17, 0
	s_nop 1
	v_add_f32_dpp v34, v34, v34 quad_perm:[1,0,3,2] row_mask:0xf bank_mask:0xf
	s_nop 1
	v_add_f32_dpp v34, v34, v34 quad_perm:[2,3,0,1] row_mask:0xf bank_mask:0xf
	v_sub_f32_e32 v34, v36, v34
	v_cndmask_b32_e32 v34, v17, v34, vcc
	ds_read_b32 v17, v56 offset:26752
	v_cndmask_b32_e64 v36, 0, 1.0, s[0:1]
	v_cmp_eq_u32_e64 s[0:1], 5, v53
	s_waitcnt lgkmcnt(0)
; template <int W> __device__ __forceinline__ void dn_solve(const LAS float* Mf, float (&t)[16], int lane) {
;     const int j = 16 * W + (lane >> 2), q = lane & 3;
; #pragma unroll
;     for (int s = 0; s < 16; ++s) t[s] = 0.f;
; #pragma unroll
;     for (int i = 16 * W; i < 64; ++i) {
;         float acc = 0.f;
; #pragma unroll
;         for (int s = 4 * W; s <= (i - 1) / 4 && i > 16 * W; ++s) acc += Mf[i * 64 + 4 * s + q] * t[s];
;         acc += __shfl_xor(acc, 1); acc += __shfl_xor(acc, 2);
;         const float val = (i == j ? 1.f : 0.f) - acc;
;         if (q == (i & 3)) t[i >> 2] = val;
;         asm volatile("" : "+v"(t[0]), "+v"(t[1]), "+v"(t[2]), "+v"(t[3]), "+v"(t[4]), "+v"(t[5]), "+v"(t[6]), "+v"(t[7]), "+v"(t[8]), "+v"(t[9]), "+v"(t[10]), "+v"(t[11]), "+v"(t[12]), "+v"(t[13]), "+v"(t[14]), "+v"(t[15]));
	v_fma_f32 v17, v17, v34, 0
	s_nop 1
	v_add_f32_dpp v17, v17, v17 quad_perm:[1,0,3,2] row_mask:0xf bank_mask:0xf
	s_nop 1
	v_add_f32_dpp v17, v17, v17 quad_perm:[2,3,0,1] row_mask:0xf bank_mask:0xf
	v_sub_f32_e32 v17, v36, v17
	v_cndmask_b32_e64 v35, v13, v17, s[42:43]
	ds_read2_b32 v[36:37], v38 offset0:96 offset1:100
	s_waitcnt lgkmcnt(0)
	v_pk_mul_f32 v[36:37], v[36:37], v[34:35]
	s_nop 0
	v_add_f32_e32 v13, 0, v36
	v_add_f32_e32 v13, v13, v37
	v_cndmask_b32_e64 v36, 0, 1.0, s[0:1]
	v_cmp_eq_u32_e64 s[0:1], 6, v53
	s_waitcnt lgkmcnt(0)
	s_nop 1
	v_add_f32_dpp v13, v13, v13 quad_perm:[1,0,3,2] row_mask:0xf bank_mask:0xf
	s_nop 1
	v_add_f32_dpp v13, v13, v13 quad_perm:[2,3,0,1] row_mask:0xf bank_mask:0xf
	v_sub_f32_e32 v13, v36, v13
	v_cndmask_b32_e64 v35, v35, v13, s[46:47]
	ds_read2_b32 v[36:37], v38 offset0:160 offset1:164
	s_waitcnt lgkmcnt(0)
	v_pk_mul_f32 v[36:37], v[36:37], v[34:35]
	s_nop 0
	v_add_f32_e32 v13, 0, v36
	v_add_f32_e32 v13, v13, v37
	v_cndmask_b32_e64 v36, 0, 1.0, s[0:1]
	v_cmp_eq_u32_e64 s[0:1], 7, v53
	s_waitcnt lgkmcnt(0)
	s_nop 1
	v_add_f32_dpp v13, v13, v13 quad_perm:[1,0,3,2] row_mask:0xf bank_mask:0xf
	s_nop 1
	v_add_f32_dpp v13, v13, v13 quad_perm:[2,3,0,1] row_mask:0xf bank_mask:0xf
	v_sub_f32_e32 v13, v36, v13
	v_cndmask_b32_e64 v35, v35, v13, s[44:45]
	ds_read2_b32 v[36:37], v38 offset0:224 offset1:228
	s_waitcnt lgkmcnt(0)
	v_pk_mul_f32 v[36:37], v[36:37], v[34:35]
	s_nop 0
	v_add_f32_e32 v13, 0, v36
	v_add_f32_e32 v13, v13, v37
	v_cndmask_b32_e64 v36, 0, 1.0, s[0:1]
	v_cmp_eq_u32_e64 s[0:1], 8, v53
	s_waitcnt lgkmcnt(0)
	ds_read2_b32 v[38:39], v42 offset0:32 offset1:36
	s_nop 1
	v_add_f32_dpp v13, v13, v13 quad_perm:[1,0,3,2] row_mask:0xf bank_mask:0xf
	s_nop 1
	v_add_f32_dpp v13, v13, v13 quad_perm:[2,3,0,1] row_mask:0xf bank_mask:0xf
	v_sub_f32_e32 v13, v36, v13
	v_cndmask_b32_e32 v36, v35, v13, vcc
	v_mov_b32_e32 v35, v36
	s_waitcnt lgkmcnt(0)
	v_pk_mul_f32 v[38:39], v[38:39], v[34:35]
	s_nop 0
	v_add_f32_e32 v13, 0, v38
	v_add_f32_e32 v13, v13, v39
	v_cndmask_b32_e64 v35, 0, 1.0, s[0:1]
	v_cmp_eq_u32_e64 s[0:1], 9, v53
	s_waitcnt lgkmcnt(0)
	ds_read2_b32 v[38:39], v42 offset0:96 offset1:100
	ds_read_b32 v41, v56 offset:28064
	s_nop 1
	v_add_f32_dpp v13, v13, v13 quad_perm:[1,0,3,2] row_mask:0xf bank_mask:0xf
	s_nop 1
	v_add_f32_dpp v13, v13, v13 quad_perm:[2,3,0,1] row_mask:0xf bank_mask:0xf
	v_sub_f32_e32 v13, v35, v13
	v_cndmask_b32_e64 v37, v15, v13, s[42:43]
	v_cndmask_b32_e64 v17, 0, 1.0, s[0:1]
	v_cmp_eq_u32_e64 s[0:1], 10, v53
	s_waitcnt lgkmcnt(1)
	v_mov_b32_e32 v40, v39
	v_fma_f32 v13, v38, v34, 0
	s_waitcnt lgkmcnt(0)
	v_pk_mul_f32 v[38:39], v[36:37], v[40:41]
	s_nop 0
	v_add_f32_e32 v13, v13, v38
	v_add_f32_e32 v13, v13, v39
	ds_read2_b32 v[38:39], v42 offset0:160 offset1:164
	ds_read_b32 v41, v56 offset:28320
	s_nop 1
	v_add_f32_dpp v13, v13, v13 quad_perm:[1,0,3,2] row_mask:0xf bank_mask:0xf
	s_nop 1
	v_add_f32_dpp v13, v13, v13 quad_perm:[2,3,0,1] row_mask:0xf bank_mask:0xf
	v_sub_f32_e32 v13, v17, v13
	v_cndmask_b32_e64 v37, v37, v13, s[46:47]
	v_cndmask_b32_e64 v17, 0, 1.0, s[0:1]
	v_cmp_eq_u32_e64 s[0:1], 11, v53
	s_waitcnt lgkmcnt(1)
	v_mov_b32_e32 v40, v39
	v_fma_f32 v13, v38, v34, 0
	s_waitcnt lgkmcnt(0)
	v_pk_mul_f32 v[38:39], v[36:37], v[40:41]
	s_nop 0
	v_add_f32_e32 v13, v13, v38
	v_add_f32_e32 v13, v13, v39
	ds_read2_b32 v[38:39], v42 offset0:224 offset1:228
	ds_read_b32 v41, v56 offset:28576
	s_nop 1
	v_add_f32_dpp v13, v13, v13 quad_perm:[1,0,3,2] row_mask:0xf bank_mask:0xf
	s_nop 1
	v_add_f32_dpp v13, v13, v13 quad_perm:[2,3,0,1] row_mask:0xf bank_mask:0xf
	v_sub_f32_e32 v13, v17, v13
	v_cndmask_b32_e64 v37, v37, v13, s[44:45]
	v_cndmask_b32_e64 v17, 0, 1.0, s[0:1]
	v_cmp_eq_u32_e64 s[0:1], 12, v53
	s_waitcnt lgkmcnt(1)
	v_mov_b32_e32 v40, v39
	v_fma_f32 v13, v38, v34, 0
	s_waitcnt lgkmcnt(0)
	v_pk_mul_f32 v[38:39], v[36:37], v[40:41]
	ds_read2_b32 v[40:41], v44 offset0:32 offset1:36
	ds_read_b32 v43, v56 offset:28832
	s_nop 0
	v_add_f32_e32 v13, v13, v38
	v_add_f32_e32 v13, v13, v39
	s_nop 1
	v_add_f32_dpp v13, v13, v13 quad_perm:[1,0,3,2] row_mask:0xf bank_mask:0xf
	s_nop 1
	v_add_f32_dpp v13, v13, v13 quad_perm:[2,3,0,1] row_mask:0xf bank_mask:0xf
	v_sub_f32_e32 v13, v17, v13
	v_cndmask_b32_e32 v38, v37, v13, vcc
	v_mov_b32_e32 v37, v38
	v_cndmask_b32_e64 v17, 0, 1.0, s[0:1]
	v_cmp_eq_u32_e64 s[0:1], 13, v53
	s_waitcnt lgkmcnt(1)
	v_mov_b32_e32 v42, v41
	v_fma_f32 v13, v40, v34, 0
	s_waitcnt lgkmcnt(0)
	v_pk_mul_f32 v[40:41], v[36:37], v[42:43]
	s_nop 0
	v_add_f32_e32 v13, v13, v40
	v_add_f32_e32 v13, v13, v41
	ds_read2_b32 v[40:41], v44 offset0:96 offset1:100
	ds_read2_b32 v[42:43], v44 offset0:104 offset1:108
	s_nop 1
	v_add_f32_dpp v13, v13, v13 quad_perm:[1,0,3,2] row_mask:0xf bank_mask:0xf
	s_nop 1
	v_add_f32_dpp v13, v13, v13 quad_perm:[2,3,0,1] row_mask:0xf bank_mask:0xf
	v_sub_f32_e32 v13, v17, v13
	v_cndmask_b32_e64 v39, v11, v13, s[42:43]
	v_mov_b32_e32 v35, v36
	v_cndmask_b32_e64 v15, 0, 1.0, s[0:1]
	v_cmp_eq_u32_e64 s[0:1], 14, v53
	s_waitcnt lgkmcnt(1)
	v_pk_mul_f32 v[40:41], v[40:41], v[34:35]
	s_waitcnt lgkmcnt(0)
	v_pk_mul_f32 v[42:43], v[38:39], v[42:43]
	v_add_f32_e32 v11, 0, v40
	v_add_f32_e32 v11, v11, v41
	v_add_f32_e32 v11, v11, v42
	v_add_f32_e32 v11, v11, v43
	v_add_u32_e32 v17, 0x7400, v56
	s_waitcnt lgkmcnt(0)
	ds_read2_b32 v[40:41], v44 offset0:160 offset1:164
	ds_read2_b32 v[42:43], v44 offset0:168 offset1:172
	s_nop 1
	v_add_f32_dpp v11, v11, v11 quad_perm:[1,0,3,2] row_mask:0xf bank_mask:0xf
	s_nop 1
	v_add_f32_dpp v11, v11, v11 quad_perm:[2,3,0,1] row_mask:0xf bank_mask:0xf
	v_sub_f32_e32 v11, v15, v11
	v_cndmask_b32_e64 v39, v39, v11, s[46:47]
	v_mov_b32_e32 v35, v36
	v_cndmask_b32_e64 v15, 0, 1.0, s[0:1]
	v_cmp_eq_u32_e64 s[0:1], 15, v53
	s_waitcnt lgkmcnt(1)
; template <int W> __device__ __forceinline__ void dn_solve(const LAS float* Mf, float (&t)[16], int lane) {
;     const int j = 16 * W + (lane >> 2), q = lane & 3;
; #pragma unroll
;     for (int s = 0; s < 16; ++s) t[s] = 0.f;
; #pragma unroll
;     for (int i = 16 * W; i < 64; ++i) {
;         float acc = 0.f;
; #pragma unroll
;         for (int s = 4 * W; s <= (i - 1) / 4 && i > 16 * W; ++s) acc += Mf[i * 64 + 4 * s + q] * t[s];
;         acc += __shfl_xor(acc, 1); acc += __shfl_xor(acc, 2);
;         const float val = (i == j ? 1.f : 0.f) - acc;
;         if (q == (i & 3)) t[i >> 2] = val;
;         asm volatile("" : "+v"(t[0]), "+v"(t[1]), "+v"(t[2]), "+v"(t[3]), "+v"(t[4]), "+v"(t[5]), "+v"(t[6]), "+v"(t[7]), "+v"(t[8]), "+v"(t[9]), "+v"(t[10]), "+v"(t[11]), "+v"(t[12]), "+v"(t[13]), "+v"(t[14]), "+v"(t[15]));
	v_pk_mul_f32 v[40:41], v[40:41], v[34:35]
	s_waitcnt lgkmcnt(0)
	v_pk_mul_f32 v[42:43], v[38:39], v[42:43]
	v_add_f32_e32 v11, 0, v40
	v_add_f32_e32 v11, v11, v41
	v_add_f32_e32 v11, v11, v42
	v_add_f32_e32 v11, v11, v43
	ds_read2_b32 v[40:41], v44 offset0:224 offset1:228
	ds_read2_b32 v[42:43], v44 offset0:232 offset1:236
	s_nop 1
	v_add_f32_dpp v11, v11, v11 quad_perm:[1,0,3,2] row_mask:0xf bank_mask:0xf
	s_nop 1
	v_add_f32_dpp v11, v11, v11 quad_perm:[2,3,0,1] row_mask:0xf bank_mask:0xf
	v_sub_f32_e32 v11, v15, v11
	v_cndmask_b32_e64 v39, v39, v11, s[44:45]
	v_mov_b32_e32 v35, v36
	v_cndmask_b32_e64 v15, 0, 1.0, s[0:1]
	s_waitcnt lgkmcnt(1)
	v_pk_mul_f32 v[40:41], v[40:41], v[34:35]
	s_nop 0
	v_add_f32_e32 v11, 0, v40
	s_waitcnt lgkmcnt(0)
	v_pk_mul_f32 v[42:43], v[38:39], v[42:43]
	v_add_f32_e32 v11, v11, v41
	v_add_f32_e32 v11, v11, v42
	v_add_f32_e32 v11, v11, v43
	ds_read2_b32 v[42:43], v17 offset0:32 offset1:36
	ds_read2_b32 v[44:45], v17 offset0:40 offset1:44
	s_nop 1
	v_add_f32_dpp v11, v11, v11 quad_perm:[1,0,3,2] row_mask:0xf bank_mask:0xf
	s_nop 1
	v_add_f32_dpp v11, v11, v11 quad_perm:[2,3,0,1] row_mask:0xf bank_mask:0xf
	v_sub_f32_e32 v11, v15, v11
	v_cndmask_b32_e32 v40, v39, v11, vcc
	v_mov_b32_e32 v35, v36
	v_mov_b32_e32 v39, v40
	s_waitcnt lgkmcnt(1)
	v_pk_mul_f32 v[42:43], v[42:43], v[34:35]
	s_nop 0
	v_add_f32_e32 v11, 0, v42
	s_waitcnt lgkmcnt(0)
	v_pk_mul_f32 v[44:45], v[38:39], v[44:45]
	v_add_f32_e32 v11, v11, v43
	v_add_f32_e32 v11, v11, v44
	v_add_f32_e32 v11, v11, v45
	ds_read2_b32 v[42:43], v17 offset0:96 offset1:100
	ds_read2_b32 v[44:45], v17 offset0:104 offset1:108
	ds_read_b32 v47, v56 offset:30144
	s_nop 1
	v_add_f32_dpp v11, v11, v11 quad_perm:[1,0,3,2] row_mask:0xf bank_mask:0xf
	s_nop 1
	v_add_f32_dpp v11, v11, v11 quad_perm:[2,3,0,1] row_mask:0xf bank_mask:0xf
	v_sub_f32_e32 v11, 0, v11
	v_cndmask_b32_e64 v41, v9, v11, s[42:43]
	v_mov_b32_e32 v37, v38
	v_add_u32_e32 v13, 0x7800, v56
	s_waitcnt lgkmcnt(2)
	v_fma_f32 v9, v42, v34, 0
	v_mov_b32_e32 v42, v43
	s_waitcnt lgkmcnt(1)
	v_mov_b32_e32 v43, v44
	v_pk_mul_f32 v[42:43], v[36:37], v[42:43]
	v_mov_b32_e32 v46, v45
	v_add_f32_e32 v9, v9, v42
	s_waitcnt lgkmcnt(0)
	v_pk_mul_f32 v[44:45], v[40:41], v[46:47]
	v_add_f32_e32 v9, v9, v43
	v_add_f32_e32 v9, v9, v44
	v_add_f32_e32 v9, v9, v45
	ds_read2_b32 v[42:43], v17 offset0:160 offset1:164
	ds_read2_b32 v[44:45], v17 offset0:168 offset1:172
	ds_read_b32 v47, v56 offset:30400
	s_nop 1
	v_add_f32_dpp v9, v9, v9 quad_perm:[1,0,3,2] row_mask:0xf bank_mask:0xf
	s_nop 1
	v_add_f32_dpp v9, v9, v9 quad_perm:[2,3,0,1] row_mask:0xf bank_mask:0xf
	v_sub_f32_e32 v9, 0, v9
	v_cndmask_b32_e64 v41, v41, v9, s[46:47]
	v_mov_b32_e32 v37, v38
	s_waitcnt lgkmcnt(2)
	v_fma_f32 v9, v42, v34, 0
	v_mov_b32_e32 v42, v43
	s_waitcnt lgkmcnt(1)
	v_mov_b32_e32 v43, v44
	v_pk_mul_f32 v[42:43], v[36:37], v[42:43]
	v_mov_b32_e32 v46, v45
	v_add_f32_e32 v9, v9, v42
	s_waitcnt lgkmcnt(0)
	v_pk_mul_f32 v[44:45], v[40:41], v[46:47]
	v_add_f32_e32 v9, v9, v43
	v_add_f32_e32 v9, v9, v44
	v_add_f32_e32 v9, v9, v45
	ds_read2_b32 v[42:43], v17 offset0:224 offset1:228
	ds_read2_b32 v[44:45], v17 offset0:232 offset1:236
	ds_read_b32 v47, v56 offset:30656
	s_nop 1
	v_add_f32_dpp v9, v9, v9 quad_perm:[1,0,3,2] row_mask:0xf bank_mask:0xf
	s_nop 1
	v_add_f32_dpp v9, v9, v9 quad_perm:[2,3,0,1] row_mask:0xf bank_mask:0xf
	v_sub_f32_e32 v9, 0, v9
	v_cndmask_b32_e64 v41, v41, v9, s[44:45]
	v_mov_b32_e32 v37, v38
	s_waitcnt lgkmcnt(2)
	v_fma_f32 v9, v42, v34, 0
	v_mov_b32_e32 v42, v43
	s_waitcnt lgkmcnt(1)
	v_mov_b32_e32 v43, v44
	v_pk_mul_f32 v[42:43], v[36:37], v[42:43]
	v_mov_b32_e32 v46, v45
	v_add_f32_e32 v9, v9, v42
	s_waitcnt lgkmcnt(0)
	v_pk_mul_f32 v[44:45], v[40:41], v[46:47]
	v_add_f32_e32 v9, v9, v43
	v_add_f32_e32 v9, v9, v44
	v_add_f32_e32 v9, v9, v45
	ds_read2_b32 v[44:45], v13 offset0:32 offset1:36
	ds_read2_b32 v[46:47], v13 offset0:40 offset1:44
	ds_read_b32 v59, v56 offset:30912
	s_nop 1
	v_add_f32_dpp v9, v9, v9 quad_perm:[1,0,3,2] row_mask:0xf bank_mask:0xf
	s_nop 1
	v_add_f32_dpp v9, v9, v9 quad_perm:[2,3,0,1] row_mask:0xf bank_mask:0xf
	v_sub_f32_e32 v9, 0, v9
	v_cndmask_b32_e32 v42, v41, v9, vcc
	v_mov_b32_e32 v37, v38
	v_mov_b32_e32 v41, v42
	s_waitcnt lgkmcnt(2)
	v_fma_f32 v9, v44, v34, 0
	v_mov_b32_e32 v44, v45
	s_waitcnt lgkmcnt(1)
	v_mov_b32_e32 v45, v46
	v_pk_mul_f32 v[44:45], v[36:37], v[44:45]
	v_mov_b32_e32 v58, v47
	v_add_f32_e32 v9, v9, v44
	s_waitcnt lgkmcnt(0)
	v_pk_mul_f32 v[46:47], v[40:41], v[58:59]
	v_add_f32_e32 v9, v9, v45
	v_add_f32_e32 v9, v9, v46
	v_add_f32_e32 v9, v9, v47
	ds_read2_b32 v[44:45], v13 offset0:96 offset1:100
	ds_read2_b32 v[46:47], v13 offset0:104 offset1:108
	ds_read2_b32 v[58:59], v13 offset0:112 offset1:116
	s_nop 1
	v_add_f32_dpp v9, v9, v9 quad_perm:[1,0,3,2] row_mask:0xf bank_mask:0xf
	s_nop 1
	v_add_f32_dpp v9, v9, v9 quad_perm:[2,3,0,1] row_mask:0xf bank_mask:0xf
	v_sub_f32_e32 v9, 0, v9
	v_cndmask_b32_e64 v43, v7, v9, s[42:43]
	v_mov_b32_e32 v39, v40
	v_add_u32_e32 v11, 0x7c00, v56
	s_waitcnt lgkmcnt(2)
	v_fma_f32 v7, v44, v34, 0
	s_waitcnt lgkmcnt(1)
	v_pk_mul_f32 v[46:47], v[38:39], v[46:47]
	v_fmac_f32_e32 v7, v36, v45
	v_add_f32_e32 v7, v7, v46
	s_waitcnt lgkmcnt(0)
	v_pk_mul_f32 v[58:59], v[42:43], v[58:59]
	v_add_f32_e32 v7, v7, v47
	v_add_f32_e32 v7, v7, v58
	v_add_f32_e32 v7, v7, v59
	ds_read2_b32 v[44:45], v13 offset0:160 offset1:164
	ds_read2_b32 v[46:47], v13 offset0:168 offset1:172
	ds_read2_b32 v[58:59], v13 offset0:176 offset1:180
	s_nop 1
	v_add_f32_dpp v7, v7, v7 quad_perm:[1,0,3,2] row_mask:0xf bank_mask:0xf
	s_nop 1
	v_add_f32_dpp v7, v7, v7 quad_perm:[2,3,0,1] row_mask:0xf bank_mask:0xf
	v_sub_f32_e32 v7, 0, v7
	v_cndmask_b32_e64 v43, v43, v7, s[46:47]
	v_mov_b32_e32 v39, v40
	s_waitcnt lgkmcnt(2)
; template <int W> __device__ __forceinline__ void dn_solve(const LAS float* Mf, float (&t)[16], int lane) {
;     const int j = 16 * W + (lane >> 2), q = lane & 3;
; #pragma unroll
;     for (int s = 0; s < 16; ++s) t[s] = 0.f;
; #pragma unroll
;     for (int i = 16 * W; i < 64; ++i) {
;         float acc = 0.f;
; #pragma unroll
;         for (int s = 4 * W; s <= (i - 1) / 4 && i > 16 * W; ++s) acc += Mf[i * 64 + 4 * s + q] * t[s];
;         acc += __shfl_xor(acc, 1); acc += __shfl_xor(acc, 2);
;         const float val = (i == j ? 1.f : 0.f) - acc;
;         if (q == (i & 3)) t[i >> 2] = val;
;         asm volatile("" : "+v"(t[0]), "+v"(t[1]), "+v"(t[2]), "+v"(t[3]), "+v"(t[4]), "+v"(t[5]), "+v"(t[6]), "+v"(t[7]), "+v"(t[8]), "+v"(t[9]), "+v"(t[10]), "+v"(t[11]), "+v"(t[12]), "+v"(t[13]), "+v"(t[14]), "+v"(t[15]));
	v_fma_f32 v7, v44, v34, 0
	s_waitcnt lgkmcnt(1)
	v_pk_mul_f32 v[46:47], v[38:39], v[46:47]
	v_fmac_f32_e32 v7, v36, v45
	v_add_f32_e32 v7, v7, v46
	s_waitcnt lgkmcnt(0)
	v_pk_mul_f32 v[58:59], v[42:43], v[58:59]
	v_add_f32_e32 v7, v7, v47
	v_add_f32_e32 v7, v7, v58
	v_add_f32_e32 v7, v7, v59
	ds_read2_b32 v[44:45], v13 offset0:224 offset1:228
	ds_read2_b32 v[46:47], v13 offset0:232 offset1:236
	ds_read2_b32 v[58:59], v13 offset0:240 offset1:244
	s_nop 1
	v_add_f32_dpp v7, v7, v7 quad_perm:[1,0,3,2] row_mask:0xf bank_mask:0xf
	s_nop 1
	v_add_f32_dpp v7, v7, v7 quad_perm:[2,3,0,1] row_mask:0xf bank_mask:0xf
	v_sub_f32_e32 v7, 0, v7
	v_cndmask_b32_e64 v43, v43, v7, s[44:45]
	v_mov_b32_e32 v39, v40
	s_waitcnt lgkmcnt(2)
	v_fma_f32 v7, v44, v34, 0
	s_waitcnt lgkmcnt(1)
	v_pk_mul_f32 v[46:47], v[38:39], v[46:47]
	v_fmac_f32_e32 v7, v36, v45
	v_add_f32_e32 v7, v7, v46
	s_waitcnt lgkmcnt(0)
	v_pk_mul_f32 v[58:59], v[42:43], v[58:59]
	v_add_f32_e32 v7, v7, v47
	v_add_f32_e32 v7, v7, v58
	v_add_f32_e32 v7, v7, v59
	ds_read2_b32 v[46:47], v11 offset0:32 offset1:36
	ds_read2_b32 v[58:59], v11 offset0:40 offset1:44
	ds_read2_b32 v[60:61], v11 offset0:48 offset1:52
	s_nop 1
	v_add_f32_dpp v7, v7, v7 quad_perm:[1,0,3,2] row_mask:0xf bank_mask:0xf
	s_nop 1
	v_add_f32_dpp v7, v7, v7 quad_perm:[2,3,0,1] row_mask:0xf bank_mask:0xf
	v_sub_f32_e32 v7, 0, v7
	v_cndmask_b32_e32 v44, v43, v7, vcc
	v_mov_b32_e32 v39, v40
	v_mov_b32_e32 v43, v44
	s_waitcnt lgkmcnt(2)
	v_fma_f32 v7, v46, v34, 0
	s_waitcnt lgkmcnt(1)
	v_pk_mul_f32 v[58:59], v[38:39], v[58:59]
	v_fmac_f32_e32 v7, v36, v47
	v_add_f32_e32 v7, v7, v58
	s_waitcnt lgkmcnt(0)
	v_pk_mul_f32 v[60:61], v[42:43], v[60:61]
	v_add_f32_e32 v7, v7, v59
	v_add_f32_e32 v7, v7, v60
	v_add_f32_e32 v7, v7, v61
	ds_read2_b32 v[46:47], v11 offset0:96 offset1:100
	ds_read2_b32 v[58:59], v11 offset0:104 offset1:108
	ds_read2_b32 v[60:61], v11 offset0:112 offset1:116
	ds_read_b32 v63, v56 offset:32224
	s_nop 1
	v_add_f32_dpp v7, v7, v7 quad_perm:[1,0,3,2] row_mask:0xf bank_mask:0xf
	s_nop 1
	v_add_f32_dpp v7, v7, v7 quad_perm:[2,3,0,1] row_mask:0xf bank_mask:0xf
	v_sub_f32_e32 v7, 0, v7
	v_cndmask_b32_e64 v45, v5, v7, s[42:43]
	v_mov_b32_e32 v41, v42
	s_waitcnt lgkmcnt(3)
	v_fma_f32 v5, v46, v34, 0
	s_waitcnt lgkmcnt(2)
	v_mov_b32_e32 v64, v59
	s_waitcnt lgkmcnt(1)
	v_mov_b32_e32 v65, v60
	v_fmac_f32_e32 v5, v36, v47
	v_pk_mul_f32 v[46:47], v[40:41], v[64:65]
	v_fmac_f32_e32 v5, v38, v58
	v_mov_b32_e32 v62, v61
	v_add_f32_e32 v5, v5, v46
	s_waitcnt lgkmcnt(0)
	v_pk_mul_f32 v[60:61], v[44:45], v[62:63]
	v_add_f32_e32 v5, v5, v47
	v_add_f32_e32 v5, v5, v60
	v_add_f32_e32 v5, v5, v61
	v_add_u32_e32 v9, 0x8000, v56
	s_waitcnt lgkmcnt(0)
	ds_read2_b32 v[46:47], v11 offset0:160 offset1:164
	ds_read2_b32 v[58:59], v11 offset0:168 offset1:172
	ds_read2_b32 v[60:61], v11 offset0:176 offset1:180
	ds_read_b32 v63, v56 offset:32480
	s_nop 1
	v_add_f32_dpp v5, v5, v5 quad_perm:[1,0,3,2] row_mask:0xf bank_mask:0xf
	s_nop 1
	v_add_f32_dpp v5, v5, v5 quad_perm:[2,3,0,1] row_mask:0xf bank_mask:0xf
	v_sub_f32_e32 v5, 0, v5
	v_cndmask_b32_e64 v45, v45, v5, s[46:47]
	v_mov_b32_e32 v41, v42
	s_waitcnt lgkmcnt(3)
	v_fma_f32 v5, v46, v34, 0
	s_waitcnt lgkmcnt(2)
	v_mov_b32_e32 v64, v59
	s_waitcnt lgkmcnt(1)
	v_mov_b32_e32 v65, v60
	v_fmac_f32_e32 v5, v36, v47
	v_pk_mul_f32 v[46:47], v[40:41], v[64:65]
	v_fmac_f32_e32 v5, v38, v58
	v_mov_b32_e32 v62, v61
	v_add_f32_e32 v5, v5, v46
	s_waitcnt lgkmcnt(0)
	v_pk_mul_f32 v[60:61], v[44:45], v[62:63]
	v_add_f32_e32 v5, v5, v47
	v_add_f32_e32 v5, v5, v60
	v_add_f32_e32 v5, v5, v61
	ds_read2_b32 v[46:47], v11 offset0:224 offset1:228
	ds_read2_b32 v[58:59], v11 offset0:232 offset1:236
	ds_read2_b32 v[60:61], v11 offset0:240 offset1:244
	ds_read_b32 v63, v56 offset:32736
	s_nop 1
	v_add_f32_dpp v5, v5, v5 quad_perm:[1,0,3,2] row_mask:0xf bank_mask:0xf
	s_nop 1
	v_add_f32_dpp v5, v5, v5 quad_perm:[2,3,0,1] row_mask:0xf bank_mask:0xf
	v_sub_f32_e32 v5, 0, v5
	v_cndmask_b32_e64 v45, v45, v5, s[44:45]
	v_mov_b32_e32 v41, v42
	s_waitcnt lgkmcnt(3)
	v_fma_f32 v5, v46, v34, 0
	s_waitcnt lgkmcnt(2)
; template <int W> __device__ __forceinline__ void dn_solve(const LAS float* Mf, float (&t)[16], int lane) {
;     const int j = 16 * W + (lane >> 2), q = lane & 3;
; #pragma unroll
;     for (int s = 0; s < 16; ++s) t[s] = 0.f;
; #pragma unroll
;     for (int i = 16 * W; i < 64; ++i) {
;         float acc = 0.f;
; #pragma unroll
;         for (int s = 4 * W; s <= (i - 1) / 4 && i > 16 * W; ++s) acc += Mf[i * 64 + 4 * s + q] * t[s];
;         acc += __shfl_xor(acc, 1); acc += __shfl_xor(acc, 2);
;         const float val = (i == j ? 1.f : 0.f) - acc;
;         if (q == (i & 3)) t[i >> 2] = val;
;         asm volatile("" : "+v"(t[0]), "+v"(t[1]), "+v"(t[2]), "+v"(t[3]), "+v"(t[4]), "+v"(t[5]), "+v"(t[6]), "+v"(t[7]), "+v"(t[8]), "+v"(t[9]), "+v"(t[10]), "+v"(t[11]), "+v"(t[12]), "+v"(t[13]), "+v"(t[14]), "+v"(t[15]));
	v_mov_b32_e32 v64, v59
	s_waitcnt lgkmcnt(1)
	v_mov_b32_e32 v65, v60
	v_fmac_f32_e32 v5, v36, v47
	v_pk_mul_f32 v[46:47], v[40:41], v[64:65]
	v_fmac_f32_e32 v5, v38, v58
	v_mov_b32_e32 v62, v61
	v_add_f32_e32 v5, v5, v46
	s_waitcnt lgkmcnt(0)
	v_pk_mul_f32 v[60:61], v[44:45], v[62:63]
	v_add_f32_e32 v5, v5, v47
	v_add_f32_e32 v5, v5, v60
	v_add_f32_e32 v5, v5, v61
	ds_read2_b32 v[58:59], v9 offset0:32 offset1:36
	ds_read2_b32 v[60:61], v9 offset0:40 offset1:44
	ds_read2_b32 v[62:63], v9 offset0:48 offset1:52
	ds_read_b32 v65, v56 offset:32992
	s_nop 1
	v_add_f32_dpp v5, v5, v5 quad_perm:[1,0,3,2] row_mask:0xf bank_mask:0xf
	s_nop 1
	v_add_f32_dpp v5, v5, v5 quad_perm:[2,3,0,1] row_mask:0xf bank_mask:0xf
	v_sub_f32_e32 v5, 0, v5
	v_cndmask_b32_e32 v46, v45, v5, vcc
	v_mov_b32_e32 v41, v42
	s_waitcnt lgkmcnt(3)
	v_fma_f32 v5, v58, v34, 0
	s_waitcnt lgkmcnt(2)
	v_mov_b32_e32 v66, v61
	s_waitcnt lgkmcnt(1)
	v_mov_b32_e32 v67, v62
	v_fmac_f32_e32 v5, v36, v59
	v_pk_mul_f32 v[58:59], v[40:41], v[66:67]
	v_fmac_f32_e32 v5, v38, v60
	v_mov_b32_e32 v45, v46
	v_mov_b32_e32 v64, v63
	v_add_f32_e32 v5, v5, v58
	s_waitcnt lgkmcnt(0)
	v_pk_mul_f32 v[62:63], v[44:45], v[64:65]
	v_add_f32_e32 v5, v5, v59
	v_add_f32_e32 v5, v5, v62
	v_add_f32_e32 v5, v5, v63
	ds_read2_b32 v[58:59], v9 offset0:96 offset1:100
	ds_read2_b32 v[60:61], v9 offset0:112 offset1:116
	ds_read2_b32 v[62:63], v9 offset0:120 offset1:124
	ds_read2_b32 v[64:65], v9 offset0:104 offset1:108
	s_nop 1
	v_add_f32_dpp v5, v5, v5 quad_perm:[1,0,3,2] row_mask:0xf bank_mask:0xf
	s_nop 1
	v_add_f32_dpp v5, v5, v5 quad_perm:[2,3,0,1] row_mask:0xf bank_mask:0xf
	v_sub_f32_e32 v5, 0, v5
	v_cndmask_b32_e64 v47, v3, v5, s[42:43]
	v_mov_b32_e32 v43, v44
	s_waitcnt lgkmcnt(3)
	v_fma_f32 v3, v58, v34, 0
	v_fmac_f32_e32 v3, v36, v59
	s_waitcnt lgkmcnt(2)
	v_pk_mul_f32 v[60:61], v[42:43], v[60:61]
	s_waitcnt lgkmcnt(0)
	v_fmac_f32_e32 v3, v38, v64
	v_fmac_f32_e32 v3, v40, v65
	v_add_f32_e32 v3, v3, v60
	v_pk_mul_f32 v[62:63], v[46:47], v[62:63]
	v_add_f32_e32 v3, v3, v61
	v_add_f32_e32 v3, v3, v62
	v_add_f32_e32 v3, v3, v63
	ds_read2_b32 v[58:59], v9 offset0:160 offset1:164
	ds_read2_b32 v[60:61], v9 offset0:176 offset1:180
	ds_read2_b32 v[62:63], v9 offset0:184 offset1:188
	ds_read2_b32 v[64:65], v9 offset0:168 offset1:172
	s_nop 1
	v_add_f32_dpp v3, v3, v3 quad_perm:[1,0,3,2] row_mask:0xf bank_mask:0xf
	s_nop 1
	v_add_f32_dpp v3, v3, v3 quad_perm:[2,3,0,1] row_mask:0xf bank_mask:0xf
	v_sub_f32_e32 v3, 0, v3
	v_cndmask_b32_e64 v47, v47, v3, s[46:47]
	v_mov_b32_e32 v43, v44
	s_waitcnt lgkmcnt(3)
	v_fma_f32 v3, v58, v34, 0
	v_fmac_f32_e32 v3, v36, v59
	s_waitcnt lgkmcnt(2)
	v_pk_mul_f32 v[60:61], v[42:43], v[60:61]
	s_waitcnt lgkmcnt(0)
	v_fmac_f32_e32 v3, v38, v64
	v_fmac_f32_e32 v3, v40, v65
	v_add_f32_e32 v3, v3, v60
	v_pk_mul_f32 v[62:63], v[46:47], v[62:63]
	v_add_f32_e32 v3, v3, v61
	v_add_f32_e32 v3, v3, v62
	v_add_f32_e32 v3, v3, v63
	ds_read2_b32 v[58:59], v9 offset0:224 offset1:228
	ds_read2_b32 v[60:61], v9 offset0:232 offset1:236
	ds_read2_b32 v[62:63], v9 offset0:240 offset1:244
	ds_read2_b32 v[64:65], v9 offset0:248 offset1:252
	s_nop 1
	v_add_f32_dpp v3, v3, v3 quad_perm:[1,0,3,2] row_mask:0xf bank_mask:0xf
	s_nop 1
	v_add_f32_dpp v3, v3, v3 quad_perm:[2,3,0,1] row_mask:0xf bank_mask:0xf
	v_sub_f32_e32 v3, 0, v3
	v_cndmask_b32_e64 v47, v47, v3, s[44:45]
	v_mov_b32_e32 v35, v36
	s_waitcnt lgkmcnt(3)
	v_pk_mul_f32 v[58:59], v[58:59], v[34:35]
	v_mov_b32_e32 v39, v40
	v_add_f32_e32 v3, 0, v58
	s_waitcnt lgkmcnt(2)
	v_pk_mul_f32 v[60:61], v[38:39], v[60:61]
	v_add_f32_e32 v3, v3, v59
	v_mov_b32_e32 v43, v44
	v_add_f32_e32 v3, v3, v60
	s_waitcnt lgkmcnt(1)
	v_pk_mul_f32 v[62:63], v[42:43], v[62:63]
	v_add_f32_e32 v3, v3, v61
	v_add_f32_e32 v3, v3, v62
	v_add_f32_e32 v3, v3, v63
	s_waitcnt lgkmcnt(0)
	v_pk_mul_f32 v[58:59], v[46:47], v[64:65]
	s_nop 0
	v_add_f32_e32 v3, v3, v58
	v_add_f32_e32 v3, v3, v59
	s_nop 1
	v_add_f32_dpp v3, v3, v3 quad_perm:[1,0,3,2] row_mask:0xf bank_mask:0xf
	s_nop 1
	v_add_f32_dpp v3, v3, v3 quad_perm:[2,3,0,1] row_mask:0xf bank_mask:0xf
	v_sub_f32_e32 v3, 0, v3
	v_cndmask_b32_e32 v3, v47, v3, vcc

; template <int W> __device__ __forceinline__ void dn_solve(const LAS float* Mf, float (&t)[16], int lane) {
;     const int j = 16 * W + (lane >> 2), q = lane & 3;
; #pragma unroll
;     for (int s = 0; s < 16; ++s) t[s] = 0.f;
; #pragma unroll
;     for (int i = 16 * W; i < 64; ++i) {
;         float acc = 0.f;
; #pragma unroll
;         for (int s = 4 * W; s <= (i - 1) / 4 && i > 16 * W; ++s) acc += Mf[i * 64 + 4 * s + q] * t[s];
;         acc += __shfl_xor(acc, 1); acc += __shfl_xor(acc, 2);
;         const float val = (i == j ? 1.f : 0.f) - acc;
;         if (q == (i & 3)) t[i >> 2] = val;
;         asm volatile("" : "+v"(t[0]), "+v"(t[1]), "+v"(t[2]), "+v"(t[3]), "+v"(t[4]), "+v"(t[5]), "+v"(t[6]), "+v"(t[7]), "+v"(t[8]), "+v"(t[9]), "+v"(t[10]), "+v"(t[11]), "+v"(t[12]), "+v"(t[13]), "+v"(t[14]), "+v"(t[15]));
; __device__ __forceinline__ void dn_t_phase(LAS unsigned char* lds, const bf16_t* P, float* AB, bf16_t* TP, const float* a_log, const float* dt_bias, int G) {
;     ...
;         if (w == 0) dn_solve<0>(Mf, tc, lane); else if (w == 1) dn_solve<1>(Mf, tc, lane); else if (w == 2) dn_solve<2>(Mf, tc, lane); else dn_solve<3>(Mf, tc, lane);
.LBB0_114:
	s_andn2_b64 vcc, exec, s[0:1]
	s_cbranch_vccnz .LBB0_120
	s_mov_b64 s[86:87], -1
	s_cmp_eq_u32 s80, 1
	v_cmp_eq_u32_e64 s[46:47], 1, v52
	v_cmp_eq_u32_e64 s[76:77], 1, v53
	v_cmp_eq_u32_e64 s[44:45], 2, v52
	v_cmp_eq_u32_e64 s[74:75], 2, v53
	v_cmp_eq_u32_e32 vcc, 3, v52
	v_cmp_eq_u32_e64 s[72:73], 3, v53
	v_cmp_eq_u32_e64 s[70:71], 4, v53
	v_cmp_eq_u32_e64 s[68:69], 5, v53
	v_cmp_eq_u32_e64 s[66:67], 6, v53
	v_cmp_eq_u32_e64 s[64:65], 7, v53
	v_cmp_eq_u32_e64 s[62:63], 8, v53
	v_cmp_eq_u32_e64 s[60:61], 9, v53
	v_cmp_eq_u32_e64 s[58:59], 10, v53
	v_cmp_eq_u32_e64 s[56:57], 11, v53
	v_cmp_eq_u32_e64 s[54:55], 12, v53
	v_cmp_eq_u32_e64 s[52:53], 13, v53
	v_cmp_eq_u32_e64 s[0:1], 14, v53
	v_cmp_eq_u32_e64 s[48:49], 15, v53
	s_cbranch_scc1 .LBB0_117
	v_mov_b32_e32 v3, v1
	v_mov_b32_e32 v6, v1
	v_mov_b32_e32 v7, v1
	v_mov_b32_e32 v9, v1
	v_mov_b32_e32 v11, v1
	v_mov_b32_e32 v13, v1
	v_mov_b32_e32 v15, v1
	v_mov_b32_e32 v17, v1
	v_mov_b32_e32 v35, v1
	s_waitcnt lgkmcnt(14)
	ds_read_b32 v4, v56 offset:17664
	v_mov_b32_e32 v37, v1
	v_mov_b32_e32 v39, v1
	v_mov_b32_e32 v41, v1
	v_mov_b32_e32 v43, v1
	v_mov_b32_e32 v45, v1
	v_mov_b32_e32 v47, v1
	v_mov_b32_e32 v2, v57
	v_cndmask_b32_e64 v8, 0, 1.0, s[76:77]
	v_add_u32_e32 v10, 0x4800, v56
	v_add_u32_e32 v12, 0x5800, v56
	v_add_u32_e32 v14, 0x5c00, v56
	s_waitcnt lgkmcnt(0)
	v_fma_f32 v4, v4, v2, 0
	s_mov_b64 s[86:87], 0
	s_waitcnt lgkmcnt(0)
	s_nop 1
	v_add_f32_dpp v4, v4, v4 quad_perm:[1,0,3,2] row_mask:0xf bank_mask:0xf
	s_nop 1
	v_add_f32_dpp v4, v4, v4 quad_perm:[2,3,0,1] row_mask:0xf bank_mask:0xf
	v_sub_f32_e32 v4, v8, v4
	v_cndmask_b32_e64 v2, v2, v4, s[46:47]
	ds_read_b32 v4, v56 offset:17920
	v_cndmask_b32_e64 v8, 0, 1.0, s[74:75]
	s_waitcnt lgkmcnt(0)
	v_fma_f32 v4, v4, v2, 0
	s_nop 1
	v_add_f32_dpp v4, v4, v4 quad_perm:[1,0,3,2] row_mask:0xf bank_mask:0xf
	s_nop 1
	v_add_f32_dpp v4, v4, v4 quad_perm:[2,3,0,1] row_mask:0xf bank_mask:0xf
	v_sub_f32_e32 v4, v8, v4
	v_cndmask_b32_e64 v2, v2, v4, s[44:45]
	ds_read_b32 v4, v56 offset:18176
	v_cndmask_b32_e64 v8, 0, 1.0, s[72:73]
	s_waitcnt lgkmcnt(0)
	v_fma_f32 v4, v4, v2, 0
	s_nop 1
	v_add_f32_dpp v4, v4, v4 quad_perm:[1,0,3,2] row_mask:0xf bank_mask:0xf
	s_nop 1
	v_add_f32_dpp v4, v4, v4 quad_perm:[2,3,0,1] row_mask:0xf bank_mask:0xf
	v_sub_f32_e32 v4, v8, v4
	v_cndmask_b32_e32 v2, v2, v4, vcc
	ds_read_b32 v4, v56 offset:18432
	v_cndmask_b32_e64 v8, 0, 1.0, s[70:71]
	s_waitcnt lgkmcnt(0)
	v_fma_f32 v4, v4, v2, 0
	s_nop 1
	v_add_f32_dpp v4, v4, v4 quad_perm:[1,0,3,2] row_mask:0xf bank_mask:0xf
	s_waitcnt lgkmcnt(0)
	s_nop 1
	v_add_f32_dpp v4, v4, v4 quad_perm:[2,3,0,1] row_mask:0xf bank_mask:0xf
	v_sub_f32_e32 v4, v8, v4
	v_cndmask_b32_e64 v3, v3, v4, s[42:43]
	ds_read2_b32 v[4:5], v10 offset0:64 offset1:68
	v_cndmask_b32_e64 v8, 0, 1.0, s[68:69]
	s_waitcnt lgkmcnt(0)
	v_pk_mul_f32 v[4:5], v[4:5], v[2:3]
	s_nop 0
	v_add_f32_e32 v4, 0, v4
	v_add_f32_e32 v4, v4, v5
	s_nop 1
	v_add_f32_dpp v4, v4, v4 quad_perm:[1,0,3,2] row_mask:0xf bank_mask:0xf
	s_waitcnt lgkmcnt(0)
	s_nop 1
	v_add_f32_dpp v4, v4, v4 quad_perm:[2,3,0,1] row_mask:0xf bank_mask:0xf
	v_sub_f32_e32 v4, v8, v4
	v_cndmask_b32_e64 v3, v3, v4, s[46:47]
	ds_read2_b32 v[4:5], v10 offset0:128 offset1:132
	v_cndmask_b32_e64 v8, 0, 1.0, s[66:67]
	s_waitcnt lgkmcnt(0)
	v_pk_mul_f32 v[4:5], v[4:5], v[2:3]
	s_nop 0
	v_add_f32_e32 v4, 0, v4
	v_add_f32_e32 v4, v4, v5
	s_nop 1
	v_add_f32_dpp v4, v4, v4 quad_perm:[1,0,3,2] row_mask:0xf bank_mask:0xf
	s_waitcnt lgkmcnt(0)
	s_nop 1
	v_add_f32_dpp v4, v4, v4 quad_perm:[2,3,0,1] row_mask:0xf bank_mask:0xf
	v_sub_f32_e32 v4, v8, v4
	v_cndmask_b32_e64 v3, v3, v4, s[44:45]
	ds_read2_b32 v[4:5], v10 offset0:192 offset1:196
	v_cndmask_b32_e64 v8, 0, 1.0, s[64:65]
	v_add_u32_e32 v10, 0x4c00, v56
	s_waitcnt lgkmcnt(0)
	ds_read2_b32 v[58:59], v10 offset1:4
	v_pk_mul_f32 v[4:5], v[4:5], v[2:3]
	s_nop 0
	v_add_f32_e32 v4, 0, v4
	v_add_f32_e32 v4, v4, v5
	s_nop 1
	v_add_f32_dpp v4, v4, v4 quad_perm:[1,0,3,2] row_mask:0xf bank_mask:0xf
	s_nop 1
	v_add_f32_dpp v4, v4, v4 quad_perm:[2,3,0,1] row_mask:0xf bank_mask:0xf
	v_sub_f32_e32 v4, v8, v4
	v_cndmask_b32_e32 v4, v3, v4, vcc
	v_mov_b32_e32 v3, v4
	v_cndmask_b32_e64 v8, 0, 1.0, s[62:63]
	s_waitcnt lgkmcnt(0)
	v_pk_mul_f32 v[58:59], v[58:59], v[2:3]
	s_nop 0
	v_add_f32_e32 v3, 0, v58
	v_add_f32_e32 v3, v3, v59
	ds_read2_b32 v[58:59], v10 offset0:64 offset1:68
	ds_read_b32 v61, v56 offset:19744
	s_nop 1
	v_add_f32_dpp v3, v3, v3 quad_perm:[1,0,3,2] row_mask:0xf bank_mask:0xf
	s_nop 1
	v_add_f32_dpp v3, v3, v3 quad_perm:[2,3,0,1] row_mask:0xf bank_mask:0xf
	v_sub_f32_e32 v3, v8, v3
	v_cndmask_b32_e64 v5, v6, v3, s[42:43]
	v_cndmask_b32_e64 v8, 0, 1.0, s[60:61]
	s_waitcnt lgkmcnt(1)
	v_mov_b32_e32 v60, v59
	v_fma_f32 v3, v58, v2, 0
	s_waitcnt lgkmcnt(0)
	v_pk_mul_f32 v[58:59], v[4:5], v[60:61]
	s_nop 0
	v_add_f32_e32 v3, v3, v58
	v_add_f32_e32 v3, v3, v59
	ds_read2_b32 v[58:59], v10 offset0:128 offset1:132
	ds_read_b32 v61, v56 offset:20000
	s_nop 1
	v_add_f32_dpp v3, v3, v3 quad_perm:[1,0,3,2] row_mask:0xf bank_mask:0xf
	s_nop 1
	v_add_f32_dpp v3, v3, v3 quad_perm:[2,3,0,1] row_mask:0xf bank_mask:0xf
	v_sub_f32_e32 v3, v8, v3
	v_cndmask_b32_e64 v5, v5, v3, s[46:47]
	v_cndmask_b32_e64 v8, 0, 1.0, s[58:59]
	s_waitcnt lgkmcnt(1)
	v_mov_b32_e32 v60, v59
	v_fma_f32 v3, v58, v2, 0
	s_waitcnt lgkmcnt(0)
	v_pk_mul_f32 v[58:59], v[4:5], v[60:61]
	s_nop 0
	v_add_f32_e32 v3, v3, v58
	v_add_f32_e32 v3, v3, v59
	ds_read2_b32 v[58:59], v10 offset0:192 offset1:196
	ds_read_b32 v61, v56 offset:20256
	s_nop 1
	v_add_f32_dpp v3, v3, v3 quad_perm:[1,0,3,2] row_mask:0xf bank_mask:0xf
	s_nop 1
	v_add_f32_dpp v3, v3, v3 quad_perm:[2,3,0,1] row_mask:0xf bank_mask:0xf
	v_sub_f32_e32 v3, v8, v3
	v_cndmask_b32_e64 v5, v5, v3, s[44:45]
	v_cndmask_b32_e64 v8, 0, 1.0, s[56:57]
	v_add_u32_e32 v10, 0x5000, v56
	s_waitcnt lgkmcnt(1)
; template <int W> __device__ __forceinline__ void dn_solve(const LAS float* Mf, float (&t)[16], int lane) {
;     const int j = 16 * W + (lane >> 2), q = lane & 3;
; #pragma unroll
;     for (int s = 0; s < 16; ++s) t[s] = 0.f;
; #pragma unroll
;     for (int i = 16 * W; i < 64; ++i) {
;         float acc = 0.f;
; #pragma unroll
;         for (int s = 4 * W; s <= (i - 1) / 4 && i > 16 * W; ++s) acc += Mf[i * 64 + 4 * s + q] * t[s];
;         acc += __shfl_xor(acc, 1); acc += __shfl_xor(acc, 2);
;         const float val = (i == j ? 1.f : 0.f) - acc;
;         if (q == (i & 3)) t[i >> 2] = val;
;         asm volatile("" : "+v"(t[0]), "+v"(t[1]), "+v"(t[2]), "+v"(t[3]), "+v"(t[4]), "+v"(t[5]), "+v"(t[6]), "+v"(t[7]), "+v"(t[8]), "+v"(t[9]), "+v"(t[10]), "+v"(t[11]), "+v"(t[12]), "+v"(t[13]), "+v"(t[14]), "+v"(t[15]));
	v_mov_b32_e32 v60, v59
	v_fma_f32 v3, v58, v2, 0
	s_waitcnt lgkmcnt(0)
	v_pk_mul_f32 v[58:59], v[4:5], v[60:61]
	s_nop 0
	v_add_f32_e32 v3, v3, v58
	v_add_f32_e32 v3, v3, v59
	ds_read2_b32 v[58:59], v10 offset1:4
	ds_read_b32 v61, v56 offset:20512
	s_nop 1
	v_add_f32_dpp v3, v3, v3 quad_perm:[1,0,3,2] row_mask:0xf bank_mask:0xf
	s_nop 1
	v_add_f32_dpp v3, v3, v3 quad_perm:[2,3,0,1] row_mask:0xf bank_mask:0xf
	v_sub_f32_e32 v3, v8, v3
	v_cndmask_b32_e32 v6, v5, v3, vcc
	v_mov_b32_e32 v5, v6
	v_cndmask_b32_e64 v8, 0, 1.0, s[54:55]
	s_waitcnt lgkmcnt(1)
	v_mov_b32_e32 v60, v59
	v_fma_f32 v3, v58, v2, 0
	s_waitcnt lgkmcnt(0)
	v_pk_mul_f32 v[58:59], v[4:5], v[60:61]
	s_nop 0
	v_add_f32_e32 v3, v3, v58
	v_add_f32_e32 v3, v3, v59
	ds_read2_b32 v[58:59], v10 offset0:64 offset1:68
	ds_read2_b32 v[60:61], v10 offset0:72 offset1:76
	s_nop 1
	v_add_f32_dpp v3, v3, v3 quad_perm:[1,0,3,2] row_mask:0xf bank_mask:0xf
	s_nop 1
	v_add_f32_dpp v3, v3, v3 quad_perm:[2,3,0,1] row_mask:0xf bank_mask:0xf
	v_sub_f32_e32 v3, v8, v3
	v_cndmask_b32_e64 v7, v7, v3, s[42:43]
	v_mov_b32_e32 v3, v4
	v_cndmask_b32_e64 v8, 0, 1.0, s[52:53]
	s_waitcnt lgkmcnt(1)
	v_pk_mul_f32 v[58:59], v[58:59], v[2:3]
	s_nop 0
	v_add_f32_e32 v3, 0, v58
	s_waitcnt lgkmcnt(0)
	v_pk_mul_f32 v[60:61], v[6:7], v[60:61]
	v_add_f32_e32 v3, v3, v59
	v_add_f32_e32 v3, v3, v60
	v_add_f32_e32 v3, v3, v61
	ds_read2_b32 v[58:59], v10 offset0:128 offset1:132
	ds_read2_b32 v[60:61], v10 offset0:136 offset1:140
	s_nop 1
	v_add_f32_dpp v3, v3, v3 quad_perm:[1,0,3,2] row_mask:0xf bank_mask:0xf
	s_nop 1
	v_add_f32_dpp v3, v3, v3 quad_perm:[2,3,0,1] row_mask:0xf bank_mask:0xf
	v_sub_f32_e32 v3, v8, v3
	v_cndmask_b32_e64 v7, v7, v3, s[46:47]
	v_mov_b32_e32 v3, v4
	v_cndmask_b32_e64 v8, 0, 1.0, s[0:1]
	s_waitcnt lgkmcnt(1)
	v_pk_mul_f32 v[58:59], v[58:59], v[2:3]
	s_nop 0
	v_add_f32_e32 v3, 0, v58
	s_waitcnt lgkmcnt(0)
	v_pk_mul_f32 v[60:61], v[6:7], v[60:61]
	v_add_f32_e32 v3, v3, v59
	v_add_f32_e32 v3, v3, v60
	v_add_f32_e32 v3, v3, v61
	ds_read2_b32 v[58:59], v10 offset0:192 offset1:196
	ds_read2_b32 v[60:61], v10 offset0:200 offset1:204
	s_nop 1
	v_add_f32_dpp v3, v3, v3 quad_perm:[1,0,3,2] row_mask:0xf bank_mask:0xf
	s_nop 1
	v_add_f32_dpp v3, v3, v3 quad_perm:[2,3,0,1] row_mask:0xf bank_mask:0xf
	v_sub_f32_e32 v3, v8, v3
	v_cndmask_b32_e64 v7, v7, v3, s[44:45]
	v_mov_b32_e32 v3, v4
	v_cndmask_b32_e64 v8, 0, 1.0, s[48:49]
	v_add_u32_e32 v10, 0x5400, v56
	s_waitcnt lgkmcnt(1)
	v_pk_mul_f32 v[58:59], v[58:59], v[2:3]
	s_waitcnt lgkmcnt(0)
	v_pk_mul_f32 v[60:61], v[6:7], v[60:61]
	v_add_f32_e32 v3, 0, v58
	v_add_f32_e32 v3, v3, v59
	v_add_f32_e32 v3, v3, v60
	v_add_f32_e32 v3, v3, v61
	ds_read2_b32 v[58:59], v10 offset1:4
	ds_read2_b32 v[60:61], v10 offset0:8 offset1:12
	s_nop 1
	v_add_f32_dpp v3, v3, v3 quad_perm:[1,0,3,2] row_mask:0xf bank_mask:0xf
	s_nop 1
	v_add_f32_dpp v3, v3, v3 quad_perm:[2,3,0,1] row_mask:0xf bank_mask:0xf
	v_sub_f32_e32 v3, v8, v3
	v_cndmask_b32_e32 v8, v7, v3, vcc
	v_mov_b32_e32 v3, v4
	v_mov_b32_e32 v7, v8
	s_waitcnt lgkmcnt(1)
	v_pk_mul_f32 v[58:59], v[58:59], v[2:3]
	s_nop 0
	v_add_f32_e32 v3, 0, v58
	s_waitcnt lgkmcnt(0)
	v_pk_mul_f32 v[60:61], v[6:7], v[60:61]
	v_add_f32_e32 v3, v3, v59
	v_add_f32_e32 v3, v3, v60
	v_add_f32_e32 v3, v3, v61
	ds_read2_b32 v[58:59], v10 offset0:64 offset1:68
	ds_read2_b32 v[60:61], v10 offset0:72 offset1:76
	ds_read_b32 v63, v56 offset:21824
	s_nop 1
	v_add_f32_dpp v3, v3, v3 quad_perm:[1,0,3,2] row_mask:0xf bank_mask:0xf
	s_nop 1
	v_add_f32_dpp v3, v3, v3 quad_perm:[2,3,0,1] row_mask:0xf bank_mask:0xf
	v_sub_f32_e32 v3, 0, v3
	v_cndmask_b32_e64 v9, v9, v3, s[42:43]
	v_mov_b32_e32 v5, v6
	s_waitcnt lgkmcnt(2)
	v_fma_f32 v3, v58, v2, 0
	v_mov_b32_e32 v58, v59
	s_waitcnt lgkmcnt(1)
	v_mov_b32_e32 v59, v60
	v_pk_mul_f32 v[58:59], v[4:5], v[58:59]
	v_mov_b32_e32 v62, v61
	v_add_f32_e32 v3, v3, v58
	s_waitcnt lgkmcnt(0)
	v_pk_mul_f32 v[60:61], v[8:9], v[62:63]
	v_add_f32_e32 v3, v3, v59
	v_add_f32_e32 v3, v3, v60
	v_add_f32_e32 v3, v3, v61
	ds_read2_b32 v[58:59], v10 offset0:128 offset1:132
	ds_read2_b32 v[60:61], v10 offset0:136 offset1:140
	ds_read_b32 v63, v56 offset:22080
	s_nop 1
	v_add_f32_dpp v3, v3, v3 quad_perm:[1,0,3,2] row_mask:0xf bank_mask:0xf
	s_nop 1
	v_add_f32_dpp v3, v3, v3 quad_perm:[2,3,0,1] row_mask:0xf bank_mask:0xf
	v_sub_f32_e32 v3, 0, v3
	v_cndmask_b32_e64 v9, v9, v3, s[46:47]
	v_mov_b32_e32 v5, v6
	s_waitcnt lgkmcnt(2)
	v_fma_f32 v3, v58, v2, 0
	v_mov_b32_e32 v58, v59
	s_waitcnt lgkmcnt(1)
	v_mov_b32_e32 v59, v60
	v_pk_mul_f32 v[58:59], v[4:5], v[58:59]
	v_mov_b32_e32 v62, v61
	v_add_f32_e32 v3, v3, v58
	s_waitcnt lgkmcnt(0)
	v_pk_mul_f32 v[60:61], v[8:9], v[62:63]
	v_add_f32_e32 v3, v3, v59
	v_add_f32_e32 v3, v3, v60
	v_add_f32_e32 v3, v3, v61
	ds_read2_b32 v[58:59], v10 offset0:192 offset1:196
	ds_read2_b32 v[60:61], v10 offset0:200 offset1:204
	ds_read_b32 v63, v56 offset:22336
	s_nop 1
	v_add_f32_dpp v3, v3, v3 quad_perm:[1,0,3,2] row_mask:0xf bank_mask:0xf
	s_nop 1
	v_add_f32_dpp v3, v3, v3 quad_perm:[2,3,0,1] row_mask:0xf bank_mask:0xf
	v_sub_f32_e32 v3, 0, v3
	v_cndmask_b32_e64 v9, v9, v3, s[44:45]
	v_mov_b32_e32 v5, v6
	s_waitcnt lgkmcnt(2)
	v_fma_f32 v3, v58, v2, 0
	v_mov_b32_e32 v58, v59
	s_waitcnt lgkmcnt(1)
	v_mov_b32_e32 v59, v60
	v_pk_mul_f32 v[58:59], v[4:5], v[58:59]
	v_mov_b32_e32 v62, v61
	v_add_f32_e32 v3, v3, v58
	s_waitcnt lgkmcnt(0)
	v_pk_mul_f32 v[60:61], v[8:9], v[62:63]
	v_add_f32_e32 v3, v3, v59
	v_add_f32_e32 v3, v3, v60
	v_add_f32_e32 v3, v3, v61
	ds_read2_b32 v[58:59], v12 offset1:4
	ds_read2_b32 v[60:61], v12 offset0:8 offset1:12
	ds_read_b32 v63, v56 offset:22592
	s_nop 1
	v_add_f32_dpp v3, v3, v3 quad_perm:[1,0,3,2] row_mask:0xf bank_mask:0xf
	s_nop 1
	v_add_f32_dpp v3, v3, v3 quad_perm:[2,3,0,1] row_mask:0xf bank_mask:0xf
	v_sub_f32_e32 v3, 0, v3
	v_cndmask_b32_e32 v10, v9, v3, vcc
	v_mov_b32_e32 v5, v6
	v_mov_b32_e32 v9, v10
	s_waitcnt lgkmcnt(2)
; template <int W> __device__ __forceinline__ void dn_solve(const LAS float* Mf, float (&t)[16], int lane) {
;     const int j = 16 * W + (lane >> 2), q = lane & 3;
; #pragma unroll
;     for (int s = 0; s < 16; ++s) t[s] = 0.f;
; #pragma unroll
;     for (int i = 16 * W; i < 64; ++i) {
;         float acc = 0.f;
; #pragma unroll
;         for (int s = 4 * W; s <= (i - 1) / 4 && i > 16 * W; ++s) acc += Mf[i * 64 + 4 * s + q] * t[s];
;         acc += __shfl_xor(acc, 1); acc += __shfl_xor(acc, 2);
;         const float val = (i == j ? 1.f : 0.f) - acc;
;         if (q == (i & 3)) t[i >> 2] = val;
;         asm volatile("" : "+v"(t[0]), "+v"(t[1]), "+v"(t[2]), "+v"(t[3]), "+v"(t[4]), "+v"(t[5]), "+v"(t[6]), "+v"(t[7]), "+v"(t[8]), "+v"(t[9]), "+v"(t[10]), "+v"(t[11]), "+v"(t[12]), "+v"(t[13]), "+v"(t[14]), "+v"(t[15]));
	v_fma_f32 v3, v58, v2, 0
	v_mov_b32_e32 v58, v59
	s_waitcnt lgkmcnt(1)
	v_mov_b32_e32 v59, v60
	v_pk_mul_f32 v[58:59], v[4:5], v[58:59]
	v_mov_b32_e32 v62, v61
	v_add_f32_e32 v3, v3, v58
	s_waitcnt lgkmcnt(0)
	v_pk_mul_f32 v[60:61], v[8:9], v[62:63]
	v_add_f32_e32 v3, v3, v59
	v_add_f32_e32 v3, v3, v60
	v_add_f32_e32 v3, v3, v61
	ds_read2_b32 v[58:59], v12 offset0:64 offset1:68
	ds_read2_b32 v[60:61], v12 offset0:72 offset1:76
	ds_read2_b32 v[62:63], v12 offset0:80 offset1:84
	s_nop 1
	v_add_f32_dpp v3, v3, v3 quad_perm:[1,0,3,2] row_mask:0xf bank_mask:0xf
	s_nop 1
	v_add_f32_dpp v3, v3, v3 quad_perm:[2,3,0,1] row_mask:0xf bank_mask:0xf
	v_sub_f32_e32 v3, 0, v3
	v_cndmask_b32_e64 v11, v11, v3, s[42:43]
	v_mov_b32_e32 v7, v8
	s_waitcnt lgkmcnt(2)
	v_fma_f32 v3, v58, v2, 0
	s_waitcnt lgkmcnt(1)
	v_pk_mul_f32 v[60:61], v[6:7], v[60:61]
	v_fmac_f32_e32 v3, v4, v59
	v_add_f32_e32 v3, v3, v60
	s_waitcnt lgkmcnt(0)
	v_pk_mul_f32 v[62:63], v[10:11], v[62:63]
	v_add_f32_e32 v3, v3, v61
	v_add_f32_e32 v3, v3, v62
	v_add_f32_e32 v3, v3, v63
	ds_read2_b32 v[58:59], v12 offset0:128 offset1:132
	ds_read2_b32 v[60:61], v12 offset0:136 offset1:140
	ds_read2_b32 v[62:63], v12 offset0:144 offset1:148
	s_nop 1
	v_add_f32_dpp v3, v3, v3 quad_perm:[1,0,3,2] row_mask:0xf bank_mask:0xf
	s_nop 1
	v_add_f32_dpp v3, v3, v3 quad_perm:[2,3,0,1] row_mask:0xf bank_mask:0xf
	v_sub_f32_e32 v3, 0, v3
	v_cndmask_b32_e64 v11, v11, v3, s[46:47]
	v_mov_b32_e32 v7, v8
	s_waitcnt lgkmcnt(2)
	v_fma_f32 v3, v58, v2, 0
	s_waitcnt lgkmcnt(1)
	v_pk_mul_f32 v[60:61], v[6:7], v[60:61]
	v_fmac_f32_e32 v3, v4, v59
	v_add_f32_e32 v3, v3, v60
	s_waitcnt lgkmcnt(0)
	v_pk_mul_f32 v[62:63], v[10:11], v[62:63]
	v_add_f32_e32 v3, v3, v61
	v_add_f32_e32 v3, v3, v62
	v_add_f32_e32 v3, v3, v63
	ds_read2_b32 v[58:59], v12 offset0:192 offset1:196
	ds_read2_b32 v[60:61], v12 offset0:200 offset1:204
	ds_read2_b32 v[62:63], v12 offset0:208 offset1:212
	s_nop 1
	v_add_f32_dpp v3, v3, v3 quad_perm:[1,0,3,2] row_mask:0xf bank_mask:0xf
	s_nop 1
	v_add_f32_dpp v3, v3, v3 quad_perm:[2,3,0,1] row_mask:0xf bank_mask:0xf
	v_sub_f32_e32 v3, 0, v3
	v_cndmask_b32_e64 v11, v11, v3, s[44:45]
	v_mov_b32_e32 v7, v8
	s_waitcnt lgkmcnt(2)
	v_fma_f32 v3, v58, v2, 0
	s_waitcnt lgkmcnt(1)
	v_pk_mul_f32 v[60:61], v[6:7], v[60:61]
	v_fmac_f32_e32 v3, v4, v59
	v_add_f32_e32 v3, v3, v60
	s_waitcnt lgkmcnt(0)
	v_pk_mul_f32 v[62:63], v[10:11], v[62:63]
	v_add_f32_e32 v3, v3, v61
	v_add_f32_e32 v3, v3, v62
	v_add_f32_e32 v3, v3, v63
	ds_read2_b32 v[58:59], v14 offset1:4
	ds_read2_b32 v[60:61], v14 offset0:8 offset1:12
	ds_read2_b32 v[62:63], v14 offset0:16 offset1:20
	s_nop 1
	v_add_f32_dpp v3, v3, v3 quad_perm:[1,0,3,2] row_mask:0xf bank_mask:0xf
	s_nop 1
	v_add_f32_dpp v3, v3, v3 quad_perm:[2,3,0,1] row_mask:0xf bank_mask:0xf
	v_sub_f32_e32 v3, 0, v3
	v_cndmask_b32_e32 v12, v11, v3, vcc
	v_mov_b32_e32 v7, v8
	v_mov_b32_e32 v11, v12
	s_waitcnt lgkmcnt(2)
	v_fma_f32 v3, v58, v2, 0
	s_waitcnt lgkmcnt(1)
	v_pk_mul_f32 v[60:61], v[6:7], v[60:61]
	v_fmac_f32_e32 v3, v4, v59
	v_add_f32_e32 v3, v3, v60
	s_waitcnt lgkmcnt(0)
	v_pk_mul_f32 v[62:63], v[10:11], v[62:63]
	v_add_f32_e32 v3, v3, v61
	v_add_f32_e32 v3, v3, v62
	v_add_f32_e32 v3, v3, v63
	v_add_u32_e32 v7, 0x6000, v56
	s_waitcnt lgkmcnt(0)
	ds_read2_b32 v[58:59], v14 offset0:64 offset1:68
	ds_read2_b32 v[60:61], v14 offset0:72 offset1:76
	ds_read2_b32 v[62:63], v14 offset0:80 offset1:84
	ds_read_b32 v65, v56 offset:23904
	s_nop 1
	v_add_f32_dpp v3, v3, v3 quad_perm:[1,0,3,2] row_mask:0xf bank_mask:0xf
	s_nop 1
	v_add_f32_dpp v3, v3, v3 quad_perm:[2,3,0,1] row_mask:0xf bank_mask:0xf
	v_sub_f32_e32 v3, 0, v3
	v_cndmask_b32_e64 v13, v13, v3, s[42:43]
	v_mov_b32_e32 v9, v10
	s_waitcnt lgkmcnt(3)
	v_fma_f32 v3, v58, v2, 0
	s_waitcnt lgkmcnt(2)
	v_mov_b32_e32 v66, v61
	s_waitcnt lgkmcnt(1)
	v_mov_b32_e32 v67, v62
	v_fmac_f32_e32 v3, v4, v59
	v_pk_mul_f32 v[58:59], v[8:9], v[66:67]
	v_fmac_f32_e32 v3, v6, v60
	v_mov_b32_e32 v64, v63
	v_add_f32_e32 v3, v3, v58
	s_waitcnt lgkmcnt(0)
	v_pk_mul_f32 v[62:63], v[12:13], v[64:65]
	v_add_f32_e32 v3, v3, v59
	v_add_f32_e32 v3, v3, v62
	v_add_f32_e32 v3, v3, v63
	ds_read2_b32 v[58:59], v14 offset0:128 offset1:132
	ds_read2_b32 v[60:61], v14 offset0:136 offset1:140
	ds_read2_b32 v[62:63], v14 offset0:144 offset1:148
	ds_read_b32 v65, v56 offset:24160
	s_nop 1
	v_add_f32_dpp v3, v3, v3 quad_perm:[1,0,3,2] row_mask:0xf bank_mask:0xf
	s_nop 1
	v_add_f32_dpp v3, v3, v3 quad_perm:[2,3,0,1] row_mask:0xf bank_mask:0xf
	v_sub_f32_e32 v3, 0, v3
	v_cndmask_b32_e64 v13, v13, v3, s[46:47]
	v_mov_b32_e32 v9, v10
	s_waitcnt lgkmcnt(3)
	v_fma_f32 v3, v58, v2, 0
	s_waitcnt lgkmcnt(2)
	v_mov_b32_e32 v66, v61
	s_waitcnt lgkmcnt(1)
	v_mov_b32_e32 v67, v62
	v_fmac_f32_e32 v3, v4, v59
	v_pk_mul_f32 v[58:59], v[8:9], v[66:67]
	v_fmac_f32_e32 v3, v6, v60
	v_mov_b32_e32 v64, v63
	v_add_f32_e32 v3, v3, v58
	s_waitcnt lgkmcnt(0)
	v_pk_mul_f32 v[62:63], v[12:13], v[64:65]
	v_add_f32_e32 v3, v3, v59
	v_add_f32_e32 v3, v3, v62
	v_add_f32_e32 v3, v3, v63
	ds_read2_b32 v[58:59], v14 offset0:192 offset1:196
	ds_read2_b32 v[60:61], v14 offset0:200 offset1:204
	ds_read2_b32 v[62:63], v14 offset0:208 offset1:212
	ds_read_b32 v65, v56 offset:24416
	s_nop 1
	v_add_f32_dpp v3, v3, v3 quad_perm:[1,0,3,2] row_mask:0xf bank_mask:0xf
	s_nop 1
	v_add_f32_dpp v3, v3, v3 quad_perm:[2,3,0,1] row_mask:0xf bank_mask:0xf
	v_sub_f32_e32 v3, 0, v3
	v_cndmask_b32_e64 v13, v13, v3, s[44:45]
	v_mov_b32_e32 v9, v10
	s_waitcnt lgkmcnt(3)
	v_fma_f32 v3, v58, v2, 0
	s_waitcnt lgkmcnt(2)
	v_mov_b32_e32 v66, v61
	s_waitcnt lgkmcnt(1)
; template <int W> __device__ __forceinline__ void dn_solve(const LAS float* Mf, float (&t)[16], int lane) {
;     const int j = 16 * W + (lane >> 2), q = lane & 3;
; #pragma unroll
;     for (int s = 0; s < 16; ++s) t[s] = 0.f;
; #pragma unroll
;     for (int i = 16 * W; i < 64; ++i) {
;         float acc = 0.f;
; #pragma unroll
;         for (int s = 4 * W; s <= (i - 1) / 4 && i > 16 * W; ++s) acc += Mf[i * 64 + 4 * s + q] * t[s];
;         acc += __shfl_xor(acc, 1); acc += __shfl_xor(acc, 2);
;         const float val = (i == j ? 1.f : 0.f) - acc;
;         if (q == (i & 3)) t[i >> 2] = val;
;         asm volatile("" : "+v"(t[0]), "+v"(t[1]), "+v"(t[2]), "+v"(t[3]), "+v"(t[4]), "+v"(t[5]), "+v"(t[6]), "+v"(t[7]), "+v"(t[8]), "+v"(t[9]), "+v"(t[10]), "+v"(t[11]), "+v"(t[12]), "+v"(t[13]), "+v"(t[14]), "+v"(t[15]));
	v_mov_b32_e32 v67, v62
	v_fmac_f32_e32 v3, v4, v59
	v_pk_mul_f32 v[58:59], v[8:9], v[66:67]
	v_fmac_f32_e32 v3, v6, v60
	v_mov_b32_e32 v64, v63
	v_add_f32_e32 v3, v3, v58
	s_waitcnt lgkmcnt(0)
	v_pk_mul_f32 v[62:63], v[12:13], v[64:65]
	v_add_f32_e32 v3, v3, v59
	v_add_f32_e32 v3, v3, v62
	v_add_f32_e32 v3, v3, v63
	ds_read2_b32 v[58:59], v7 offset1:4
	ds_read2_b32 v[60:61], v7 offset0:8 offset1:12
	ds_read2_b32 v[62:63], v7 offset0:16 offset1:20
	ds_read_b32 v65, v56 offset:24672
	s_nop 1
	v_add_f32_dpp v3, v3, v3 quad_perm:[1,0,3,2] row_mask:0xf bank_mask:0xf
	s_nop 1
	v_add_f32_dpp v3, v3, v3 quad_perm:[2,3,0,1] row_mask:0xf bank_mask:0xf
	v_sub_f32_e32 v3, 0, v3
	v_cndmask_b32_e32 v14, v13, v3, vcc
	v_mov_b32_e32 v9, v10
	s_waitcnt lgkmcnt(3)
	v_fma_f32 v3, v58, v2, 0
	s_waitcnt lgkmcnt(2)
	v_mov_b32_e32 v66, v61
	s_waitcnt lgkmcnt(1)
	v_mov_b32_e32 v67, v62
	v_fmac_f32_e32 v3, v4, v59
	v_pk_mul_f32 v[58:59], v[8:9], v[66:67]
	v_fmac_f32_e32 v3, v6, v60
	v_mov_b32_e32 v13, v14
	v_mov_b32_e32 v64, v63
	v_add_f32_e32 v3, v3, v58
	s_waitcnt lgkmcnt(0)
	v_pk_mul_f32 v[62:63], v[12:13], v[64:65]
	v_add_f32_e32 v3, v3, v59
	v_add_f32_e32 v3, v3, v62
	v_add_f32_e32 v3, v3, v63
	ds_read2_b32 v[58:59], v7 offset0:64 offset1:68
	ds_read2_b32 v[60:61], v7 offset0:80 offset1:84
	ds_read2_b32 v[62:63], v7 offset0:88 offset1:92
	ds_read2_b32 v[64:65], v7 offset0:72 offset1:76
	s_nop 1
	v_add_f32_dpp v3, v3, v3 quad_perm:[1,0,3,2] row_mask:0xf bank_mask:0xf
	s_nop 1
	v_add_f32_dpp v3, v3, v3 quad_perm:[2,3,0,1] row_mask:0xf bank_mask:0xf
	v_sub_f32_e32 v3, 0, v3
	v_cndmask_b32_e64 v15, v15, v3, s[42:43]
	v_mov_b32_e32 v11, v12
	s_waitcnt lgkmcnt(3)
	v_fma_f32 v3, v58, v2, 0
	v_fmac_f32_e32 v3, v4, v59
	s_waitcnt lgkmcnt(2)
	v_pk_mul_f32 v[60:61], v[10:11], v[60:61]
	s_waitcnt lgkmcnt(0)
	v_fmac_f32_e32 v3, v6, v64
	v_fmac_f32_e32 v3, v8, v65
	v_add_f32_e32 v3, v3, v60
	v_pk_mul_f32 v[62:63], v[14:15], v[62:63]
	v_add_f32_e32 v3, v3, v61
	v_add_f32_e32 v3, v3, v62
	v_add_f32_e32 v3, v3, v63
	ds_read2_b32 v[58:59], v7 offset0:128 offset1:132
	ds_read2_b32 v[60:61], v7 offset0:144 offset1:148
	ds_read2_b32 v[62:63], v7 offset0:152 offset1:156
	ds_read2_b32 v[64:65], v7 offset0:136 offset1:140
	s_nop 1
	v_add_f32_dpp v3, v3, v3 quad_perm:[1,0,3,2] row_mask:0xf bank_mask:0xf
	s_nop 1
	v_add_f32_dpp v3, v3, v3 quad_perm:[2,3,0,1] row_mask:0xf bank_mask:0xf
	v_sub_f32_e32 v3, 0, v3
	v_cndmask_b32_e64 v15, v15, v3, s[46:47]
	v_mov_b32_e32 v11, v12
	s_waitcnt lgkmcnt(3)
	v_fma_f32 v3, v58, v2, 0
	v_fmac_f32_e32 v3, v4, v59
	s_waitcnt lgkmcnt(2)
	v_pk_mul_f32 v[60:61], v[10:11], v[60:61]
	s_waitcnt lgkmcnt(0)
	v_fmac_f32_e32 v3, v6, v64
	v_fmac_f32_e32 v3, v8, v65
	v_add_f32_e32 v3, v3, v60
	v_pk_mul_f32 v[62:63], v[14:15], v[62:63]
	v_add_f32_e32 v3, v3, v61
	v_add_f32_e32 v3, v3, v62
	v_add_f32_e32 v3, v3, v63
	ds_read2_b32 v[58:59], v7 offset0:192 offset1:196
	ds_read2_b32 v[60:61], v7 offset0:208 offset1:212
	ds_read2_b32 v[62:63], v7 offset0:216 offset1:220
	ds_read2_b32 v[64:65], v7 offset0:200 offset1:204
	s_nop 1
	v_add_f32_dpp v3, v3, v3 quad_perm:[1,0,3,2] row_mask:0xf bank_mask:0xf
	s_nop 1
	v_add_f32_dpp v3, v3, v3 quad_perm:[2,3,0,1] row_mask:0xf bank_mask:0xf
	v_sub_f32_e32 v3, 0, v3
	v_cndmask_b32_e64 v15, v15, v3, s[44:45]
	v_mov_b32_e32 v11, v12
	s_waitcnt lgkmcnt(3)
	v_fma_f32 v3, v58, v2, 0
	v_fmac_f32_e32 v3, v4, v59
	s_waitcnt lgkmcnt(2)
	v_pk_mul_f32 v[60:61], v[10:11], v[60:61]
	s_waitcnt lgkmcnt(0)
	v_fmac_f32_e32 v3, v6, v64
	v_fmac_f32_e32 v3, v8, v65
	v_add_f32_e32 v3, v3, v60
	v_pk_mul_f32 v[62:63], v[14:15], v[62:63]
	v_add_f32_e32 v3, v3, v61
	v_add_f32_e32 v3, v3, v62
	v_add_f32_e32 v3, v3, v63
	v_add_u32_e32 v7, 0x6400, v56
	s_waitcnt lgkmcnt(0)
	ds_read2_b32 v[58:59], v7 offset1:4
	ds_read2_b32 v[60:61], v7 offset0:8 offset1:12
	ds_read2_b32 v[62:63], v7 offset0:16 offset1:20
	ds_read2_b32 v[64:65], v7 offset0:24 offset1:28
	s_nop 1
	v_add_f32_dpp v3, v3, v3 quad_perm:[1,0,3,2] row_mask:0xf bank_mask:0xf
	s_nop 1
	v_add_f32_dpp v3, v3, v3 quad_perm:[2,3,0,1] row_mask:0xf bank_mask:0xf
	v_sub_f32_e32 v3, 0, v3
	v_cndmask_b32_e32 v16, v15, v3, vcc
	v_mov_b32_e32 v11, v12
	s_waitcnt lgkmcnt(3)
	v_fma_f32 v3, v58, v2, 0
	v_fmac_f32_e32 v3, v4, v59
	s_waitcnt lgkmcnt(2)
	v_fmac_f32_e32 v3, v6, v60
	s_waitcnt lgkmcnt(1)
	v_pk_mul_f32 v[62:63], v[10:11], v[62:63]
	v_fmac_f32_e32 v3, v8, v61
	v_mov_b32_e32 v15, v16
	v_add_f32_e32 v3, v3, v62
	s_waitcnt lgkmcnt(0)
	v_pk_mul_f32 v[64:65], v[14:15], v[64:65]
	v_add_f32_e32 v3, v3, v63
	v_add_f32_e32 v3, v3, v64
	v_add_f32_e32 v3, v3, v65
	ds_read2_b32 v[58:59], v7 offset0:64 offset1:68
	ds_read2_b32 v[60:61], v7 offset0:72 offset1:76
	ds_read2_b32 v[62:63], v7 offset0:80 offset1:84
	ds_read2_b32 v[64:65], v7 offset0:88 offset1:92
	ds_read_b32 v67, v56 offset:25984
	s_nop 1
	v_add_f32_dpp v3, v3, v3 quad_perm:[1,0,3,2] row_mask:0xf bank_mask:0xf
	s_nop 1
	v_add_f32_dpp v3, v3, v3 quad_perm:[2,3,0,1] row_mask:0xf bank_mask:0xf
	v_sub_f32_e32 v3, 0, v3
	v_cndmask_b32_e64 v17, v17, v3, s[42:43]
	s_waitcnt lgkmcnt(4)
	v_fma_f32 v3, v58, v2, 0
	v_fmac_f32_e32 v3, v4, v59
	s_waitcnt lgkmcnt(3)
	v_fmac_f32_e32 v3, v6, v60
	v_mov_b32_e32 v13, v14
	s_waitcnt lgkmcnt(2)
	v_mov_b32_e32 v68, v63
	s_waitcnt lgkmcnt(1)
	v_mov_b32_e32 v69, v64
	v_fmac_f32_e32 v3, v8, v61
	v_pk_mul_f32 v[58:59], v[12:13], v[68:69]
	v_fmac_f32_e32 v3, v10, v62
	v_mov_b32_e32 v66, v65
	v_add_f32_e32 v3, v3, v58
	s_waitcnt lgkmcnt(0)
; template <int W> __device__ __forceinline__ void dn_solve(const LAS float* Mf, float (&t)[16], int lane) {
;     const int j = 16 * W + (lane >> 2), q = lane & 3;
; #pragma unroll
;     for (int s = 0; s < 16; ++s) t[s] = 0.f;
; #pragma unroll
;     for (int i = 16 * W; i < 64; ++i) {
;         float acc = 0.f;
; #pragma unroll
;         for (int s = 4 * W; s <= (i - 1) / 4 && i > 16 * W; ++s) acc += Mf[i * 64 + 4 * s + q] * t[s];
;         acc += __shfl_xor(acc, 1); acc += __shfl_xor(acc, 2);
;         const float val = (i == j ? 1.f : 0.f) - acc;
;         if (q == (i & 3)) t[i >> 2] = val;
;         asm volatile("" : "+v"(t[0]), "+v"(t[1]), "+v"(t[2]), "+v"(t[3]), "+v"(t[4]), "+v"(t[5]), "+v"(t[6]), "+v"(t[7]), "+v"(t[8]), "+v"(t[9]), "+v"(t[10]), "+v"(t[11]), "+v"(t[12]), "+v"(t[13]), "+v"(t[14]), "+v"(t[15]));
	v_pk_mul_f32 v[64:65], v[16:17], v[66:67]
	v_add_f32_e32 v3, v3, v59
	v_add_f32_e32 v3, v3, v64
	v_add_f32_e32 v3, v3, v65
	ds_read2_b32 v[58:59], v7 offset0:128 offset1:132
	ds_read2_b32 v[60:61], v7 offset0:136 offset1:140
	ds_read2_b32 v[62:63], v7 offset0:144 offset1:148
	ds_read2_b32 v[64:65], v7 offset0:152 offset1:156
	ds_read_b32 v67, v56 offset:26240
	s_nop 1
	v_add_f32_dpp v3, v3, v3 quad_perm:[1,0,3,2] row_mask:0xf bank_mask:0xf
	s_nop 1
	v_add_f32_dpp v3, v3, v3 quad_perm:[2,3,0,1] row_mask:0xf bank_mask:0xf
	v_sub_f32_e32 v3, 0, v3
	v_cndmask_b32_e64 v17, v17, v3, s[46:47]
	s_waitcnt lgkmcnt(4)
	v_fma_f32 v3, v58, v2, 0
	v_fmac_f32_e32 v3, v4, v59
	s_waitcnt lgkmcnt(3)
	v_fmac_f32_e32 v3, v6, v60
	v_mov_b32_e32 v13, v14
	s_waitcnt lgkmcnt(2)
	v_mov_b32_e32 v68, v63
	s_waitcnt lgkmcnt(1)
	v_mov_b32_e32 v69, v64
	v_fmac_f32_e32 v3, v8, v61
	v_pk_mul_f32 v[58:59], v[12:13], v[68:69]
	v_fmac_f32_e32 v3, v10, v62
	v_mov_b32_e32 v66, v65
	v_add_f32_e32 v3, v3, v58
	s_waitcnt lgkmcnt(0)
	v_pk_mul_f32 v[64:65], v[16:17], v[66:67]
	v_add_f32_e32 v3, v3, v59
	v_add_f32_e32 v3, v3, v64
	v_add_f32_e32 v3, v3, v65
	ds_read2_b32 v[58:59], v7 offset0:192 offset1:196
	ds_read2_b32 v[60:61], v7 offset0:200 offset1:204
	ds_read2_b32 v[62:63], v7 offset0:208 offset1:212
	ds_read2_b32 v[64:65], v7 offset0:216 offset1:220
	ds_read_b32 v67, v56 offset:26496
	s_nop 1
	v_add_f32_dpp v3, v3, v3 quad_perm:[1,0,3,2] row_mask:0xf bank_mask:0xf
	s_nop 1
	v_add_f32_dpp v3, v3, v3 quad_perm:[2,3,0,1] row_mask:0xf bank_mask:0xf
	v_sub_f32_e32 v3, 0, v3
	v_cndmask_b32_e64 v17, v17, v3, s[44:45]
	s_waitcnt lgkmcnt(4)
	v_fma_f32 v3, v58, v2, 0
	v_fmac_f32_e32 v3, v4, v59
	s_waitcnt lgkmcnt(3)
	v_fmac_f32_e32 v3, v6, v60
	v_mov_b32_e32 v13, v14
	s_waitcnt lgkmcnt(2)
	v_mov_b32_e32 v68, v63
	s_waitcnt lgkmcnt(1)
	v_mov_b32_e32 v69, v64
	v_fmac_f32_e32 v3, v8, v61
	v_pk_mul_f32 v[58:59], v[12:13], v[68:69]
	v_fmac_f32_e32 v3, v10, v62
	v_mov_b32_e32 v66, v65
	v_add_f32_e32 v3, v3, v58
	s_waitcnt lgkmcnt(0)
	v_pk_mul_f32 v[64:65], v[16:17], v[66:67]
	v_add_f32_e32 v3, v3, v59
	v_add_f32_e32 v3, v3, v64
	v_add_f32_e32 v3, v3, v65
	v_add_u32_e32 v7, 0x6800, v56
	s_waitcnt lgkmcnt(0)
	ds_read2_b32 v[58:59], v7 offset1:4
	ds_read2_b32 v[60:61], v7 offset0:8 offset1:12
	ds_read2_b32 v[62:63], v7 offset0:16 offset1:20
	ds_read2_b32 v[64:65], v7 offset0:24 offset1:28
	ds_read_b32 v67, v56 offset:26752
	s_nop 1
	v_add_f32_dpp v3, v3, v3 quad_perm:[1,0,3,2] row_mask:0xf bank_mask:0xf
	s_nop 1
	v_add_f32_dpp v3, v3, v3 quad_perm:[2,3,0,1] row_mask:0xf bank_mask:0xf
	v_sub_f32_e32 v3, 0, v3
	v_cndmask_b32_e32 v34, v17, v3, vcc
	s_waitcnt lgkmcnt(4)
	v_fma_f32 v3, v58, v2, 0
	v_fmac_f32_e32 v3, v4, v59
	s_waitcnt lgkmcnt(3)
	v_fmac_f32_e32 v3, v6, v60
	v_mov_b32_e32 v13, v14
	s_waitcnt lgkmcnt(2)
	v_mov_b32_e32 v68, v63
	s_waitcnt lgkmcnt(1)
	v_mov_b32_e32 v69, v64
	v_fmac_f32_e32 v3, v8, v61
	v_pk_mul_f32 v[58:59], v[12:13], v[68:69]
	v_fmac_f32_e32 v3, v10, v62
	v_mov_b32_e32 v17, v34
	v_mov_b32_e32 v66, v65
	v_add_f32_e32 v3, v3, v58
	s_waitcnt lgkmcnt(0)
	v_pk_mul_f32 v[64:65], v[16:17], v[66:67]
	v_add_f32_e32 v3, v3, v59
	v_add_f32_e32 v3, v3, v64
	v_add_f32_e32 v3, v3, v65
	ds_read2_b32 v[58:59], v7 offset0:64 offset1:68
	ds_read2_b32 v[60:61], v7 offset0:72 offset1:76
	ds_read2_b32 v[62:63], v7 offset0:88 offset1:92
	ds_read2_b32 v[64:65], v7 offset0:96 offset1:100
	ds_read2_b32 v[66:67], v7 offset0:80 offset1:84
	s_nop 1
	v_add_f32_dpp v3, v3, v3 quad_perm:[1,0,3,2] row_mask:0xf bank_mask:0xf
	s_nop 1
	v_add_f32_dpp v3, v3, v3 quad_perm:[2,3,0,1] row_mask:0xf bank_mask:0xf
	v_sub_f32_e32 v3, 0, v3
	v_cndmask_b32_e64 v35, v35, v3, s[42:43]
	s_waitcnt lgkmcnt(4)
	v_fma_f32 v3, v58, v2, 0
	v_fmac_f32_e32 v3, v4, v59
	s_waitcnt lgkmcnt(3)
	v_fmac_f32_e32 v3, v6, v60
	v_fmac_f32_e32 v3, v8, v61
	v_mov_b32_e32 v15, v16
	s_waitcnt lgkmcnt(0)
	v_fmac_f32_e32 v3, v10, v66
	v_pk_mul_f32 v[62:63], v[14:15], v[62:63]
	v_fmac_f32_e32 v3, v12, v67
	v_add_f32_e32 v3, v3, v62
	v_pk_mul_f32 v[64:65], v[34:35], v[64:65]
	v_add_f32_e32 v3, v3, v63
	v_add_f32_e32 v3, v3, v64
	v_add_f32_e32 v3, v3, v65
	ds_read2_b32 v[58:59], v7 offset0:128 offset1:132
	ds_read2_b32 v[60:61], v7 offset0:136 offset1:140
	ds_read2_b32 v[62:63], v7 offset0:152 offset1:156
	ds_read2_b32 v[64:65], v7 offset0:160 offset1:164
	ds_read2_b32 v[66:67], v7 offset0:144 offset1:148
	s_nop 1
	v_add_f32_dpp v3, v3, v3 quad_perm:[1,0,3,2] row_mask:0xf bank_mask:0xf
	s_nop 1
	v_add_f32_dpp v3, v3, v3 quad_perm:[2,3,0,1] row_mask:0xf bank_mask:0xf
	v_sub_f32_e32 v3, 0, v3
	v_cndmask_b32_e64 v35, v35, v3, s[46:47]
	s_waitcnt lgkmcnt(4)
	v_fma_f32 v3, v58, v2, 0
	v_fmac_f32_e32 v3, v4, v59
	s_waitcnt lgkmcnt(3)
	v_fmac_f32_e32 v3, v6, v60
	v_fmac_f32_e32 v3, v8, v61
	v_mov_b32_e32 v15, v16
	s_waitcnt lgkmcnt(0)
	v_fmac_f32_e32 v3, v10, v66
	v_pk_mul_f32 v[62:63], v[14:15], v[62:63]
	v_fmac_f32_e32 v3, v12, v67
	v_add_f32_e32 v3, v3, v62
	v_pk_mul_f32 v[64:65], v[34:35], v[64:65]
	v_add_f32_e32 v3, v3, v63
	v_add_f32_e32 v3, v3, v64
	v_add_f32_e32 v3, v3, v65
	ds_read2_b32 v[58:59], v7 offset0:192 offset1:196
	ds_read2_b32 v[60:61], v7 offset0:200 offset1:204
	ds_read2_b32 v[62:63], v7 offset0:216 offset1:220
	ds_read2_b32 v[64:65], v7 offset0:224 offset1:228
	ds_read2_b32 v[66:67], v7 offset0:208 offset1:212
	s_nop 1
	v_add_f32_dpp v3, v3, v3 quad_perm:[1,0,3,2] row_mask:0xf bank_mask:0xf
	s_nop 1
	v_add_f32_dpp v3, v3, v3 quad_perm:[2,3,0,1] row_mask:0xf bank_mask:0xf
	v_sub_f32_e32 v3, 0, v3
	v_cndmask_b32_e64 v35, v35, v3, s[44:45]
	s_waitcnt lgkmcnt(4)
	v_fma_f32 v3, v58, v2, 0
	v_fmac_f32_e32 v3, v4, v59
	s_waitcnt lgkmcnt(3)
; template <int W> __device__ __forceinline__ void dn_solve(const LAS float* Mf, float (&t)[16], int lane) {
;     const int j = 16 * W + (lane >> 2), q = lane & 3;
; #pragma unroll
;     for (int s = 0; s < 16; ++s) t[s] = 0.f;
; #pragma unroll
;     for (int i = 16 * W; i < 64; ++i) {
;         float acc = 0.f;
; #pragma unroll
;         for (int s = 4 * W; s <= (i - 1) / 4 && i > 16 * W; ++s) acc += Mf[i * 64 + 4 * s + q] * t[s];
;         acc += __shfl_xor(acc, 1); acc += __shfl_xor(acc, 2);
;         const float val = (i == j ? 1.f : 0.f) - acc;
;         if (q == (i & 3)) t[i >> 2] = val;
;         asm volatile("" : "+v"(t[0]), "+v"(t[1]), "+v"(t[2]), "+v"(t[3]), "+v"(t[4]), "+v"(t[5]), "+v"(t[6]), "+v"(t[7]), "+v"(t[8]), "+v"(t[9]), "+v"(t[10]), "+v"(t[11]), "+v"(t[12]), "+v"(t[13]), "+v"(t[14]), "+v"(t[15]));
	v_fmac_f32_e32 v3, v6, v60
	v_fmac_f32_e32 v3, v8, v61
	v_mov_b32_e32 v15, v16
	s_waitcnt lgkmcnt(0)
	v_fmac_f32_e32 v3, v10, v66
	v_pk_mul_f32 v[62:63], v[14:15], v[62:63]
	v_fmac_f32_e32 v3, v12, v67
	v_add_f32_e32 v3, v3, v62
	v_pk_mul_f32 v[64:65], v[34:35], v[64:65]
	v_add_f32_e32 v3, v3, v63
	v_add_f32_e32 v3, v3, v64
	v_add_f32_e32 v3, v3, v65
	v_add_u32_e32 v7, 0x6c00, v56
	s_waitcnt lgkmcnt(0)
	ds_read2_b32 v[58:59], v7 offset1:4
	ds_read2_b32 v[60:61], v7 offset0:8 offset1:12
	ds_read2_b32 v[62:63], v7 offset0:16 offset1:20
	ds_read2_b32 v[64:65], v7 offset0:24 offset1:28
	ds_read2_b32 v[66:67], v7 offset0:32 offset1:36
	s_nop 1
	v_add_f32_dpp v3, v3, v3 quad_perm:[1,0,3,2] row_mask:0xf bank_mask:0xf
	s_nop 1
	v_add_f32_dpp v3, v3, v3 quad_perm:[2,3,0,1] row_mask:0xf bank_mask:0xf
	v_sub_f32_e32 v3, 0, v3
	v_cndmask_b32_e32 v36, v35, v3, vcc
	s_waitcnt lgkmcnt(4)
	v_fma_f32 v3, v58, v2, 0
	v_fmac_f32_e32 v3, v4, v59
	s_waitcnt lgkmcnt(3)
	v_fmac_f32_e32 v3, v6, v60
	v_fmac_f32_e32 v3, v8, v61
	v_mov_b32_e32 v15, v16
	s_waitcnt lgkmcnt(2)
	v_fmac_f32_e32 v3, v10, v62
	s_waitcnt lgkmcnt(1)
	v_pk_mul_f32 v[64:65], v[14:15], v[64:65]
	v_fmac_f32_e32 v3, v12, v63
	v_mov_b32_e32 v35, v36
	v_add_f32_e32 v3, v3, v64
	s_waitcnt lgkmcnt(0)
	v_pk_mul_f32 v[66:67], v[34:35], v[66:67]
	v_add_f32_e32 v3, v3, v65
	v_add_f32_e32 v3, v3, v66
	v_add_f32_e32 v3, v3, v67
	ds_read2_b32 v[58:59], v7 offset0:64 offset1:68
	ds_read2_b32 v[60:61], v7 offset0:72 offset1:76
	ds_read2_b32 v[62:63], v7 offset0:80 offset1:84
	ds_read2_b32 v[64:65], v7 offset0:88 offset1:92
	ds_read2_b32 v[66:67], v7 offset0:96 offset1:100
	ds_read_b32 v69, v56 offset:28064
	s_nop 1
	v_add_f32_dpp v3, v3, v3 quad_perm:[1,0,3,2] row_mask:0xf bank_mask:0xf
	s_nop 1
	v_add_f32_dpp v3, v3, v3 quad_perm:[2,3,0,1] row_mask:0xf bank_mask:0xf
	v_sub_f32_e32 v3, 0, v3
	v_cndmask_b32_e64 v37, v37, v3, s[42:43]
	s_waitcnt lgkmcnt(5)
	v_fma_f32 v3, v58, v2, 0
	v_fmac_f32_e32 v3, v4, v59
	s_waitcnt lgkmcnt(4)
	v_fmac_f32_e32 v3, v6, v60
	v_fmac_f32_e32 v3, v8, v61
	s_waitcnt lgkmcnt(3)
	v_fmac_f32_e32 v3, v10, v62
	v_mov_b32_e32 v17, v34
	s_waitcnt lgkmcnt(2)
	v_mov_b32_e32 v70, v65
	s_waitcnt lgkmcnt(1)
	v_mov_b32_e32 v71, v66
	v_fmac_f32_e32 v3, v12, v63
	v_pk_mul_f32 v[58:59], v[16:17], v[70:71]
	v_fmac_f32_e32 v3, v14, v64
	v_mov_b32_e32 v68, v67
	v_add_f32_e32 v3, v3, v58
	s_waitcnt lgkmcnt(0)
	v_pk_mul_f32 v[66:67], v[36:37], v[68:69]
	v_add_f32_e32 v3, v3, v59
	v_add_f32_e32 v3, v3, v66
	v_add_f32_e32 v3, v3, v67
	ds_read2_b32 v[58:59], v7 offset0:128 offset1:132
	ds_read2_b32 v[60:61], v7 offset0:136 offset1:140
	ds_read2_b32 v[62:63], v7 offset0:144 offset1:148
	ds_read2_b32 v[64:65], v7 offset0:152 offset1:156
	ds_read2_b32 v[66:67], v7 offset0:160 offset1:164
	ds_read_b32 v69, v56 offset:28320
	s_nop 1
	v_add_f32_dpp v3, v3, v3 quad_perm:[1,0,3,2] row_mask:0xf bank_mask:0xf
	s_nop 1
	v_add_f32_dpp v3, v3, v3 quad_perm:[2,3,0,1] row_mask:0xf bank_mask:0xf
	v_sub_f32_e32 v3, 0, v3
	v_cndmask_b32_e64 v37, v37, v3, s[46:47]
	s_waitcnt lgkmcnt(5)
	v_fma_f32 v3, v58, v2, 0
	v_fmac_f32_e32 v3, v4, v59
	s_waitcnt lgkmcnt(4)
	v_fmac_f32_e32 v3, v6, v60
	v_fmac_f32_e32 v3, v8, v61
	s_waitcnt lgkmcnt(3)
	v_fmac_f32_e32 v3, v10, v62
	v_mov_b32_e32 v17, v34
	s_waitcnt lgkmcnt(2)
	v_mov_b32_e32 v70, v65
	s_waitcnt lgkmcnt(1)
	v_mov_b32_e32 v71, v66
	v_fmac_f32_e32 v3, v12, v63
	v_pk_mul_f32 v[58:59], v[16:17], v[70:71]
	v_fmac_f32_e32 v3, v14, v64
	v_mov_b32_e32 v68, v67
	v_add_f32_e32 v3, v3, v58
	s_waitcnt lgkmcnt(0)
	v_pk_mul_f32 v[66:67], v[36:37], v[68:69]
	v_add_f32_e32 v3, v3, v59
	v_add_f32_e32 v3, v3, v66
	v_add_f32_e32 v3, v3, v67
	ds_read2_b32 v[58:59], v7 offset0:192 offset1:196
	ds_read2_b32 v[60:61], v7 offset0:200 offset1:204
	ds_read2_b32 v[62:63], v7 offset0:208 offset1:212
	ds_read2_b32 v[64:65], v7 offset0:216 offset1:220
	ds_read2_b32 v[66:67], v7 offset0:224 offset1:228
	ds_read_b32 v69, v56 offset:28576
	s_nop 1
	v_add_f32_dpp v3, v3, v3 quad_perm:[1,0,3,2] row_mask:0xf bank_mask:0xf
	s_nop 1
	v_add_f32_dpp v3, v3, v3 quad_perm:[2,3,0,1] row_mask:0xf bank_mask:0xf
	v_sub_f32_e32 v3, 0, v3
	v_cndmask_b32_e64 v37, v37, v3, s[44:45]
	s_waitcnt lgkmcnt(5)
	v_fma_f32 v3, v58, v2, 0
	v_fmac_f32_e32 v3, v4, v59
	s_waitcnt lgkmcnt(4)
	v_fmac_f32_e32 v3, v6, v60
	v_fmac_f32_e32 v3, v8, v61
	s_waitcnt lgkmcnt(3)
	v_fmac_f32_e32 v3, v10, v62
	v_mov_b32_e32 v17, v34
	s_waitcnt lgkmcnt(2)
	v_mov_b32_e32 v70, v65
	s_waitcnt lgkmcnt(1)
	v_mov_b32_e32 v71, v66
	v_fmac_f32_e32 v3, v12, v63
	v_pk_mul_f32 v[58:59], v[16:17], v[70:71]
	v_fmac_f32_e32 v3, v14, v64
	v_mov_b32_e32 v68, v67
	v_add_f32_e32 v3, v3, v58
	s_waitcnt lgkmcnt(0)
	v_pk_mul_f32 v[66:67], v[36:37], v[68:69]
	v_add_f32_e32 v3, v3, v59
	v_add_f32_e32 v3, v3, v66
	v_add_f32_e32 v3, v3, v67
	v_add_u32_e32 v7, 0x7000, v56
	s_waitcnt lgkmcnt(0)
	ds_read2_b32 v[58:59], v7 offset1:4
	ds_read2_b32 v[60:61], v7 offset0:8 offset1:12
	ds_read2_b32 v[62:63], v7 offset0:16 offset1:20
	ds_read2_b32 v[64:65], v7 offset0:24 offset1:28
	ds_read2_b32 v[66:67], v7 offset0:32 offset1:36
	ds_read_b32 v69, v56 offset:28832
	s_nop 1
	v_add_f32_dpp v3, v3, v3 quad_perm:[1,0,3,2] row_mask:0xf bank_mask:0xf
	s_nop 1
	v_add_f32_dpp v3, v3, v3 quad_perm:[2,3,0,1] row_mask:0xf bank_mask:0xf
	v_sub_f32_e32 v3, 0, v3
	v_cndmask_b32_e32 v38, v37, v3, vcc
	s_waitcnt lgkmcnt(5)
	v_fma_f32 v3, v58, v2, 0
	v_fmac_f32_e32 v3, v4, v59
	s_waitcnt lgkmcnt(4)
	v_fmac_f32_e32 v3, v6, v60
	v_fmac_f32_e32 v3, v8, v61
	s_waitcnt lgkmcnt(3)
	v_fmac_f32_e32 v3, v10, v62
	v_mov_b32_e32 v17, v34
	s_waitcnt lgkmcnt(2)
	v_mov_b32_e32 v70, v65
	s_waitcnt lgkmcnt(1)
; template <int W> __device__ __forceinline__ void dn_solve(const LAS float* Mf, float (&t)[16], int lane) {
;     const int j = 16 * W + (lane >> 2), q = lane & 3;
; #pragma unroll
;     for (int s = 0; s < 16; ++s) t[s] = 0.f;
; #pragma unroll
;     for (int i = 16 * W; i < 64; ++i) {
;         float acc = 0.f;
; #pragma unroll
;         for (int s = 4 * W; s <= (i - 1) / 4 && i > 16 * W; ++s) acc += Mf[i * 64 + 4 * s + q] * t[s];
;         acc += __shfl_xor(acc, 1); acc += __shfl_xor(acc, 2);
;         const float val = (i == j ? 1.f : 0.f) - acc;
;         if (q == (i & 3)) t[i >> 2] = val;
;         asm volatile("" : "+v"(t[0]), "+v"(t[1]), "+v"(t[2]), "+v"(t[3]), "+v"(t[4]), "+v"(t[5]), "+v"(t[6]), "+v"(t[7]), "+v"(t[8]), "+v"(t[9]), "+v"(t[10]), "+v"(t[11]), "+v"(t[12]), "+v"(t[13]), "+v"(t[14]), "+v"(t[15]));
	v_mov_b32_e32 v71, v66
	v_fmac_f32_e32 v3, v12, v63
	v_pk_mul_f32 v[58:59], v[16:17], v[70:71]
	v_fmac_f32_e32 v3, v14, v64
	v_mov_b32_e32 v37, v38
	v_mov_b32_e32 v68, v67
	v_add_f32_e32 v3, v3, v58
	s_waitcnt lgkmcnt(0)
	v_pk_mul_f32 v[66:67], v[36:37], v[68:69]
	v_add_f32_e32 v3, v3, v59
	v_add_f32_e32 v3, v3, v66
	v_add_f32_e32 v3, v3, v67
	ds_read2_b32 v[58:59], v7 offset0:64 offset1:68
	ds_read2_b32 v[60:61], v7 offset0:72 offset1:76
	ds_read2_b32 v[62:63], v7 offset0:80 offset1:84
	ds_read2_b32 v[64:65], v7 offset0:96 offset1:100
	ds_read2_b32 v[66:67], v7 offset0:104 offset1:108
	ds_read2_b32 v[68:69], v7 offset0:88 offset1:92
	s_nop 1
	v_add_f32_dpp v3, v3, v3 quad_perm:[1,0,3,2] row_mask:0xf bank_mask:0xf
	s_nop 1
	v_add_f32_dpp v3, v3, v3 quad_perm:[2,3,0,1] row_mask:0xf bank_mask:0xf
	v_sub_f32_e32 v3, 0, v3
	v_cndmask_b32_e64 v39, v39, v3, s[42:43]
	s_waitcnt lgkmcnt(5)
	v_fma_f32 v3, v58, v2, 0
	v_fmac_f32_e32 v3, v4, v59
	s_waitcnt lgkmcnt(4)
	v_fmac_f32_e32 v3, v6, v60
	v_fmac_f32_e32 v3, v8, v61
	s_waitcnt lgkmcnt(3)
	v_fmac_f32_e32 v3, v10, v62
	v_fmac_f32_e32 v3, v12, v63
	v_mov_b32_e32 v35, v36
	s_waitcnt lgkmcnt(0)
	v_fmac_f32_e32 v3, v14, v68
	v_pk_mul_f32 v[64:65], v[34:35], v[64:65]
	v_fmac_f32_e32 v3, v16, v69
	v_add_f32_e32 v3, v3, v64
	v_pk_mul_f32 v[66:67], v[38:39], v[66:67]
	v_add_f32_e32 v3, v3, v65
	v_add_f32_e32 v3, v3, v66
	v_add_f32_e32 v3, v3, v67
	ds_read2_b32 v[58:59], v7 offset0:128 offset1:132
	ds_read2_b32 v[60:61], v7 offset0:136 offset1:140
	ds_read2_b32 v[62:63], v7 offset0:144 offset1:148
	ds_read2_b32 v[64:65], v7 offset0:160 offset1:164
	ds_read2_b32 v[66:67], v7 offset0:168 offset1:172
	ds_read2_b32 v[68:69], v7 offset0:152 offset1:156
	s_nop 1
	v_add_f32_dpp v3, v3, v3 quad_perm:[1,0,3,2] row_mask:0xf bank_mask:0xf
	s_nop 1
	v_add_f32_dpp v3, v3, v3 quad_perm:[2,3,0,1] row_mask:0xf bank_mask:0xf
	v_sub_f32_e32 v3, 0, v3
	v_cndmask_b32_e64 v39, v39, v3, s[46:47]
	s_waitcnt lgkmcnt(5)
	v_fma_f32 v3, v58, v2, 0
	v_fmac_f32_e32 v3, v4, v59
	s_waitcnt lgkmcnt(4)
	v_fmac_f32_e32 v3, v6, v60
	v_fmac_f32_e32 v3, v8, v61
	s_waitcnt lgkmcnt(3)
	v_fmac_f32_e32 v3, v10, v62
	v_fmac_f32_e32 v3, v12, v63
	v_mov_b32_e32 v35, v36
	s_waitcnt lgkmcnt(0)
	v_fmac_f32_e32 v3, v14, v68
	v_pk_mul_f32 v[64:65], v[34:35], v[64:65]
	v_fmac_f32_e32 v3, v16, v69
	v_add_f32_e32 v3, v3, v64
	v_pk_mul_f32 v[66:67], v[38:39], v[66:67]
	v_add_f32_e32 v3, v3, v65
	v_add_f32_e32 v3, v3, v66
	v_add_f32_e32 v3, v3, v67
	ds_read2_b32 v[58:59], v7 offset0:192 offset1:196
	ds_read2_b32 v[60:61], v7 offset0:200 offset1:204
	ds_read2_b32 v[62:63], v7 offset0:208 offset1:212
	ds_read2_b32 v[64:65], v7 offset0:224 offset1:228
	ds_read2_b32 v[66:67], v7 offset0:232 offset1:236
	ds_read2_b32 v[68:69], v7 offset0:216 offset1:220
	s_nop 1
	v_add_f32_dpp v3, v3, v3 quad_perm:[1,0,3,2] row_mask:0xf bank_mask:0xf
	s_nop 1
	v_add_f32_dpp v3, v3, v3 quad_perm:[2,3,0,1] row_mask:0xf bank_mask:0xf
	v_sub_f32_e32 v3, 0, v3
	v_cndmask_b32_e64 v39, v39, v3, s[44:45]
	s_waitcnt lgkmcnt(5)
	v_fma_f32 v3, v58, v2, 0
	v_fmac_f32_e32 v3, v4, v59
	s_waitcnt lgkmcnt(4)
	v_fmac_f32_e32 v3, v6, v60
	v_fmac_f32_e32 v3, v8, v61
	s_waitcnt lgkmcnt(3)
	v_fmac_f32_e32 v3, v10, v62
	v_fmac_f32_e32 v3, v12, v63
	v_mov_b32_e32 v35, v36
	s_waitcnt lgkmcnt(0)
	v_fmac_f32_e32 v3, v14, v68
	v_pk_mul_f32 v[64:65], v[34:35], v[64:65]
	v_fmac_f32_e32 v3, v16, v69
	v_add_f32_e32 v3, v3, v64
	v_pk_mul_f32 v[66:67], v[38:39], v[66:67]
	v_add_f32_e32 v3, v3, v65
	v_add_f32_e32 v3, v3, v66
	v_add_f32_e32 v3, v3, v67
	v_add_u32_e32 v7, 0x7400, v56
	s_waitcnt lgkmcnt(0)
	ds_read2_b32 v[58:59], v7 offset1:4
	ds_read2_b32 v[60:61], v7 offset0:8 offset1:12
	ds_read2_b32 v[62:63], v7 offset0:16 offset1:20
	ds_read2_b32 v[64:65], v7 offset0:24 offset1:28
	ds_read2_b32 v[66:67], v7 offset0:32 offset1:36
	ds_read2_b32 v[68:69], v7 offset0:40 offset1:44
	s_nop 1
	v_add_f32_dpp v3, v3, v3 quad_perm:[1,0,3,2] row_mask:0xf bank_mask:0xf
	s_nop 1
	v_add_f32_dpp v3, v3, v3 quad_perm:[2,3,0,1] row_mask:0xf bank_mask:0xf
	v_sub_f32_e32 v3, 0, v3
	v_cndmask_b32_e32 v40, v39, v3, vcc
	s_waitcnt lgkmcnt(5)
	v_fma_f32 v3, v58, v2, 0
	v_fmac_f32_e32 v3, v4, v59
	s_waitcnt lgkmcnt(4)
	v_fmac_f32_e32 v3, v6, v60
	v_fmac_f32_e32 v3, v8, v61
	s_waitcnt lgkmcnt(3)
	v_fmac_f32_e32 v3, v10, v62
	v_fmac_f32_e32 v3, v12, v63
	v_mov_b32_e32 v35, v36
	s_waitcnt lgkmcnt(2)
	v_fmac_f32_e32 v3, v14, v64
	s_waitcnt lgkmcnt(1)
	v_pk_mul_f32 v[66:67], v[34:35], v[66:67]
	v_fmac_f32_e32 v3, v16, v65
	v_mov_b32_e32 v39, v40
	v_add_f32_e32 v3, v3, v66
	s_waitcnt lgkmcnt(0)
	v_pk_mul_f32 v[68:69], v[38:39], v[68:69]
	v_add_f32_e32 v3, v3, v67
	v_add_f32_e32 v3, v3, v68
	v_add_f32_e32 v3, v3, v69
	ds_read2_b32 v[58:59], v7 offset0:64 offset1:68
	ds_read2_b32 v[60:61], v7 offset0:72 offset1:76
	ds_read2_b32 v[62:63], v7 offset0:80 offset1:84
	ds_read2_b32 v[64:65], v7 offset0:88 offset1:92
	ds_read2_b32 v[66:67], v7 offset0:96 offset1:100
	ds_read2_b32 v[68:69], v7 offset0:104 offset1:108
	ds_read_b32 v71, v56 offset:30144
	s_nop 1
	v_add_f32_dpp v3, v3, v3 quad_perm:[1,0,3,2] row_mask:0xf bank_mask:0xf
	s_nop 1
	v_add_f32_dpp v3, v3, v3 quad_perm:[2,3,0,1] row_mask:0xf bank_mask:0xf
	v_sub_f32_e32 v3, 0, v3
	v_cndmask_b32_e64 v41, v41, v3, s[42:43]
	s_waitcnt lgkmcnt(6)
	v_fma_f32 v3, v58, v2, 0
	v_fmac_f32_e32 v3, v4, v59
	s_waitcnt lgkmcnt(5)
	v_fmac_f32_e32 v3, v6, v60
	v_fmac_f32_e32 v3, v8, v61
	s_waitcnt lgkmcnt(4)
	v_fmac_f32_e32 v3, v10, v62
	v_fmac_f32_e32 v3, v12, v63
	s_waitcnt lgkmcnt(3)
	v_fmac_f32_e32 v3, v14, v64
	v_mov_b32_e32 v37, v38
	s_waitcnt lgkmcnt(2)
	v_mov_b32_e32 v72, v67
	s_waitcnt lgkmcnt(1)
; template <int W> __device__ __forceinline__ void dn_solve(const LAS float* Mf, float (&t)[16], int lane) {
;     const int j = 16 * W + (lane >> 2), q = lane & 3;
; #pragma unroll
;     for (int s = 0; s < 16; ++s) t[s] = 0.f;
; #pragma unroll
;     for (int i = 16 * W; i < 64; ++i) {
;         float acc = 0.f;
; #pragma unroll
;         for (int s = 4 * W; s <= (i - 1) / 4 && i > 16 * W; ++s) acc += Mf[i * 64 + 4 * s + q] * t[s];
;         acc += __shfl_xor(acc, 1); acc += __shfl_xor(acc, 2);
;         const float val = (i == j ? 1.f : 0.f) - acc;
;         if (q == (i & 3)) t[i >> 2] = val;
;         asm volatile("" : "+v"(t[0]), "+v"(t[1]), "+v"(t[2]), "+v"(t[3]), "+v"(t[4]), "+v"(t[5]), "+v"(t[6]), "+v"(t[7]), "+v"(t[8]), "+v"(t[9]), "+v"(t[10]), "+v"(t[11]), "+v"(t[12]), "+v"(t[13]), "+v"(t[14]), "+v"(t[15]));
	v_mov_b32_e32 v73, v68
	v_fmac_f32_e32 v3, v16, v65
	v_pk_mul_f32 v[58:59], v[36:37], v[72:73]
	v_fmac_f32_e32 v3, v34, v66
	v_mov_b32_e32 v70, v69
	v_add_f32_e32 v3, v3, v58
	s_waitcnt lgkmcnt(0)
	v_pk_mul_f32 v[68:69], v[40:41], v[70:71]
	v_add_f32_e32 v3, v3, v59
	v_add_f32_e32 v3, v3, v68
	v_add_f32_e32 v3, v3, v69
	ds_read2_b32 v[58:59], v7 offset0:128 offset1:132
	ds_read2_b32 v[60:61], v7 offset0:136 offset1:140
	ds_read2_b32 v[62:63], v7 offset0:144 offset1:148
	ds_read2_b32 v[64:65], v7 offset0:152 offset1:156
	ds_read2_b32 v[66:67], v7 offset0:160 offset1:164
	ds_read2_b32 v[68:69], v7 offset0:168 offset1:172
	ds_read_b32 v71, v56 offset:30400
	s_nop 1
	v_add_f32_dpp v3, v3, v3 quad_perm:[1,0,3,2] row_mask:0xf bank_mask:0xf
	s_nop 1
	v_add_f32_dpp v3, v3, v3 quad_perm:[2,3,0,1] row_mask:0xf bank_mask:0xf
	v_sub_f32_e32 v3, 0, v3
	v_cndmask_b32_e64 v41, v41, v3, s[46:47]
	s_waitcnt lgkmcnt(6)
	v_fma_f32 v3, v58, v2, 0
	v_fmac_f32_e32 v3, v4, v59
	s_waitcnt lgkmcnt(5)
	v_fmac_f32_e32 v3, v6, v60
	v_fmac_f32_e32 v3, v8, v61
	s_waitcnt lgkmcnt(4)
	v_fmac_f32_e32 v3, v10, v62
	v_fmac_f32_e32 v3, v12, v63
	s_waitcnt lgkmcnt(3)
	v_fmac_f32_e32 v3, v14, v64
	v_mov_b32_e32 v37, v38
	s_waitcnt lgkmcnt(2)
	v_mov_b32_e32 v72, v67
	s_waitcnt lgkmcnt(1)
	v_mov_b32_e32 v73, v68
	v_fmac_f32_e32 v3, v16, v65
	v_pk_mul_f32 v[58:59], v[36:37], v[72:73]
	v_fmac_f32_e32 v3, v34, v66
	v_mov_b32_e32 v70, v69
	v_add_f32_e32 v3, v3, v58
	s_waitcnt lgkmcnt(0)
	v_pk_mul_f32 v[68:69], v[40:41], v[70:71]
	v_add_f32_e32 v3, v3, v59
	v_add_f32_e32 v3, v3, v68
	v_add_f32_e32 v3, v3, v69
	ds_read2_b32 v[58:59], v7 offset0:192 offset1:196
	ds_read2_b32 v[60:61], v7 offset0:200 offset1:204
	ds_read2_b32 v[62:63], v7 offset0:208 offset1:212
	ds_read2_b32 v[64:65], v7 offset0:216 offset1:220
	ds_read2_b32 v[66:67], v7 offset0:224 offset1:228
	ds_read2_b32 v[68:69], v7 offset0:232 offset1:236
	ds_read_b32 v71, v56 offset:30656
	s_nop 1
	v_add_f32_dpp v3, v3, v3 quad_perm:[1,0,3,2] row_mask:0xf bank_mask:0xf
	s_nop 1
	v_add_f32_dpp v3, v3, v3 quad_perm:[2,3,0,1] row_mask:0xf bank_mask:0xf
	v_sub_f32_e32 v3, 0, v3
	v_cndmask_b32_e64 v41, v41, v3, s[44:45]
	s_waitcnt lgkmcnt(6)
	v_fma_f32 v3, v58, v2, 0
	v_fmac_f32_e32 v3, v4, v59
	s_waitcnt lgkmcnt(5)
	v_fmac_f32_e32 v3, v6, v60
	v_fmac_f32_e32 v3, v8, v61
	s_waitcnt lgkmcnt(4)
	v_fmac_f32_e32 v3, v10, v62
	v_fmac_f32_e32 v3, v12, v63
	s_waitcnt lgkmcnt(3)
	v_fmac_f32_e32 v3, v14, v64
	v_mov_b32_e32 v37, v38
	s_waitcnt lgkmcnt(2)
	v_mov_b32_e32 v72, v67
	s_waitcnt lgkmcnt(1)
	v_mov_b32_e32 v73, v68
	v_fmac_f32_e32 v3, v16, v65
	v_pk_mul_f32 v[58:59], v[36:37], v[72:73]
	v_fmac_f32_e32 v3, v34, v66
	v_mov_b32_e32 v70, v69
	v_add_f32_e32 v3, v3, v58
	s_waitcnt lgkmcnt(0)
	v_pk_mul_f32 v[68:69], v[40:41], v[70:71]
	v_add_f32_e32 v3, v3, v59
	v_add_f32_e32 v3, v3, v68
	v_add_f32_e32 v3, v3, v69
	v_add_u32_e32 v7, 0x7800, v56
	s_waitcnt lgkmcnt(0)
	ds_read2_b32 v[58:59], v7 offset1:4
	ds_read2_b32 v[60:61], v7 offset0:8 offset1:12
	ds_read2_b32 v[62:63], v7 offset0:16 offset1:20
	ds_read2_b32 v[64:65], v7 offset0:24 offset1:28
	ds_read2_b32 v[66:67], v7 offset0:32 offset1:36
	ds_read2_b32 v[68:69], v7 offset0:40 offset1:44
	ds_read_b32 v71, v56 offset:30912
	s_nop 1
	v_add_f32_dpp v3, v3, v3 quad_perm:[1,0,3,2] row_mask:0xf bank_mask:0xf
	s_nop 1
	v_add_f32_dpp v3, v3, v3 quad_perm:[2,3,0,1] row_mask:0xf bank_mask:0xf
	v_sub_f32_e32 v3, 0, v3
	v_cndmask_b32_e32 v42, v41, v3, vcc
	s_waitcnt lgkmcnt(6)
	v_fma_f32 v3, v58, v2, 0
	v_fmac_f32_e32 v3, v4, v59
	s_waitcnt lgkmcnt(5)
	v_fmac_f32_e32 v3, v6, v60
	v_fmac_f32_e32 v3, v8, v61
	s_waitcnt lgkmcnt(4)
	v_fmac_f32_e32 v3, v10, v62
	v_fmac_f32_e32 v3, v12, v63
	s_waitcnt lgkmcnt(3)
	v_fmac_f32_e32 v3, v14, v64
	v_mov_b32_e32 v37, v38
	s_waitcnt lgkmcnt(2)
	v_mov_b32_e32 v72, v67
	s_waitcnt lgkmcnt(1)
	v_mov_b32_e32 v73, v68
	v_fmac_f32_e32 v3, v16, v65
	v_pk_mul_f32 v[58:59], v[36:37], v[72:73]
	v_fmac_f32_e32 v3, v34, v66
	v_mov_b32_e32 v41, v42
	v_mov_b32_e32 v70, v69
	v_add_f32_e32 v3, v3, v58
	s_waitcnt lgkmcnt(0)
	v_pk_mul_f32 v[68:69], v[40:41], v[70:71]
	v_add_f32_e32 v3, v3, v59
	v_add_f32_e32 v3, v3, v68
	v_add_f32_e32 v3, v3, v69
	ds_read2_b32 v[58:59], v7 offset0:64 offset1:68
	ds_read2_b32 v[60:61], v7 offset0:72 offset1:76
	ds_read2_b32 v[62:63], v7 offset0:80 offset1:84
	ds_read2_b32 v[64:65], v7 offset0:88 offset1:92
	ds_read2_b32 v[66:67], v7 offset0:104 offset1:108
	ds_read2_b32 v[68:69], v7 offset0:112 offset1:116
	ds_read2_b32 v[70:71], v7 offset0:96 offset1:100
	s_nop 1
	v_add_f32_dpp v3, v3, v3 quad_perm:[1,0,3,2] row_mask:0xf bank_mask:0xf
	s_nop 1
	v_add_f32_dpp v3, v3, v3 quad_perm:[2,3,0,1] row_mask:0xf bank_mask:0xf
	v_sub_f32_e32 v3, 0, v3
	v_cndmask_b32_e64 v43, v43, v3, s[42:43]
	s_waitcnt lgkmcnt(6)
	v_fma_f32 v3, v58, v2, 0
	v_fmac_f32_e32 v3, v4, v59
	s_waitcnt lgkmcnt(5)
	v_fmac_f32_e32 v3, v6, v60
	v_fmac_f32_e32 v3, v8, v61
	s_waitcnt lgkmcnt(4)
	v_fmac_f32_e32 v3, v10, v62
	v_fmac_f32_e32 v3, v12, v63
	s_waitcnt lgkmcnt(3)
	v_fmac_f32_e32 v3, v14, v64
	v_fmac_f32_e32 v3, v16, v65
	v_mov_b32_e32 v39, v40
	s_waitcnt lgkmcnt(0)
	v_fmac_f32_e32 v3, v34, v70
	v_pk_mul_f32 v[66:67], v[38:39], v[66:67]
	v_fmac_f32_e32 v3, v36, v71
	v_add_f32_e32 v3, v3, v66
	v_pk_mul_f32 v[68:69], v[42:43], v[68:69]
	v_add_f32_e32 v3, v3, v67
	v_add_f32_e32 v3, v3, v68
	v_add_f32_e32 v3, v3, v69
	ds_read2_b32 v[58:59], v7 offset0:128 offset1:132
	ds_read2_b32 v[60:61], v7 offset0:136 offset1:140
	ds_read2_b32 v[62:63], v7 offset0:144 offset1:148
	ds_read2_b32 v[64:65], v7 offset0:152 offset1:156
	ds_read2_b32 v[66:67], v7 offset0:168 offset1:172
	ds_read2_b32 v[68:69], v7 offset0:176 offset1:180
	ds_read2_b32 v[70:71], v7 offset0:160 offset1:164
	s_nop 1
	v_add_f32_dpp v3, v3, v3 quad_perm:[1,0,3,2] row_mask:0xf bank_mask:0xf
	s_nop 1
	v_add_f32_dpp v3, v3, v3 quad_perm:[2,3,0,1] row_mask:0xf bank_mask:0xf
	v_sub_f32_e32 v3, 0, v3
	v_cndmask_b32_e64 v43, v43, v3, s[46:47]
	s_waitcnt lgkmcnt(6)
; template <int W> __device__ __forceinline__ void dn_solve(const LAS float* Mf, float (&t)[16], int lane) {
;     const int j = 16 * W + (lane >> 2), q = lane & 3;
; #pragma unroll
;     for (int s = 0; s < 16; ++s) t[s] = 0.f;
; #pragma unroll
;     for (int i = 16 * W; i < 64; ++i) {
;         float acc = 0.f;
; #pragma unroll
;         for (int s = 4 * W; s <= (i - 1) / 4 && i > 16 * W; ++s) acc += Mf[i * 64 + 4 * s + q] * t[s];
;         acc += __shfl_xor(acc, 1); acc += __shfl_xor(acc, 2);
;         const float val = (i == j ? 1.f : 0.f) - acc;
;         if (q == (i & 3)) t[i >> 2] = val;
;         asm volatile("" : "+v"(t[0]), "+v"(t[1]), "+v"(t[2]), "+v"(t[3]), "+v"(t[4]), "+v"(t[5]), "+v"(t[6]), "+v"(t[7]), "+v"(t[8]), "+v"(t[9]), "+v"(t[10]), "+v"(t[11]), "+v"(t[12]), "+v"(t[13]), "+v"(t[14]), "+v"(t[15]));
	v_fma_f32 v3, v58, v2, 0
	v_fmac_f32_e32 v3, v4, v59
	s_waitcnt lgkmcnt(5)
	v_fmac_f32_e32 v3, v6, v60
	v_fmac_f32_e32 v3, v8, v61
	s_waitcnt lgkmcnt(4)
	v_fmac_f32_e32 v3, v10, v62
	v_fmac_f32_e32 v3, v12, v63
	s_waitcnt lgkmcnt(3)
	v_fmac_f32_e32 v3, v14, v64
	v_fmac_f32_e32 v3, v16, v65
	v_mov_b32_e32 v39, v40
	s_waitcnt lgkmcnt(0)
	v_fmac_f32_e32 v3, v34, v70
	v_pk_mul_f32 v[66:67], v[38:39], v[66:67]
	v_fmac_f32_e32 v3, v36, v71
	v_add_f32_e32 v3, v3, v66
	v_pk_mul_f32 v[68:69], v[42:43], v[68:69]
	v_add_f32_e32 v3, v3, v67
	v_add_f32_e32 v3, v3, v68
	v_add_f32_e32 v3, v3, v69
	ds_read2_b32 v[58:59], v7 offset0:192 offset1:196
	ds_read2_b32 v[60:61], v7 offset0:200 offset1:204
	ds_read2_b32 v[62:63], v7 offset0:208 offset1:212
	ds_read2_b32 v[64:65], v7 offset0:216 offset1:220
	ds_read2_b32 v[66:67], v7 offset0:232 offset1:236
	ds_read2_b32 v[68:69], v7 offset0:240 offset1:244
	ds_read2_b32 v[70:71], v7 offset0:224 offset1:228
	s_nop 1
	v_add_f32_dpp v3, v3, v3 quad_perm:[1,0,3,2] row_mask:0xf bank_mask:0xf
	s_nop 1
	v_add_f32_dpp v3, v3, v3 quad_perm:[2,3,0,1] row_mask:0xf bank_mask:0xf
	v_sub_f32_e32 v3, 0, v3
	v_cndmask_b32_e64 v43, v43, v3, s[44:45]
	s_waitcnt lgkmcnt(6)
	v_fma_f32 v3, v58, v2, 0
	v_fmac_f32_e32 v3, v4, v59
	s_waitcnt lgkmcnt(5)
	v_fmac_f32_e32 v3, v6, v60
	v_fmac_f32_e32 v3, v8, v61
	s_waitcnt lgkmcnt(4)
	v_fmac_f32_e32 v3, v10, v62
	v_fmac_f32_e32 v3, v12, v63
	s_waitcnt lgkmcnt(3)
	v_fmac_f32_e32 v3, v14, v64
	v_fmac_f32_e32 v3, v16, v65
	v_mov_b32_e32 v39, v40
	s_waitcnt lgkmcnt(0)
	v_fmac_f32_e32 v3, v34, v70
	v_pk_mul_f32 v[66:67], v[38:39], v[66:67]
	v_fmac_f32_e32 v3, v36, v71
	v_add_f32_e32 v3, v3, v66
	v_pk_mul_f32 v[68:69], v[42:43], v[68:69]
	v_add_f32_e32 v3, v3, v67
	v_add_f32_e32 v3, v3, v68
	v_add_f32_e32 v3, v3, v69
	v_add_u32_e32 v7, 0x7c00, v56
	s_waitcnt lgkmcnt(0)
	ds_read2_b32 v[58:59], v7 offset1:4
	ds_read2_b32 v[60:61], v7 offset0:8 offset1:12
	ds_read2_b32 v[62:63], v7 offset0:16 offset1:20
	ds_read2_b32 v[64:65], v7 offset0:24 offset1:28
	ds_read2_b32 v[66:67], v7 offset0:32 offset1:36
	ds_read2_b32 v[68:69], v7 offset0:40 offset1:44
	ds_read2_b32 v[70:71], v7 offset0:48 offset1:52
	s_nop 1
	v_add_f32_dpp v3, v3, v3 quad_perm:[1,0,3,2] row_mask:0xf bank_mask:0xf
	s_nop 1
	v_add_f32_dpp v3, v3, v3 quad_perm:[2,3,0,1] row_mask:0xf bank_mask:0xf
	v_sub_f32_e32 v3, 0, v3
	v_cndmask_b32_e32 v44, v43, v3, vcc
	s_waitcnt lgkmcnt(6)
	v_fma_f32 v3, v58, v2, 0
	v_fmac_f32_e32 v3, v4, v59
	s_waitcnt lgkmcnt(5)
	v_fmac_f32_e32 v3, v6, v60
	v_fmac_f32_e32 v3, v8, v61
	s_waitcnt lgkmcnt(4)
	v_fmac_f32_e32 v3, v10, v62
	v_fmac_f32_e32 v3, v12, v63
	s_waitcnt lgkmcnt(3)
	v_fmac_f32_e32 v3, v14, v64
	v_fmac_f32_e32 v3, v16, v65
	v_mov_b32_e32 v39, v40
	s_waitcnt lgkmcnt(2)
	v_fmac_f32_e32 v3, v34, v66
	s_waitcnt lgkmcnt(1)
	v_pk_mul_f32 v[68:69], v[38:39], v[68:69]
	v_fmac_f32_e32 v3, v36, v67
	v_mov_b32_e32 v43, v44
	v_add_f32_e32 v3, v3, v68
	s_waitcnt lgkmcnt(0)
	v_pk_mul_f32 v[70:71], v[42:43], v[70:71]
	v_add_f32_e32 v3, v3, v69
	v_add_f32_e32 v3, v3, v70
	v_add_f32_e32 v3, v3, v71
	ds_read2_b32 v[58:59], v7 offset0:64 offset1:68
	ds_read2_b32 v[60:61], v7 offset0:72 offset1:76
	ds_read2_b32 v[62:63], v7 offset0:80 offset1:84
	ds_read2_b32 v[64:65], v7 offset0:88 offset1:92
	ds_read2_b32 v[66:67], v7 offset0:96 offset1:100
	ds_read2_b32 v[68:69], v7 offset0:104 offset1:108
	ds_read2_b32 v[70:71], v7 offset0:112 offset1:116
	ds_read_b32 v73, v56 offset:32224
	s_nop 1
	v_add_f32_dpp v3, v3, v3 quad_perm:[1,0,3,2] row_mask:0xf bank_mask:0xf
	s_nop 1
	v_add_f32_dpp v3, v3, v3 quad_perm:[2,3,0,1] row_mask:0xf bank_mask:0xf
	v_sub_f32_e32 v3, 0, v3
	v_cndmask_b32_e64 v45, v45, v3, s[42:43]
	s_waitcnt lgkmcnt(7)
	v_fma_f32 v3, v58, v2, 0
	v_fmac_f32_e32 v3, v4, v59
	s_waitcnt lgkmcnt(6)
	v_fmac_f32_e32 v3, v6, v60
	v_fmac_f32_e32 v3, v8, v61
	s_waitcnt lgkmcnt(5)
	v_fmac_f32_e32 v3, v10, v62
	v_fmac_f32_e32 v3, v12, v63
	s_waitcnt lgkmcnt(4)
	v_fmac_f32_e32 v3, v14, v64
	v_fmac_f32_e32 v3, v16, v65
	s_waitcnt lgkmcnt(3)
	v_fmac_f32_e32 v3, v34, v66
	v_mov_b32_e32 v41, v42
	s_waitcnt lgkmcnt(2)
	v_mov_b32_e32 v74, v69
	s_waitcnt lgkmcnt(1)
	v_mov_b32_e32 v75, v70
	v_fmac_f32_e32 v3, v36, v67
	v_pk_mul_f32 v[58:59], v[40:41], v[74:75]
	v_fmac_f32_e32 v3, v38, v68
	v_mov_b32_e32 v72, v71
	v_add_f32_e32 v3, v3, v58
	s_waitcnt lgkmcnt(0)
	v_pk_mul_f32 v[70:71], v[44:45], v[72:73]
	v_add_f32_e32 v3, v3, v59
	v_add_f32_e32 v3, v3, v70
	v_add_f32_e32 v3, v3, v71
	ds_read2_b32 v[58:59], v7 offset0:128 offset1:132
	ds_read2_b32 v[60:61], v7 offset0:136 offset1:140
	ds_read2_b32 v[62:63], v7 offset0:144 offset1:148
	ds_read2_b32 v[64:65], v7 offset0:152 offset1:156
	ds_read2_b32 v[66:67], v7 offset0:160 offset1:164
	ds_read2_b32 v[68:69], v7 offset0:168 offset1:172
	ds_read2_b32 v[70:71], v7 offset0:176 offset1:180
	ds_read_b32 v73, v56 offset:32480
	s_nop 1
	v_add_f32_dpp v3, v3, v3 quad_perm:[1,0,3,2] row_mask:0xf bank_mask:0xf
	s_nop 1
	v_add_f32_dpp v3, v3, v3 quad_perm:[2,3,0,1] row_mask:0xf bank_mask:0xf
	v_sub_f32_e32 v3, 0, v3
	v_cndmask_b32_e64 v45, v45, v3, s[46:47]
	s_waitcnt lgkmcnt(7)
	v_fma_f32 v3, v58, v2, 0
	v_fmac_f32_e32 v3, v4, v59
	s_waitcnt lgkmcnt(6)
	v_fmac_f32_e32 v3, v6, v60
	v_fmac_f32_e32 v3, v8, v61
	s_waitcnt lgkmcnt(5)
	v_fmac_f32_e32 v3, v10, v62
	v_fmac_f32_e32 v3, v12, v63
	s_waitcnt lgkmcnt(4)
	v_fmac_f32_e32 v3, v14, v64
	v_fmac_f32_e32 v3, v16, v65
	s_waitcnt lgkmcnt(3)
	v_fmac_f32_e32 v3, v34, v66
	v_mov_b32_e32 v41, v42
	s_waitcnt lgkmcnt(2)
	v_mov_b32_e32 v74, v69
	s_waitcnt lgkmcnt(1)
; template <int W> __device__ __forceinline__ void dn_solve(const LAS float* Mf, float (&t)[16], int lane) {
;     const int j = 16 * W + (lane >> 2), q = lane & 3;
; #pragma unroll
;     for (int s = 0; s < 16; ++s) t[s] = 0.f;
; #pragma unroll
;     for (int i = 16 * W; i < 64; ++i) {
;         float acc = 0.f;
; #pragma unroll
;         for (int s = 4 * W; s <= (i - 1) / 4 && i > 16 * W; ++s) acc += Mf[i * 64 + 4 * s + q] * t[s];
;         acc += __shfl_xor(acc, 1); acc += __shfl_xor(acc, 2);
;         const float val = (i == j ? 1.f : 0.f) - acc;
;         if (q == (i & 3)) t[i >> 2] = val;
;         asm volatile("" : "+v"(t[0]), "+v"(t[1]), "+v"(t[2]), "+v"(t[3]), "+v"(t[4]), "+v"(t[5]), "+v"(t[6]), "+v"(t[7]), "+v"(t[8]), "+v"(t[9]), "+v"(t[10]), "+v"(t[11]), "+v"(t[12]), "+v"(t[13]), "+v"(t[14]), "+v"(t[15]));
	v_mov_b32_e32 v75, v70
	v_fmac_f32_e32 v3, v36, v67
	v_pk_mul_f32 v[58:59], v[40:41], v[74:75]
	v_fmac_f32_e32 v3, v38, v68
	v_mov_b32_e32 v72, v71
	v_add_f32_e32 v3, v3, v58
	s_waitcnt lgkmcnt(0)
	v_pk_mul_f32 v[70:71], v[44:45], v[72:73]
	v_add_f32_e32 v3, v3, v59
	v_add_f32_e32 v3, v3, v70
	v_add_f32_e32 v3, v3, v71
	ds_read2_b32 v[58:59], v7 offset0:192 offset1:196
	ds_read2_b32 v[60:61], v7 offset0:200 offset1:204
	ds_read2_b32 v[62:63], v7 offset0:208 offset1:212
	ds_read2_b32 v[64:65], v7 offset0:216 offset1:220
	ds_read2_b32 v[66:67], v7 offset0:224 offset1:228
	ds_read2_b32 v[68:69], v7 offset0:232 offset1:236
	ds_read2_b32 v[70:71], v7 offset0:240 offset1:244
	ds_read_b32 v73, v56 offset:32736
	s_nop 1
	v_add_f32_dpp v3, v3, v3 quad_perm:[1,0,3,2] row_mask:0xf bank_mask:0xf
	s_nop 1
	v_add_f32_dpp v3, v3, v3 quad_perm:[2,3,0,1] row_mask:0xf bank_mask:0xf
	v_sub_f32_e32 v3, 0, v3
	v_cndmask_b32_e64 v45, v45, v3, s[44:45]
	s_waitcnt lgkmcnt(7)
	v_fma_f32 v3, v58, v2, 0
	v_fmac_f32_e32 v3, v4, v59
	s_waitcnt lgkmcnt(6)
	v_fmac_f32_e32 v3, v6, v60
	v_fmac_f32_e32 v3, v8, v61
	s_waitcnt lgkmcnt(5)
	v_fmac_f32_e32 v3, v10, v62
	v_fmac_f32_e32 v3, v12, v63
	s_waitcnt lgkmcnt(4)
	v_fmac_f32_e32 v3, v14, v64
	v_fmac_f32_e32 v3, v16, v65
	s_waitcnt lgkmcnt(3)
	v_fmac_f32_e32 v3, v34, v66
	v_mov_b32_e32 v41, v42
	s_waitcnt lgkmcnt(2)
	v_mov_b32_e32 v74, v69
	s_waitcnt lgkmcnt(1)
	v_mov_b32_e32 v75, v70
	v_fmac_f32_e32 v3, v36, v67
	v_pk_mul_f32 v[58:59], v[40:41], v[74:75]
	v_fmac_f32_e32 v3, v38, v68
	v_mov_b32_e32 v72, v71
	v_add_f32_e32 v3, v3, v58
	s_waitcnt lgkmcnt(0)
	v_pk_mul_f32 v[70:71], v[44:45], v[72:73]
	v_add_f32_e32 v3, v3, v59
	v_add_f32_e32 v3, v3, v70
	v_add_f32_e32 v3, v3, v71
	v_add_u32_e32 v7, 0x8000, v56
	s_waitcnt lgkmcnt(0)
	ds_read2_b32 v[58:59], v7 offset1:4
	ds_read2_b32 v[60:61], v7 offset0:8 offset1:12
	ds_read2_b32 v[62:63], v7 offset0:16 offset1:20
	ds_read2_b32 v[64:65], v7 offset0:24 offset1:28
	ds_read2_b32 v[66:67], v7 offset0:32 offset1:36
	ds_read2_b32 v[68:69], v7 offset0:40 offset1:44
	ds_read2_b32 v[70:71], v7 offset0:48 offset1:52
	ds_read_b32 v73, v56 offset:32992
	s_nop 1
	v_add_f32_dpp v3, v3, v3 quad_perm:[1,0,3,2] row_mask:0xf bank_mask:0xf
	s_nop 1
	v_add_f32_dpp v3, v3, v3 quad_perm:[2,3,0,1] row_mask:0xf bank_mask:0xf
	v_sub_f32_e32 v3, 0, v3
	v_cndmask_b32_e32 v46, v45, v3, vcc
	s_waitcnt lgkmcnt(7)
	v_fma_f32 v3, v58, v2, 0
	v_fmac_f32_e32 v3, v4, v59
	s_waitcnt lgkmcnt(6)
	v_fmac_f32_e32 v3, v6, v60
	v_fmac_f32_e32 v3, v8, v61
	s_waitcnt lgkmcnt(5)
	v_fmac_f32_e32 v3, v10, v62
	v_fmac_f32_e32 v3, v12, v63
	s_waitcnt lgkmcnt(4)
	v_fmac_f32_e32 v3, v14, v64
	v_fmac_f32_e32 v3, v16, v65
	s_waitcnt lgkmcnt(3)
	v_fmac_f32_e32 v3, v34, v66
	v_mov_b32_e32 v41, v42
	s_waitcnt lgkmcnt(2)
	v_mov_b32_e32 v74, v69
	s_waitcnt lgkmcnt(1)
	v_mov_b32_e32 v75, v70
	v_fmac_f32_e32 v3, v36, v67
	v_pk_mul_f32 v[58:59], v[40:41], v[74:75]
	v_fmac_f32_e32 v3, v38, v68
	v_mov_b32_e32 v45, v46
	v_mov_b32_e32 v72, v71
	v_add_f32_e32 v3, v3, v58
	s_waitcnt lgkmcnt(0)
	v_pk_mul_f32 v[70:71], v[44:45], v[72:73]
	v_add_f32_e32 v3, v3, v59
	v_add_f32_e32 v3, v3, v70
	v_add_f32_e32 v3, v3, v71
	ds_read2_b32 v[58:59], v7 offset0:64 offset1:68
	ds_read2_b32 v[60:61], v7 offset0:72 offset1:76
	ds_read2_b32 v[62:63], v7 offset0:80 offset1:84
	ds_read2_b32 v[64:65], v7 offset0:88 offset1:92
	ds_read2_b32 v[66:67], v7 offset0:96 offset1:100
	ds_read2_b32 v[68:69], v7 offset0:112 offset1:116
	ds_read2_b32 v[70:71], v7 offset0:120 offset1:124
	ds_read2_b32 v[72:73], v7 offset0:104 offset1:108
	s_nop 1
	v_add_f32_dpp v3, v3, v3 quad_perm:[1,0,3,2] row_mask:0xf bank_mask:0xf
	s_nop 1
	v_add_f32_dpp v3, v3, v3 quad_perm:[2,3,0,1] row_mask:0xf bank_mask:0xf
	v_sub_f32_e32 v3, 0, v3
	v_cndmask_b32_e64 v47, v47, v3, s[42:43]
	s_waitcnt lgkmcnt(7)
	v_fma_f32 v3, v58, v2, 0
	v_fmac_f32_e32 v3, v4, v59
	s_waitcnt lgkmcnt(6)
	v_fmac_f32_e32 v3, v6, v60
	v_fmac_f32_e32 v3, v8, v61
	s_waitcnt lgkmcnt(5)
	v_fmac_f32_e32 v3, v10, v62
	v_fmac_f32_e32 v3, v12, v63
	s_waitcnt lgkmcnt(4)
	v_fmac_f32_e32 v3, v14, v64
	v_fmac_f32_e32 v3, v16, v65
	s_waitcnt lgkmcnt(3)
	v_fmac_f32_e32 v3, v34, v66
	v_fmac_f32_e32 v3, v36, v67
	v_mov_b32_e32 v43, v44
	s_waitcnt lgkmcnt(0)
	v_fmac_f32_e32 v3, v38, v72
	v_pk_mul_f32 v[68:69], v[42:43], v[68:69]
	v_fmac_f32_e32 v3, v40, v73
	v_add_f32_e32 v3, v3, v68
	v_pk_mul_f32 v[70:71], v[46:47], v[70:71]
	v_add_f32_e32 v3, v3, v69
	v_add_f32_e32 v3, v3, v70
	v_add_f32_e32 v3, v3, v71
	ds_read2_b32 v[58:59], v7 offset0:128 offset1:132
	ds_read2_b32 v[60:61], v7 offset0:136 offset1:140
	ds_read2_b32 v[62:63], v7 offset0:144 offset1:148
	ds_read2_b32 v[64:65], v7 offset0:152 offset1:156
	ds_read2_b32 v[66:67], v7 offset0:160 offset1:164
	ds_read2_b32 v[68:69], v7 offset0:176 offset1:180
	ds_read2_b32 v[70:71], v7 offset0:184 offset1:188
	ds_read2_b32 v[72:73], v7 offset0:168 offset1:172
	s_nop 1
	v_add_f32_dpp v3, v3, v3 quad_perm:[1,0,3,2] row_mask:0xf bank_mask:0xf
	s_nop 1
	v_add_f32_dpp v3, v3, v3 quad_perm:[2,3,0,1] row_mask:0xf bank_mask:0xf
	v_sub_f32_e32 v3, 0, v3
	v_cndmask_b32_e64 v47, v47, v3, s[46:47]
	s_waitcnt lgkmcnt(7)
	v_fma_f32 v3, v58, v2, 0
	v_fmac_f32_e32 v3, v4, v59
	s_waitcnt lgkmcnt(6)
	v_fmac_f32_e32 v3, v6, v60
	v_fmac_f32_e32 v3, v8, v61
	s_waitcnt lgkmcnt(5)
	v_fmac_f32_e32 v3, v10, v62
	v_fmac_f32_e32 v3, v12, v63
	s_waitcnt lgkmcnt(4)
	v_fmac_f32_e32 v3, v14, v64
	v_fmac_f32_e32 v3, v16, v65
	s_waitcnt lgkmcnt(3)
	v_fmac_f32_e32 v3, v34, v66
	v_fmac_f32_e32 v3, v36, v67
	v_mov_b32_e32 v43, v44
	s_waitcnt lgkmcnt(0)
; template <int W> __device__ __forceinline__ void dn_solve(const LAS float* Mf, float (&t)[16], int lane) {
;     const int j = 16 * W + (lane >> 2), q = lane & 3;
; #pragma unroll
;     for (int s = 0; s < 16; ++s) t[s] = 0.f;
; #pragma unroll
;     for (int i = 16 * W; i < 64; ++i) {
;         float acc = 0.f;
; #pragma unroll
;         for (int s = 4 * W; s <= (i - 1) / 4 && i > 16 * W; ++s) acc += Mf[i * 64 + 4 * s + q] * t[s];
;         acc += __shfl_xor(acc, 1); acc += __shfl_xor(acc, 2);
;         const float val = (i == j ? 1.f : 0.f) - acc;
;         if (q == (i & 3)) t[i >> 2] = val;
;         asm volatile("" : "+v"(t[0]), "+v"(t[1]), "+v"(t[2]), "+v"(t[3]), "+v"(t[4]), "+v"(t[5]), "+v"(t[6]), "+v"(t[7]), "+v"(t[8]), "+v"(t[9]), "+v"(t[10]), "+v"(t[11]), "+v"(t[12]), "+v"(t[13]), "+v"(t[14]), "+v"(t[15]));
; __device__ __forceinline__ void dn_t_phase(LAS unsigned char* lds, const bf16_t* P, float* AB, bf16_t* TP, const float* a_log, const float* dt_bias, int G) {
;     ...
;         if (w == 0) dn_solve<0>(Mf, tc, lane); else if (w == 1) dn_solve<1>(Mf, tc, lane); else if (w == 2) dn_solve<2>(Mf, tc, lane); else dn_solve<3>(Mf, tc, lane);
	v_fmac_f32_e32 v3, v38, v72
	v_pk_mul_f32 v[68:69], v[42:43], v[68:69]
	v_fmac_f32_e32 v3, v40, v73
	v_add_f32_e32 v3, v3, v68
	v_pk_mul_f32 v[70:71], v[46:47], v[70:71]
	v_add_f32_e32 v3, v3, v69
	v_add_f32_e32 v3, v3, v70
	v_add_f32_e32 v3, v3, v71
	ds_read2_b32 v[58:59], v7 offset0:192 offset1:196
	ds_read2_b32 v[60:61], v7 offset0:200 offset1:204
	ds_read2_b32 v[62:63], v7 offset0:208 offset1:212
	ds_read2_b32 v[64:65], v7 offset0:216 offset1:220
	ds_read2_b32 v[66:67], v7 offset0:224 offset1:228
	ds_read2_b32 v[68:69], v7 offset0:232 offset1:236
	ds_read2_b32 v[70:71], v7 offset0:240 offset1:244
	ds_read2_b32 v[72:73], v7 offset0:248 offset1:252
	s_nop 1
	v_add_f32_dpp v3, v3, v3 quad_perm:[1,0,3,2] row_mask:0xf bank_mask:0xf
	s_nop 1
	v_add_f32_dpp v3, v3, v3 quad_perm:[2,3,0,1] row_mask:0xf bank_mask:0xf
	v_sub_f32_e32 v3, 0, v3
	v_cndmask_b32_e64 v47, v47, v3, s[44:45]
	s_waitcnt lgkmcnt(7)
	v_fma_f32 v3, v58, v2, 0
	v_fmac_f32_e32 v3, v4, v59
	s_waitcnt lgkmcnt(6)
	v_fmac_f32_e32 v3, v6, v60
	v_fmac_f32_e32 v3, v8, v61
	s_waitcnt lgkmcnt(5)
	v_fmac_f32_e32 v3, v10, v62
	v_fmac_f32_e32 v3, v12, v63
	v_mov_b32_e32 v35, v36
	s_waitcnt lgkmcnt(4)
	v_fmac_f32_e32 v3, v14, v64
	s_waitcnt lgkmcnt(3)
	v_pk_mul_f32 v[66:67], v[34:35], v[66:67]
	v_fmac_f32_e32 v3, v16, v65
	v_mov_b32_e32 v39, v40
	v_add_f32_e32 v3, v3, v66
	s_waitcnt lgkmcnt(2)
	v_pk_mul_f32 v[68:69], v[38:39], v[68:69]
	v_add_f32_e32 v3, v3, v67
	v_mov_b32_e32 v43, v44
	v_add_f32_e32 v3, v3, v68
	s_waitcnt lgkmcnt(1)
	v_pk_mul_f32 v[70:71], v[42:43], v[70:71]
	v_add_f32_e32 v3, v3, v69
	v_add_f32_e32 v3, v3, v70
	s_waitcnt lgkmcnt(0)
	v_pk_mul_f32 v[72:73], v[46:47], v[72:73]
	v_add_f32_e32 v3, v3, v71
	v_add_f32_e32 v3, v3, v72
	v_add_f32_e32 v3, v3, v73
	s_nop 1
	v_add_f32_dpp v3, v3, v3 quad_perm:[1,0,3,2] row_mask:0xf bank_mask:0xf
	s_nop 1
	v_add_f32_dpp v3, v3, v3 quad_perm:[2,3,0,1] row_mask:0xf bank_mask:0xf
	v_sub_f32_e32 v3, 0, v3
	v_cndmask_b32_e32 v3, v47, v3, vcc
.LBB0_117:
	s_andn2_b64 vcc, exec, s[86:87]
	s_cbranch_vccnz .LBB0_119
	v_mov_b32_e32 v2, v1
	v_mov_b32_e32 v4, v1
	v_mov_b32_e32 v6, v1
	v_mov_b32_e32 v8, v1
	v_mov_b32_e32 v11, v1
	v_mov_b32_e32 v14, v1
	v_mov_b32_e32 v15, v1
	v_mov_b32_e32 v17, v1
	v_mov_b32_e32 v35, v1
	s_waitcnt lgkmcnt(14)
	ds_read_b32 v10, v56 offset:21824
	v_mov_b32_e32 v37, v1
	v_mov_b32_e32 v39, v1
	v_mov_b32_e32 v9, v1
	v_mov_b32_e32 v7, v1
	v_mov_b32_e32 v5, v1
	v_mov_b32_e32 v3, v1
	v_cmp_eq_u32_e32 vcc, 1, v53
	v_cmp_eq_u32_e64 s[46:47], 1, v52
	v_cmp_eq_u32_e64 s[44:45], 2, v52
	v_cndmask_b32_e64 v13, 0, 1.0, vcc
	s_waitcnt lgkmcnt(0)
	v_fma_f32 v10, v10, v57, 0
	v_cmp_eq_u32_e32 vcc, 2, v53
	v_cmp_eq_u32_e64 s[0:1], 4, v53
	v_add_u32_e32 v34, 0x5800, v56
	v_cndmask_b32_e64 v16, 0, 1.0, vcc
	s_waitcnt lgkmcnt(0)
	s_nop 1
	v_add_f32_dpp v10, v10, v10 quad_perm:[1,0,3,2] row_mask:0xf bank_mask:0xf
	v_cmp_eq_u32_e32 vcc, 3, v53
	v_add_u32_e32 v36, 0x6800, v56
	v_add_u32_e32 v38, 0x6c00, v56
	s_waitcnt lgkmcnt(0)
	ds_read_b32 v12, v56 offset:22080
	s_nop 1
	v_add_f32_dpp v10, v10, v10 quad_perm:[2,3,0,1] row_mask:0xf bank_mask:0xf
	v_sub_f32_e32 v10, v13, v10
	v_cndmask_b32_e64 v10, v57, v10, s[46:47]
	s_waitcnt lgkmcnt(0)
	v_fma_f32 v12, v12, v10, 0
	s_nop 1
	v_add_f32_dpp v12, v12, v12 quad_perm:[1,0,3,2] row_mask:0xf bank_mask:0xf
	s_nop 1
	v_add_f32_dpp v12, v12, v12 quad_perm:[2,3,0,1] row_mask:0xf bank_mask:0xf
	v_sub_f32_e32 v12, v16, v12
	v_cndmask_b32_e64 v10, v10, v12, s[44:45]
	ds_read_b32 v12, v56 offset:22336
	v_cndmask_b32_e64 v16, 0, 1.0, vcc
	v_cmp_eq_u32_e32 vcc, 3, v52
	s_waitcnt lgkmcnt(0)
	v_fma_f32 v12, v12, v10, 0
	s_nop 1
	v_add_f32_dpp v12, v12, v12 quad_perm:[1,0,3,2] row_mask:0xf bank_mask:0xf
	s_nop 1
	v_add_f32_dpp v12, v12, v12 quad_perm:[2,3,0,1] row_mask:0xf bank_mask:0xf
	v_sub_f32_e32 v12, v16, v12
	v_cndmask_b32_e32 v10, v10, v12, vcc
	ds_read_b32 v12, v56 offset:22592
	v_cndmask_b32_e64 v16, 0, 1.0, s[0:1]
	v_cmp_eq_u32_e64 s[0:1], 5, v53
	s_waitcnt lgkmcnt(0)
	v_fma_f32 v12, v12, v10, 0
	s_nop 1
	v_add_f32_dpp v12, v12, v12 quad_perm:[1,0,3,2] row_mask:0xf bank_mask:0xf
	s_waitcnt lgkmcnt(0)
	s_nop 1
	v_add_f32_dpp v12, v12, v12 quad_perm:[2,3,0,1] row_mask:0xf bank_mask:0xf
	v_sub_f32_e32 v12, v16, v12
	v_cndmask_b32_e64 v11, v11, v12, s[42:43]
	ds_read2_b32 v[12:13], v34 offset0:80 offset1:84
	v_cndmask_b32_e64 v16, 0, 1.0, s[0:1]
	v_cmp_eq_u32_e64 s[0:1], 6, v53
	s_waitcnt lgkmcnt(0)
	v_pk_mul_f32 v[12:13], v[12:13], v[10:11]
	s_nop 0
	v_add_f32_e32 v12, 0, v12
	v_add_f32_e32 v12, v12, v13
	s_nop 1
	v_add_f32_dpp v12, v12, v12 quad_perm:[1,0,3,2] row_mask:0xf bank_mask:0xf
	s_waitcnt lgkmcnt(0)
	s_nop 1
	v_add_f32_dpp v12, v12, v12 quad_perm:[2,3,0,1] row_mask:0xf bank_mask:0xf
	v_sub_f32_e32 v12, v16, v12
	v_cndmask_b32_e64 v11, v11, v12, s[46:47]
	ds_read2_b32 v[12:13], v34 offset0:144 offset1:148
	v_cndmask_b32_e64 v16, 0, 1.0, s[0:1]
	v_cmp_eq_u32_e64 s[0:1], 7, v53
	s_waitcnt lgkmcnt(0)
	v_pk_mul_f32 v[12:13], v[12:13], v[10:11]
	s_nop 0
	v_add_f32_e32 v12, 0, v12
	v_add_f32_e32 v12, v12, v13
	s_nop 1
	v_add_f32_dpp v12, v12, v12 quad_perm:[1,0,3,2] row_mask:0xf bank_mask:0xf
	s_waitcnt lgkmcnt(0)
	s_nop 1
	v_add_f32_dpp v12, v12, v12 quad_perm:[2,3,0,1] row_mask:0xf bank_mask:0xf
	v_sub_f32_e32 v12, v16, v12
	v_cndmask_b32_e64 v11, v11, v12, s[44:45]
	ds_read2_b32 v[12:13], v34 offset0:208 offset1:212
	v_cndmask_b32_e64 v16, 0, 1.0, s[0:1]
	v_add_u32_e32 v34, 0x5c00, v56
	v_cmp_eq_u32_e64 s[0:1], 8, v53
	s_waitcnt lgkmcnt(0)
; template <int W> __device__ __forceinline__ void dn_solve(const LAS float* Mf, float (&t)[16], int lane) {
;     const int j = 16 * W + (lane >> 2), q = lane & 3;
; #pragma unroll
;     for (int s = 0; s < 16; ++s) t[s] = 0.f;
; #pragma unroll
;     for (int i = 16 * W; i < 64; ++i) {
;         float acc = 0.f;
; #pragma unroll
;         for (int s = 4 * W; s <= (i - 1) / 4 && i > 16 * W; ++s) acc += Mf[i * 64 + 4 * s + q] * t[s];
;         acc += __shfl_xor(acc, 1); acc += __shfl_xor(acc, 2);
;         const float val = (i == j ? 1.f : 0.f) - acc;
;         if (q == (i & 3)) t[i >> 2] = val;
;         asm volatile("" : "+v"(t[0]), "+v"(t[1]), "+v"(t[2]), "+v"(t[3]), "+v"(t[4]), "+v"(t[5]), "+v"(t[6]), "+v"(t[7]), "+v"(t[8]), "+v"(t[9]), "+v"(t[10]), "+v"(t[11]), "+v"(t[12]), "+v"(t[13]), "+v"(t[14]), "+v"(t[15]));
	ds_read2_b32 v[40:41], v34 offset0:16 offset1:20
	v_pk_mul_f32 v[12:13], v[12:13], v[10:11]
	s_nop 0
	v_add_f32_e32 v12, 0, v12
	v_add_f32_e32 v12, v12, v13
	s_nop 1
	v_add_f32_dpp v12, v12, v12 quad_perm:[1,0,3,2] row_mask:0xf bank_mask:0xf
	s_nop 1
	v_add_f32_dpp v12, v12, v12 quad_perm:[2,3,0,1] row_mask:0xf bank_mask:0xf
	v_sub_f32_e32 v12, v16, v12
	v_cndmask_b32_e32 v12, v11, v12, vcc
	v_mov_b32_e32 v11, v12
	v_cndmask_b32_e64 v16, 0, 1.0, s[0:1]
	v_cmp_eq_u32_e64 s[0:1], 9, v53
	s_waitcnt lgkmcnt(0)
	v_pk_mul_f32 v[40:41], v[40:41], v[10:11]
	s_nop 0
	v_add_f32_e32 v11, 0, v40
	v_add_f32_e32 v11, v11, v41
	ds_read2_b32 v[40:41], v34 offset0:80 offset1:84
	ds_read_b32 v43, v56 offset:23904
	s_nop 1
	v_add_f32_dpp v11, v11, v11 quad_perm:[1,0,3,2] row_mask:0xf bank_mask:0xf
	s_nop 1
	v_add_f32_dpp v11, v11, v11 quad_perm:[2,3,0,1] row_mask:0xf bank_mask:0xf
	v_sub_f32_e32 v11, v16, v11
	v_cndmask_b32_e64 v13, v14, v11, s[42:43]
	v_cndmask_b32_e64 v16, 0, 1.0, s[0:1]
	v_cmp_eq_u32_e64 s[0:1], 10, v53
	s_waitcnt lgkmcnt(1)
	v_mov_b32_e32 v42, v41
	v_fma_f32 v11, v40, v10, 0
	s_waitcnt lgkmcnt(0)
	v_pk_mul_f32 v[40:41], v[12:13], v[42:43]
	s_nop 0
	v_add_f32_e32 v11, v11, v40
	v_add_f32_e32 v11, v11, v41
	ds_read2_b32 v[40:41], v34 offset0:144 offset1:148
	ds_read_b32 v43, v56 offset:24160
	s_nop 1
	v_add_f32_dpp v11, v11, v11 quad_perm:[1,0,3,2] row_mask:0xf bank_mask:0xf
	s_nop 1
	v_add_f32_dpp v11, v11, v11 quad_perm:[2,3,0,1] row_mask:0xf bank_mask:0xf
	v_sub_f32_e32 v11, v16, v11
	v_cndmask_b32_e64 v13, v13, v11, s[46:47]
	v_cndmask_b32_e64 v16, 0, 1.0, s[0:1]
	v_cmp_eq_u32_e64 s[0:1], 11, v53
	s_waitcnt lgkmcnt(1)
	v_mov_b32_e32 v42, v41
	v_fma_f32 v11, v40, v10, 0
	s_waitcnt lgkmcnt(0)
	v_pk_mul_f32 v[40:41], v[12:13], v[42:43]
	s_nop 0
	v_add_f32_e32 v11, v11, v40
	v_add_f32_e32 v11, v11, v41
	ds_read2_b32 v[40:41], v34 offset0:208 offset1:212
	ds_read_b32 v43, v56 offset:24416
	s_nop 1
	v_add_f32_dpp v11, v11, v11 quad_perm:[1,0,3,2] row_mask:0xf bank_mask:0xf
	s_nop 1
	v_add_f32_dpp v11, v11, v11 quad_perm:[2,3,0,1] row_mask:0xf bank_mask:0xf
	v_sub_f32_e32 v11, v16, v11
	v_cndmask_b32_e64 v13, v13, v11, s[44:45]
	v_cndmask_b32_e64 v16, 0, 1.0, s[0:1]
	v_add_u32_e32 v34, 0x6000, v56
	v_cmp_eq_u32_e64 s[0:1], 12, v53
	s_waitcnt lgkmcnt(1)
	v_mov_b32_e32 v42, v41
	v_fma_f32 v11, v40, v10, 0
	s_waitcnt lgkmcnt(0)
	v_pk_mul_f32 v[40:41], v[12:13], v[42:43]
	s_nop 0
	v_add_f32_e32 v11, v11, v40
	v_add_f32_e32 v11, v11, v41
	ds_read2_b32 v[40:41], v34 offset0:16 offset1:20
	ds_read_b32 v43, v56 offset:24672
	s_nop 1
	v_add_f32_dpp v11, v11, v11 quad_perm:[1,0,3,2] row_mask:0xf bank_mask:0xf
	s_nop 1
	v_add_f32_dpp v11, v11, v11 quad_perm:[2,3,0,1] row_mask:0xf bank_mask:0xf
	v_sub_f32_e32 v11, v16, v11
	v_cndmask_b32_e32 v14, v13, v11, vcc
	v_mov_b32_e32 v13, v14
	v_cndmask_b32_e64 v16, 0, 1.0, s[0:1]
	v_cmp_eq_u32_e64 s[0:1], 13, v53
	s_waitcnt lgkmcnt(1)
	v_mov_b32_e32 v42, v41
	v_fma_f32 v11, v40, v10, 0
	s_waitcnt lgkmcnt(0)
	v_pk_mul_f32 v[40:41], v[12:13], v[42:43]
	s_nop 0
	v_add_f32_e32 v11, v11, v40
	v_add_f32_e32 v11, v11, v41
	ds_read2_b32 v[40:41], v34 offset0:80 offset1:84
	ds_read2_b32 v[42:43], v34 offset0:88 offset1:92
	s_nop 1
	v_add_f32_dpp v11, v11, v11 quad_perm:[1,0,3,2] row_mask:0xf bank_mask:0xf
	s_nop 1
	v_add_f32_dpp v11, v11, v11 quad_perm:[2,3,0,1] row_mask:0xf bank_mask:0xf
	v_sub_f32_e32 v11, v16, v11
	v_cndmask_b32_e64 v15, v15, v11, s[42:43]
	v_mov_b32_e32 v11, v12
	v_cndmask_b32_e64 v16, 0, 1.0, s[0:1]
	v_cmp_eq_u32_e64 s[0:1], 14, v53
	s_waitcnt lgkmcnt(1)
	v_pk_mul_f32 v[40:41], v[40:41], v[10:11]
	s_waitcnt lgkmcnt(0)
	v_pk_mul_f32 v[42:43], v[14:15], v[42:43]
	v_add_f32_e32 v11, 0, v40
	v_add_f32_e32 v11, v11, v41
	v_add_f32_e32 v11, v11, v42
	v_add_f32_e32 v11, v11, v43
	ds_read2_b32 v[40:41], v34 offset0:144 offset1:148
	ds_read2_b32 v[42:43], v34 offset0:152 offset1:156
	s_nop 1
	v_add_f32_dpp v11, v11, v11 quad_perm:[1,0,3,2] row_mask:0xf bank_mask:0xf
	s_nop 1
	v_add_f32_dpp v11, v11, v11 quad_perm:[2,3,0,1] row_mask:0xf bank_mask:0xf
	v_sub_f32_e32 v11, v16, v11
	v_cndmask_b32_e64 v15, v15, v11, s[46:47]
	v_mov_b32_e32 v11, v12
	v_cndmask_b32_e64 v16, 0, 1.0, s[0:1]
	v_cmp_eq_u32_e64 s[0:1], 15, v53
	s_waitcnt lgkmcnt(1)
	v_pk_mul_f32 v[40:41], v[40:41], v[10:11]
	s_waitcnt lgkmcnt(0)
	v_pk_mul_f32 v[42:43], v[14:15], v[42:43]
	v_add_f32_e32 v11, 0, v40
	v_add_f32_e32 v11, v11, v41
	v_add_f32_e32 v11, v11, v42
	v_add_f32_e32 v11, v11, v43
	ds_read2_b32 v[40:41], v34 offset0:208 offset1:212
	ds_read2_b32 v[42:43], v34 offset0:216 offset1:220
	s_nop 1
	v_add_f32_dpp v11, v11, v11 quad_perm:[1,0,3,2] row_mask:0xf bank_mask:0xf
	s_nop 1
	v_add_f32_dpp v11, v11, v11 quad_perm:[2,3,0,1] row_mask:0xf bank_mask:0xf
	v_sub_f32_e32 v11, v16, v11
	v_cndmask_b32_e64 v15, v15, v11, s[44:45]
	v_mov_b32_e32 v11, v12
	v_cndmask_b32_e64 v16, 0, 1.0, s[0:1]
	v_add_u32_e32 v34, 0x6400, v56
	s_waitcnt lgkmcnt(1)
	v_pk_mul_f32 v[40:41], v[40:41], v[10:11]
	s_waitcnt lgkmcnt(0)
	v_pk_mul_f32 v[42:43], v[14:15], v[42:43]
	v_add_f32_e32 v11, 0, v40
	v_add_f32_e32 v11, v11, v41
	v_add_f32_e32 v11, v11, v42
	v_add_f32_e32 v11, v11, v43
	ds_read2_b32 v[40:41], v34 offset0:16 offset1:20
	ds_read2_b32 v[42:43], v34 offset0:24 offset1:28
	s_nop 1
	v_add_f32_dpp v11, v11, v11 quad_perm:[1,0,3,2] row_mask:0xf bank_mask:0xf
	s_nop 1
	v_add_f32_dpp v11, v11, v11 quad_perm:[2,3,0,1] row_mask:0xf bank_mask:0xf
	v_sub_f32_e32 v11, v16, v11
	v_cndmask_b32_e32 v16, v15, v11, vcc
	v_mov_b32_e32 v11, v12
	v_mov_b32_e32 v15, v16
	s_waitcnt lgkmcnt(1)
	v_pk_mul_f32 v[40:41], v[40:41], v[10:11]
	s_nop 0
	v_add_f32_e32 v11, 0, v40
	s_waitcnt lgkmcnt(0)
; template <int W> __device__ __forceinline__ void dn_solve(const LAS float* Mf, float (&t)[16], int lane) {
;     const int j = 16 * W + (lane >> 2), q = lane & 3;
; #pragma unroll
;     for (int s = 0; s < 16; ++s) t[s] = 0.f;
; #pragma unroll
;     for (int i = 16 * W; i < 64; ++i) {
;         float acc = 0.f;
; #pragma unroll
;         for (int s = 4 * W; s <= (i - 1) / 4 && i > 16 * W; ++s) acc += Mf[i * 64 + 4 * s + q] * t[s];
;         acc += __shfl_xor(acc, 1); acc += __shfl_xor(acc, 2);
;         const float val = (i == j ? 1.f : 0.f) - acc;
;         if (q == (i & 3)) t[i >> 2] = val;
;         asm volatile("" : "+v"(t[0]), "+v"(t[1]), "+v"(t[2]), "+v"(t[3]), "+v"(t[4]), "+v"(t[5]), "+v"(t[6]), "+v"(t[7]), "+v"(t[8]), "+v"(t[9]), "+v"(t[10]), "+v"(t[11]), "+v"(t[12]), "+v"(t[13]), "+v"(t[14]), "+v"(t[15]));
	v_pk_mul_f32 v[42:43], v[14:15], v[42:43]
	v_add_f32_e32 v11, v11, v41
	v_add_f32_e32 v11, v11, v42
	v_add_f32_e32 v11, v11, v43
	ds_read2_b32 v[40:41], v34 offset0:80 offset1:84
	ds_read2_b32 v[42:43], v34 offset0:88 offset1:92
	ds_read_b32 v45, v56 offset:25984
	s_nop 1
	v_add_f32_dpp v11, v11, v11 quad_perm:[1,0,3,2] row_mask:0xf bank_mask:0xf
	s_nop 1
	v_add_f32_dpp v11, v11, v11 quad_perm:[2,3,0,1] row_mask:0xf bank_mask:0xf
	v_sub_f32_e32 v11, 0, v11
	v_cndmask_b32_e64 v17, v17, v11, s[42:43]
	v_mov_b32_e32 v13, v14
	s_waitcnt lgkmcnt(2)
	v_fma_f32 v11, v40, v10, 0
	v_mov_b32_e32 v40, v41
	s_waitcnt lgkmcnt(1)
	v_mov_b32_e32 v41, v42
	v_pk_mul_f32 v[40:41], v[12:13], v[40:41]
	v_mov_b32_e32 v44, v43
	v_add_f32_e32 v11, v11, v40
	s_waitcnt lgkmcnt(0)
	v_pk_mul_f32 v[42:43], v[16:17], v[44:45]
	v_add_f32_e32 v11, v11, v41
	v_add_f32_e32 v11, v11, v42
	v_add_f32_e32 v11, v11, v43
	ds_read2_b32 v[40:41], v34 offset0:144 offset1:148
	ds_read2_b32 v[42:43], v34 offset0:152 offset1:156
	ds_read_b32 v45, v56 offset:26240
	s_nop 1
	v_add_f32_dpp v11, v11, v11 quad_perm:[1,0,3,2] row_mask:0xf bank_mask:0xf
	s_nop 1
	v_add_f32_dpp v11, v11, v11 quad_perm:[2,3,0,1] row_mask:0xf bank_mask:0xf
	v_sub_f32_e32 v11, 0, v11
	v_cndmask_b32_e64 v17, v17, v11, s[46:47]
	v_mov_b32_e32 v13, v14
	s_waitcnt lgkmcnt(2)
	v_fma_f32 v11, v40, v10, 0
	v_mov_b32_e32 v40, v41
	s_waitcnt lgkmcnt(1)
	v_mov_b32_e32 v41, v42
	v_pk_mul_f32 v[40:41], v[12:13], v[40:41]
	v_mov_b32_e32 v44, v43
	v_add_f32_e32 v11, v11, v40
	s_waitcnt lgkmcnt(0)
	v_pk_mul_f32 v[42:43], v[16:17], v[44:45]
	v_add_f32_e32 v11, v11, v41
	v_add_f32_e32 v11, v11, v42
	v_add_f32_e32 v11, v11, v43
	ds_read2_b32 v[40:41], v34 offset0:208 offset1:212
	ds_read2_b32 v[42:43], v34 offset0:216 offset1:220
	ds_read_b32 v45, v56 offset:26496
	s_nop 1
	v_add_f32_dpp v11, v11, v11 quad_perm:[1,0,3,2] row_mask:0xf bank_mask:0xf
	s_nop 1
	v_add_f32_dpp v11, v11, v11 quad_perm:[2,3,0,1] row_mask:0xf bank_mask:0xf
	v_sub_f32_e32 v11, 0, v11
	v_cndmask_b32_e64 v17, v17, v11, s[44:45]
	v_mov_b32_e32 v13, v14
	s_waitcnt lgkmcnt(2)
	v_fma_f32 v11, v40, v10, 0
	v_mov_b32_e32 v40, v41
	s_waitcnt lgkmcnt(1)
	v_mov_b32_e32 v41, v42
	v_pk_mul_f32 v[40:41], v[12:13], v[40:41]
	v_mov_b32_e32 v44, v43
	v_add_f32_e32 v11, v11, v40
	s_waitcnt lgkmcnt(0)
	v_pk_mul_f32 v[42:43], v[16:17], v[44:45]
	v_add_f32_e32 v11, v11, v41
	v_add_f32_e32 v11, v11, v42
	v_add_f32_e32 v11, v11, v43
	ds_read2_b32 v[40:41], v36 offset0:16 offset1:20
	ds_read2_b32 v[42:43], v36 offset0:24 offset1:28
	ds_read_b32 v45, v56 offset:26752
	s_nop 1
	v_add_f32_dpp v11, v11, v11 quad_perm:[1,0,3,2] row_mask:0xf bank_mask:0xf
	s_nop 1
	v_add_f32_dpp v11, v11, v11 quad_perm:[2,3,0,1] row_mask:0xf bank_mask:0xf
	v_sub_f32_e32 v11, 0, v11
	v_cndmask_b32_e32 v34, v17, v11, vcc
	v_mov_b32_e32 v13, v14
	v_mov_b32_e32 v17, v34
	s_waitcnt lgkmcnt(2)
	v_fma_f32 v11, v40, v10, 0
	v_mov_b32_e32 v40, v41
	s_waitcnt lgkmcnt(1)
	v_mov_b32_e32 v41, v42
	v_pk_mul_f32 v[40:41], v[12:13], v[40:41]
	v_mov_b32_e32 v44, v43
	v_add_f32_e32 v11, v11, v40
	s_waitcnt lgkmcnt(0)
	v_pk_mul_f32 v[42:43], v[16:17], v[44:45]
	v_add_f32_e32 v11, v11, v41
	v_add_f32_e32 v11, v11, v42
	v_add_f32_e32 v11, v11, v43
	ds_read2_b32 v[40:41], v36 offset0:80 offset1:84
	ds_read2_b32 v[42:43], v36 offset0:88 offset1:92
	ds_read2_b32 v[44:45], v36 offset0:96 offset1:100
	s_nop 1
	v_add_f32_dpp v11, v11, v11 quad_perm:[1,0,3,2] row_mask:0xf bank_mask:0xf
	s_nop 1
	v_add_f32_dpp v11, v11, v11 quad_perm:[2,3,0,1] row_mask:0xf bank_mask:0xf
	v_sub_f32_e32 v11, 0, v11
	v_cndmask_b32_e64 v35, v35, v11, s[42:43]
	v_mov_b32_e32 v15, v16
	s_waitcnt lgkmcnt(2)
	v_fma_f32 v11, v40, v10, 0
	s_waitcnt lgkmcnt(1)
	v_pk_mul_f32 v[42:43], v[14:15], v[42:43]
	v_fmac_f32_e32 v11, v12, v41
	v_add_f32_e32 v11, v11, v42
	s_waitcnt lgkmcnt(0)
	v_pk_mul_f32 v[44:45], v[34:35], v[44:45]
	v_add_f32_e32 v11, v11, v43
	v_add_f32_e32 v11, v11, v44
	v_add_f32_e32 v11, v11, v45
	ds_read2_b32 v[40:41], v36 offset0:144 offset1:148
	ds_read2_b32 v[42:43], v36 offset0:152 offset1:156
	ds_read2_b32 v[44:45], v36 offset0:160 offset1:164
	s_nop 1
	v_add_f32_dpp v11, v11, v11 quad_perm:[1,0,3,2] row_mask:0xf bank_mask:0xf
	s_nop 1
	v_add_f32_dpp v11, v11, v11 quad_perm:[2,3,0,1] row_mask:0xf bank_mask:0xf
	v_sub_f32_e32 v11, 0, v11
	v_cndmask_b32_e64 v35, v35, v11, s[46:47]
	v_mov_b32_e32 v15, v16
	s_waitcnt lgkmcnt(2)
	v_fma_f32 v11, v40, v10, 0
	s_waitcnt lgkmcnt(1)
	v_pk_mul_f32 v[42:43], v[14:15], v[42:43]
	v_fmac_f32_e32 v11, v12, v41
	v_add_f32_e32 v11, v11, v42
	s_waitcnt lgkmcnt(0)
	v_pk_mul_f32 v[44:45], v[34:35], v[44:45]
	v_add_f32_e32 v11, v11, v43
	v_add_f32_e32 v11, v11, v44
	v_add_f32_e32 v11, v11, v45
	ds_read2_b32 v[40:41], v36 offset0:208 offset1:212
	ds_read2_b32 v[42:43], v36 offset0:216 offset1:220
	ds_read2_b32 v[44:45], v36 offset0:224 offset1:228
	s_nop 1
	v_add_f32_dpp v11, v11, v11 quad_perm:[1,0,3,2] row_mask:0xf bank_mask:0xf
	s_nop 1
	v_add_f32_dpp v11, v11, v11 quad_perm:[2,3,0,1] row_mask:0xf bank_mask:0xf
	v_sub_f32_e32 v11, 0, v11
	v_cndmask_b32_e64 v35, v35, v11, s[44:45]
	v_mov_b32_e32 v15, v16
	s_waitcnt lgkmcnt(2)
	v_fma_f32 v11, v40, v10, 0
	s_waitcnt lgkmcnt(1)
	v_pk_mul_f32 v[42:43], v[14:15], v[42:43]
	v_fmac_f32_e32 v11, v12, v41
	v_add_f32_e32 v11, v11, v42
	s_waitcnt lgkmcnt(0)
	v_pk_mul_f32 v[44:45], v[34:35], v[44:45]
	v_add_f32_e32 v11, v11, v43
	v_add_f32_e32 v11, v11, v44
	v_add_f32_e32 v11, v11, v45
	ds_read2_b32 v[40:41], v38 offset0:16 offset1:20
	ds_read2_b32 v[42:43], v38 offset0:24 offset1:28
	ds_read2_b32 v[44:45], v38 offset0:32 offset1:36
	s_nop 1
	v_add_f32_dpp v11, v11, v11 quad_perm:[1,0,3,2] row_mask:0xf bank_mask:0xf
	s_nop 1
	v_add_f32_dpp v11, v11, v11 quad_perm:[2,3,0,1] row_mask:0xf bank_mask:0xf
	v_sub_f32_e32 v11, 0, v11
	v_cndmask_b32_e32 v36, v35, v11, vcc
	v_mov_b32_e32 v15, v16
	v_mov_b32_e32 v35, v36
	s_waitcnt lgkmcnt(2)
; #define LAS __attribute__((address_space(3)))
; template <int W> __device__ __forceinline__ void dn_solve(const LAS float* Mf, float (&t)[16], int lane) {
;     const int j = 16 * W + (lane >> 2), q = lane & 3;
; #pragma unroll
;     for (int s = 0; s < 16; ++s) t[s] = 0.f;
; #pragma unroll
;     for (int i = 16 * W; i < 64; ++i) {
;         float acc = 0.f;
; #pragma unroll
;         for (int s = 4 * W; s <= (i - 1) / 4 && i > 16 * W; ++s) acc += Mf[i * 64 + 4 * s + q] * t[s];
;         acc += __shfl_xor(acc, 1); acc += __shfl_xor(acc, 2);
;         const float val = (i == j ? 1.f : 0.f) - acc;
;         if (q == (i & 3)) t[i >> 2] = val;
;         asm volatile("" : "+v"(t[0]), "+v"(t[1]), "+v"(t[2]), "+v"(t[3]), "+v"(t[4]), "+v"(t[5]), "+v"(t[6]), "+v"(t[7]), "+v"(t[8]), "+v"(t[9]), "+v"(t[10]), "+v"(t[11]), "+v"(t[12]), "+v"(t[13]), "+v"(t[14]), "+v"(t[15]));
;     }
; }
	v_fma_f32 v11, v40, v10, 0
	s_waitcnt lgkmcnt(1)
	v_pk_mul_f32 v[42:43], v[14:15], v[42:43]
	v_fmac_f32_e32 v11, v12, v41
	v_add_f32_e32 v11, v11, v42
	s_waitcnt lgkmcnt(0)
	v_pk_mul_f32 v[44:45], v[34:35], v[44:45]
	v_add_f32_e32 v11, v11, v43
	v_add_f32_e32 v11, v11, v44
	v_add_f32_e32 v11, v11, v45
	v_add_u32_e32 v15, 0x7000, v56
	s_waitcnt lgkmcnt(0)
	ds_read2_b32 v[40:41], v38 offset0:80 offset1:84
	ds_read2_b32 v[42:43], v38 offset0:88 offset1:92
	ds_read2_b32 v[44:45], v38 offset0:96 offset1:100
	ds_read_b32 v47, v56 offset:28064
	s_nop 1
	v_add_f32_dpp v11, v11, v11 quad_perm:[1,0,3,2] row_mask:0xf bank_mask:0xf
	s_nop 1
	v_add_f32_dpp v11, v11, v11 quad_perm:[2,3,0,1] row_mask:0xf bank_mask:0xf
	v_sub_f32_e32 v11, 0, v11
	v_cndmask_b32_e64 v37, v37, v11, s[42:43]
	v_mov_b32_e32 v17, v34
	s_waitcnt lgkmcnt(3)
	v_fma_f32 v11, v40, v10, 0
	s_waitcnt lgkmcnt(2)
	v_mov_b32_e32 v58, v43
	s_waitcnt lgkmcnt(1)
	v_mov_b32_e32 v59, v44
	v_fmac_f32_e32 v11, v12, v41
	v_pk_mul_f32 v[40:41], v[16:17], v[58:59]
	v_fmac_f32_e32 v11, v14, v42
	v_mov_b32_e32 v46, v45
	v_add_f32_e32 v11, v11, v40
	s_waitcnt lgkmcnt(0)
	v_pk_mul_f32 v[44:45], v[36:37], v[46:47]
	v_add_f32_e32 v11, v11, v41
	v_add_f32_e32 v11, v11, v44
	v_add_f32_e32 v11, v11, v45
	ds_read2_b32 v[40:41], v38 offset0:144 offset1:148
	ds_read2_b32 v[42:43], v38 offset0:152 offset1:156
	ds_read2_b32 v[44:45], v38 offset0:160 offset1:164
	ds_read_b32 v47, v56 offset:28320
	s_nop 1
	v_add_f32_dpp v11, v11, v11 quad_perm:[1,0,3,2] row_mask:0xf bank_mask:0xf
	s_nop 1
	v_add_f32_dpp v11, v11, v11 quad_perm:[2,3,0,1] row_mask:0xf bank_mask:0xf
	v_sub_f32_e32 v11, 0, v11
	v_cndmask_b32_e64 v37, v37, v11, s[46:47]
	v_mov_b32_e32 v17, v34
	s_waitcnt lgkmcnt(3)
	v_fma_f32 v11, v40, v10, 0
	s_waitcnt lgkmcnt(2)
	v_mov_b32_e32 v58, v43
	s_waitcnt lgkmcnt(1)
	v_mov_b32_e32 v59, v44
	v_fmac_f32_e32 v11, v12, v41
	v_pk_mul_f32 v[40:41], v[16:17], v[58:59]
	v_fmac_f32_e32 v11, v14, v42
	v_mov_b32_e32 v46, v45
	v_add_f32_e32 v11, v11, v40
	s_waitcnt lgkmcnt(0)
	v_pk_mul_f32 v[44:45], v[36:37], v[46:47]
	v_add_f32_e32 v11, v11, v41
	v_add_f32_e32 v11, v11, v44
	v_add_f32_e32 v11, v11, v45
	ds_read2_b32 v[40:41], v38 offset0:208 offset1:212
	ds_read2_b32 v[42:43], v38 offset0:216 offset1:220
	ds_read2_b32 v[44:45], v38 offset0:224 offset1:228
	ds_read_b32 v47, v56 offset:28576
	s_nop 1
	v_add_f32_dpp v11, v11, v11 quad_perm:[1,0,3,2] row_mask:0xf bank_mask:0xf
	s_nop 1
	v_add_f32_dpp v11, v11, v11 quad_perm:[2,3,0,1] row_mask:0xf bank_mask:0xf
	v_sub_f32_e32 v11, 0, v11
	v_cndmask_b32_e64 v37, v37, v11, s[44:45]
	v_mov_b32_e32 v17, v34
	s_waitcnt lgkmcnt(3)
	v_fma_f32 v11, v40, v10, 0
	s_waitcnt lgkmcnt(2)
	v_mov_b32_e32 v58, v43
	s_waitcnt lgkmcnt(1)
	v_mov_b32_e32 v59, v44
	v_fmac_f32_e32 v11, v12, v41
	v_pk_mul_f32 v[40:41], v[16:17], v[58:59]
	v_fmac_f32_e32 v11, v14, v42
	v_mov_b32_e32 v46, v45
	v_add_f32_e32 v11, v11, v40
	s_waitcnt lgkmcnt(0)
	v_pk_mul_f32 v[44:45], v[36:37], v[46:47]
	v_add_f32_e32 v11, v11, v41
	v_add_f32_e32 v11, v11, v44
	v_add_f32_e32 v11, v11, v45
	ds_read2_b32 v[40:41], v15 offset0:16 offset1:20
	ds_read2_b32 v[42:43], v15 offset0:24 offset1:28
	ds_read2_b32 v[44:45], v15 offset0:32 offset1:36
	ds_read_b32 v47, v56 offset:28832
	s_nop 1
	v_add_f32_dpp v11, v11, v11 quad_perm:[1,0,3,2] row_mask:0xf bank_mask:0xf
	s_nop 1
	v_add_f32_dpp v11, v11, v11 quad_perm:[2,3,0,1] row_mask:0xf bank_mask:0xf
	v_sub_f32_e32 v11, 0, v11
	v_cndmask_b32_e32 v38, v37, v11, vcc
	v_mov_b32_e32 v17, v34
	s_waitcnt lgkmcnt(3)
	v_fma_f32 v11, v40, v10, 0
	s_waitcnt lgkmcnt(2)
	v_mov_b32_e32 v58, v43
	s_waitcnt lgkmcnt(1)
	v_mov_b32_e32 v59, v44
	v_fmac_f32_e32 v11, v12, v41
	v_pk_mul_f32 v[40:41], v[16:17], v[58:59]
	v_fmac_f32_e32 v11, v14, v42
	v_mov_b32_e32 v37, v38
	v_mov_b32_e32 v46, v45
	v_add_f32_e32 v11, v11, v40
	s_waitcnt lgkmcnt(0)
	v_pk_mul_f32 v[44:45], v[36:37], v[46:47]
	v_add_f32_e32 v11, v11, v41
	v_add_f32_e32 v11, v11, v44
	v_add_f32_e32 v11, v11, v45
	ds_read2_b32 v[40:41], v15 offset0:80 offset1:84
	ds_read2_b32 v[42:43], v15 offset0:96 offset1:100
	ds_read2_b32 v[44:45], v15 offset0:104 offset1:108
	ds_read2_b32 v[46:47], v15 offset0:88 offset1:92
	s_nop 1
	v_add_f32_dpp v11, v11, v11 quad_perm:[1,0,3,2] row_mask:0xf bank_mask:0xf
	s_nop 1
	v_add_f32_dpp v11, v11, v11 quad_perm:[2,3,0,1] row_mask:0xf bank_mask:0xf
	v_sub_f32_e32 v11, 0, v11
	v_cndmask_b32_e64 v39, v39, v11, s[42:43]
	v_mov_b32_e32 v35, v36
	s_waitcnt lgkmcnt(3)
	v_fma_f32 v11, v40, v10, 0
	v_fmac_f32_e32 v11, v12, v41
	s_waitcnt lgkmcnt(2)
	v_pk_mul_f32 v[42:43], v[34:35], v[42:43]
	s_waitcnt lgkmcnt(0)
	v_fmac_f32_e32 v11, v14, v46
	v_fmac_f32_e32 v11, v16, v47
	v_add_f32_e32 v11, v11, v42
	v_pk_mul_f32 v[44:45], v[38:39], v[44:45]
	v_add_f32_e32 v11, v11, v43
	v_add_f32_e32 v11, v11, v44
	v_add_f32_e32 v11, v11, v45
	ds_read2_b32 v[40:41], v15 offset0:144 offset1:148
	ds_read2_b32 v[42:43], v15 offset0:160 offset1:164
	ds_read2_b32 v[44:45], v15 offset0:168 offset1:172
	ds_read2_b32 v[46:47], v15 offset0:152 offset1:156
	s_nop 1
	v_add_f32_dpp v11, v11, v11 quad_perm:[1,0,3,2] row_mask:0xf bank_mask:0xf
	s_nop 1
	v_add_f32_dpp v11, v11, v11 quad_perm:[2,3,0,1] row_mask:0xf bank_mask:0xf
	v_sub_f32_e32 v11, 0, v11
	v_cndmask_b32_e64 v39, v39, v11, s[46:47]
	v_mov_b32_e32 v35, v36
	s_waitcnt lgkmcnt(3)
	v_fma_f32 v11, v40, v10, 0
	v_fmac_f32_e32 v11, v12, v41
	s_waitcnt lgkmcnt(2)
	v_pk_mul_f32 v[42:43], v[34:35], v[42:43]
	s_waitcnt lgkmcnt(0)
; #define LAS __attribute__((address_space(3)))
; template <int W> __device__ __forceinline__ void dn_solve(const LAS float* Mf, float (&t)[16], int lane) {
;     const int j = 16 * W + (lane >> 2), q = lane & 3;
; #pragma unroll
;     for (int s = 0; s < 16; ++s) t[s] = 0.f;
; #pragma unroll
;     for (int i = 16 * W; i < 64; ++i) {
;         float acc = 0.f;
; #pragma unroll
;         for (int s = 4 * W; s <= (i - 1) / 4 && i > 16 * W; ++s) acc += Mf[i * 64 + 4 * s + q] * t[s];
;         acc += __shfl_xor(acc, 1); acc += __shfl_xor(acc, 2);
;         const float val = (i == j ? 1.f : 0.f) - acc;
;         if (q == (i & 3)) t[i >> 2] = val;
;         asm volatile("" : "+v"(t[0]), "+v"(t[1]), "+v"(t[2]), "+v"(t[3]), "+v"(t[4]), "+v"(t[5]), "+v"(t[6]), "+v"(t[7]), "+v"(t[8]), "+v"(t[9]), "+v"(t[10]), "+v"(t[11]), "+v"(t[12]), "+v"(t[13]), "+v"(t[14]), "+v"(t[15]));
;     }
; }
	v_fmac_f32_e32 v11, v14, v46
	v_fmac_f32_e32 v11, v16, v47
	v_add_f32_e32 v11, v11, v42
	v_pk_mul_f32 v[44:45], v[38:39], v[44:45]
	v_add_f32_e32 v11, v11, v43
	v_add_f32_e32 v11, v11, v44
	v_add_f32_e32 v11, v11, v45
	ds_read2_b32 v[40:41], v15 offset0:208 offset1:212
	ds_read2_b32 v[42:43], v15 offset0:224 offset1:228
	ds_read2_b32 v[44:45], v15 offset0:232 offset1:236
	ds_read2_b32 v[46:47], v15 offset0:216 offset1:220
	s_nop 1
	v_add_f32_dpp v11, v11, v11 quad_perm:[1,0,3,2] row_mask:0xf bank_mask:0xf
	s_nop 1
	v_add_f32_dpp v11, v11, v11 quad_perm:[2,3,0,1] row_mask:0xf bank_mask:0xf
	v_sub_f32_e32 v11, 0, v11
	v_cndmask_b32_e64 v39, v39, v11, s[44:45]
	v_mov_b32_e32 v35, v36
	s_waitcnt lgkmcnt(3)
	v_fma_f32 v11, v40, v10, 0
	v_fmac_f32_e32 v11, v12, v41
	s_waitcnt lgkmcnt(2)
	v_pk_mul_f32 v[42:43], v[34:35], v[42:43]
	s_waitcnt lgkmcnt(0)
	v_fmac_f32_e32 v11, v14, v46
	v_fmac_f32_e32 v11, v16, v47
	v_add_f32_e32 v11, v11, v42
	v_pk_mul_f32 v[44:45], v[38:39], v[44:45]
	v_add_f32_e32 v11, v11, v43
	v_add_f32_e32 v11, v11, v44
	v_add_f32_e32 v11, v11, v45
	v_add_u32_e32 v15, 0x7400, v56
	s_waitcnt lgkmcnt(0)
	ds_read2_b32 v[42:43], v15 offset0:16 offset1:20
	ds_read2_b32 v[44:45], v15 offset0:24 offset1:28
	ds_read2_b32 v[46:47], v15 offset0:32 offset1:36
	ds_read2_b32 v[58:59], v15 offset0:40 offset1:44
	s_nop 1
	v_add_f32_dpp v11, v11, v11 quad_perm:[1,0,3,2] row_mask:0xf bank_mask:0xf
	s_nop 1
	v_add_f32_dpp v11, v11, v11 quad_perm:[2,3,0,1] row_mask:0xf bank_mask:0xf
	v_sub_f32_e32 v11, 0, v11
	v_cndmask_b32_e32 v40, v39, v11, vcc
	v_mov_b32_e32 v35, v36
	s_waitcnt lgkmcnt(3)
	v_fma_f32 v11, v42, v10, 0
	v_fmac_f32_e32 v11, v12, v43
	s_waitcnt lgkmcnt(2)
	v_fmac_f32_e32 v11, v14, v44
	s_waitcnt lgkmcnt(1)
	v_pk_mul_f32 v[46:47], v[34:35], v[46:47]
	v_fmac_f32_e32 v11, v16, v45
	v_mov_b32_e32 v39, v40
	v_add_f32_e32 v11, v11, v46
	s_waitcnt lgkmcnt(0)
	v_pk_mul_f32 v[58:59], v[38:39], v[58:59]
	v_add_f32_e32 v11, v11, v47
	v_add_f32_e32 v11, v11, v58
	v_add_f32_e32 v11, v11, v59
	ds_read2_b32 v[42:43], v15 offset0:80 offset1:84
	ds_read2_b32 v[44:45], v15 offset0:88 offset1:92
	ds_read2_b32 v[46:47], v15 offset0:96 offset1:100
	ds_read2_b32 v[58:59], v15 offset0:104 offset1:108
	ds_read_b32 v61, v56 offset:30144
	s_nop 1
	v_add_f32_dpp v11, v11, v11 quad_perm:[1,0,3,2] row_mask:0xf bank_mask:0xf
	s_nop 1
	v_add_f32_dpp v11, v11, v11 quad_perm:[2,3,0,1] row_mask:0xf bank_mask:0xf
	v_sub_f32_e32 v11, 0, v11
	v_cndmask_b32_e64 v41, v9, v11, s[42:43]
	s_waitcnt lgkmcnt(4)
	v_fma_f32 v9, v42, v10, 0
	v_fmac_f32_e32 v9, v12, v43
	s_waitcnt lgkmcnt(3)
	v_fmac_f32_e32 v9, v14, v44
	v_mov_b32_e32 v37, v38
	s_waitcnt lgkmcnt(2)
	v_mov_b32_e32 v62, v47
	s_waitcnt lgkmcnt(1)
	v_mov_b32_e32 v63, v58
	v_fmac_f32_e32 v9, v16, v45
	v_pk_mul_f32 v[42:43], v[36:37], v[62:63]
	v_fmac_f32_e32 v9, v34, v46
	v_mov_b32_e32 v60, v59
	v_add_f32_e32 v9, v9, v42
	s_waitcnt lgkmcnt(0)
	v_pk_mul_f32 v[58:59], v[40:41], v[60:61]
	v_add_f32_e32 v9, v9, v43
	v_add_f32_e32 v9, v9, v58
	v_add_f32_e32 v9, v9, v59
	v_add_u32_e32 v13, 0x7800, v56
	s_waitcnt lgkmcnt(0)
	ds_read2_b32 v[42:43], v15 offset0:144 offset1:148
	ds_read2_b32 v[44:45], v15 offset0:152 offset1:156
	ds_read2_b32 v[46:47], v15 offset0:160 offset1:164
	ds_read2_b32 v[58:59], v15 offset0:168 offset1:172
	ds_read_b32 v61, v56 offset:30400
	s_nop 1
	v_add_f32_dpp v9, v9, v9 quad_perm:[1,0,3,2] row_mask:0xf bank_mask:0xf
	s_nop 1
	v_add_f32_dpp v9, v9, v9 quad_perm:[2,3,0,1] row_mask:0xf bank_mask:0xf
	v_sub_f32_e32 v9, 0, v9
	v_cndmask_b32_e64 v41, v41, v9, s[46:47]
	s_waitcnt lgkmcnt(4)
	v_fma_f32 v9, v42, v10, 0
	v_fmac_f32_e32 v9, v12, v43
	s_waitcnt lgkmcnt(3)
	v_fmac_f32_e32 v9, v14, v44
	v_mov_b32_e32 v37, v38
	s_waitcnt lgkmcnt(2)
	v_mov_b32_e32 v62, v47
	s_waitcnt lgkmcnt(1)
	v_mov_b32_e32 v63, v58
	v_fmac_f32_e32 v9, v16, v45
	v_pk_mul_f32 v[42:43], v[36:37], v[62:63]
	v_fmac_f32_e32 v9, v34, v46
	v_mov_b32_e32 v60, v59
	v_add_f32_e32 v9, v9, v42
	s_waitcnt lgkmcnt(0)
	v_pk_mul_f32 v[58:59], v[40:41], v[60:61]
	v_add_f32_e32 v9, v9, v43
	v_add_f32_e32 v9, v9, v58
	v_add_f32_e32 v9, v9, v59
	ds_read2_b32 v[42:43], v15 offset0:208 offset1:212
	ds_read2_b32 v[44:45], v15 offset0:216 offset1:220
	ds_read2_b32 v[46:47], v15 offset0:224 offset1:228
	ds_read2_b32 v[58:59], v15 offset0:232 offset1:236
	ds_read_b32 v61, v56 offset:30656
	s_nop 1
	v_add_f32_dpp v9, v9, v9 quad_perm:[1,0,3,2] row_mask:0xf bank_mask:0xf
	s_nop 1
	v_add_f32_dpp v9, v9, v9 quad_perm:[2,3,0,1] row_mask:0xf bank_mask:0xf
	v_sub_f32_e32 v9, 0, v9
	v_cndmask_b32_e64 v41, v41, v9, s[44:45]
	s_waitcnt lgkmcnt(4)
	v_fma_f32 v9, v42, v10, 0
	v_fmac_f32_e32 v9, v12, v43
	s_waitcnt lgkmcnt(3)
	v_fmac_f32_e32 v9, v14, v44
	v_mov_b32_e32 v37, v38
	s_waitcnt lgkmcnt(2)
	v_mov_b32_e32 v62, v47
	s_waitcnt lgkmcnt(1)
	v_mov_b32_e32 v63, v58
	v_fmac_f32_e32 v9, v16, v45
	v_pk_mul_f32 v[42:43], v[36:37], v[62:63]
	v_fmac_f32_e32 v9, v34, v46
	v_mov_b32_e32 v60, v59
	v_add_f32_e32 v9, v9, v42
	s_waitcnt lgkmcnt(0)
	v_pk_mul_f32 v[58:59], v[40:41], v[60:61]
	v_add_f32_e32 v9, v9, v43
	v_add_f32_e32 v9, v9, v58
	v_add_f32_e32 v9, v9, v59
	ds_read2_b32 v[44:45], v13 offset0:16 offset1:20
	ds_read2_b32 v[46:47], v13 offset0:24 offset1:28
	ds_read2_b32 v[58:59], v13 offset0:32 offset1:36
	ds_read2_b32 v[60:61], v13 offset0:40 offset1:44
	ds_read_b32 v63, v56 offset:30912
	s_nop 1
	v_add_f32_dpp v9, v9, v9 quad_perm:[1,0,3,2] row_mask:0xf bank_mask:0xf
	s_nop 1
	v_add_f32_dpp v9, v9, v9 quad_perm:[2,3,0,1] row_mask:0xf bank_mask:0xf
	v_sub_f32_e32 v9, 0, v9
	v_cndmask_b32_e32 v42, v41, v9, vcc
	s_waitcnt lgkmcnt(4)
; #define LAS __attribute__((address_space(3)))
; template <int W> __device__ __forceinline__ void dn_solve(const LAS float* Mf, float (&t)[16], int lane) {
;     const int j = 16 * W + (lane >> 2), q = lane & 3;
; #pragma unroll
;     for (int s = 0; s < 16; ++s) t[s] = 0.f;
; #pragma unroll
;     for (int i = 16 * W; i < 64; ++i) {
;         float acc = 0.f;
; #pragma unroll
;         for (int s = 4 * W; s <= (i - 1) / 4 && i > 16 * W; ++s) acc += Mf[i * 64 + 4 * s + q] * t[s];
;         acc += __shfl_xor(acc, 1); acc += __shfl_xor(acc, 2);
;         const float val = (i == j ? 1.f : 0.f) - acc;
;         if (q == (i & 3)) t[i >> 2] = val;
;         asm volatile("" : "+v"(t[0]), "+v"(t[1]), "+v"(t[2]), "+v"(t[3]), "+v"(t[4]), "+v"(t[5]), "+v"(t[6]), "+v"(t[7]), "+v"(t[8]), "+v"(t[9]), "+v"(t[10]), "+v"(t[11]), "+v"(t[12]), "+v"(t[13]), "+v"(t[14]), "+v"(t[15]));
;     }
; }
	v_fma_f32 v9, v44, v10, 0
	v_fmac_f32_e32 v9, v12, v45
	s_waitcnt lgkmcnt(3)
	v_fmac_f32_e32 v9, v14, v46
	v_mov_b32_e32 v37, v38
	s_waitcnt lgkmcnt(2)
	v_mov_b32_e32 v64, v59
	s_waitcnt lgkmcnt(1)
	v_mov_b32_e32 v65, v60
	v_fmac_f32_e32 v9, v16, v47
	v_pk_mul_f32 v[44:45], v[36:37], v[64:65]
	v_fmac_f32_e32 v9, v34, v58
	v_mov_b32_e32 v41, v42
	v_mov_b32_e32 v62, v61
	v_add_f32_e32 v9, v9, v44
	s_waitcnt lgkmcnt(0)
	v_pk_mul_f32 v[60:61], v[40:41], v[62:63]
	v_add_f32_e32 v9, v9, v45
	v_add_f32_e32 v9, v9, v60
	v_add_f32_e32 v9, v9, v61
	ds_read2_b32 v[44:45], v13 offset0:80 offset1:84
	ds_read2_b32 v[46:47], v13 offset0:88 offset1:92
	ds_read2_b32 v[58:59], v13 offset0:104 offset1:108
	ds_read2_b32 v[60:61], v13 offset0:112 offset1:116
	ds_read2_b32 v[62:63], v13 offset0:96 offset1:100
	s_nop 1
	v_add_f32_dpp v9, v9, v9 quad_perm:[1,0,3,2] row_mask:0xf bank_mask:0xf
	s_nop 1
	v_add_f32_dpp v9, v9, v9 quad_perm:[2,3,0,1] row_mask:0xf bank_mask:0xf
	v_sub_f32_e32 v9, 0, v9
	v_cndmask_b32_e64 v43, v7, v9, s[42:43]
	s_waitcnt lgkmcnt(4)
	v_fma_f32 v7, v44, v10, 0
	v_fmac_f32_e32 v7, v12, v45
	s_waitcnt lgkmcnt(3)
	v_fmac_f32_e32 v7, v14, v46
	v_fmac_f32_e32 v7, v16, v47
	v_mov_b32_e32 v39, v40
	s_waitcnt lgkmcnt(0)
	v_fmac_f32_e32 v7, v34, v62
	v_pk_mul_f32 v[58:59], v[38:39], v[58:59]
	v_fmac_f32_e32 v7, v36, v63
	v_add_f32_e32 v7, v7, v58
	v_pk_mul_f32 v[60:61], v[42:43], v[60:61]
	v_add_f32_e32 v7, v7, v59
	v_add_f32_e32 v7, v7, v60
	v_add_f32_e32 v7, v7, v61
	v_add_u32_e32 v11, 0x7c00, v56
	s_waitcnt lgkmcnt(0)
	ds_read2_b32 v[44:45], v13 offset0:144 offset1:148
	ds_read2_b32 v[46:47], v13 offset0:152 offset1:156
	ds_read2_b32 v[58:59], v13 offset0:168 offset1:172
	ds_read2_b32 v[60:61], v13 offset0:176 offset1:180
	ds_read2_b32 v[62:63], v13 offset0:160 offset1:164
	s_nop 1
	v_add_f32_dpp v7, v7, v7 quad_perm:[1,0,3,2] row_mask:0xf bank_mask:0xf
	s_nop 1
	v_add_f32_dpp v7, v7, v7 quad_perm:[2,3,0,1] row_mask:0xf bank_mask:0xf
	v_sub_f32_e32 v7, 0, v7
	v_cndmask_b32_e64 v43, v43, v7, s[46:47]
	s_waitcnt lgkmcnt(4)
	v_fma_f32 v7, v44, v10, 0
	v_fmac_f32_e32 v7, v12, v45
	s_waitcnt lgkmcnt(3)
	v_fmac_f32_e32 v7, v14, v46
	v_fmac_f32_e32 v7, v16, v47
	v_mov_b32_e32 v39, v40
	s_waitcnt lgkmcnt(0)
	v_fmac_f32_e32 v7, v34, v62
	v_pk_mul_f32 v[58:59], v[38:39], v[58:59]
	v_fmac_f32_e32 v7, v36, v63
	v_add_f32_e32 v7, v7, v58
	v_pk_mul_f32 v[60:61], v[42:43], v[60:61]
	v_add_f32_e32 v7, v7, v59
	v_add_f32_e32 v7, v7, v60
	v_add_f32_e32 v7, v7, v61
	ds_read2_b32 v[44:45], v13 offset0:208 offset1:212
	ds_read2_b32 v[46:47], v13 offset0:216 offset1:220
	ds_read2_b32 v[58:59], v13 offset0:232 offset1:236
	ds_read2_b32 v[60:61], v13 offset0:240 offset1:244
	ds_read2_b32 v[62:63], v13 offset0:224 offset1:228
	s_nop 1
	v_add_f32_dpp v7, v7, v7 quad_perm:[1,0,3,2] row_mask:0xf bank_mask:0xf
	s_nop 1
	v_add_f32_dpp v7, v7, v7 quad_perm:[2,3,0,1] row_mask:0xf bank_mask:0xf
	v_sub_f32_e32 v7, 0, v7
	v_cndmask_b32_e64 v43, v43, v7, s[44:45]
	s_waitcnt lgkmcnt(4)
	v_fma_f32 v7, v44, v10, 0
	v_fmac_f32_e32 v7, v12, v45
	s_waitcnt lgkmcnt(3)
	v_fmac_f32_e32 v7, v14, v46
	v_fmac_f32_e32 v7, v16, v47
	v_mov_b32_e32 v39, v40
	s_waitcnt lgkmcnt(0)
	v_fmac_f32_e32 v7, v34, v62
	v_pk_mul_f32 v[58:59], v[38:39], v[58:59]
	v_fmac_f32_e32 v7, v36, v63
	v_add_f32_e32 v7, v7, v58
	v_pk_mul_f32 v[60:61], v[42:43], v[60:61]
	v_add_f32_e32 v7, v7, v59
	v_add_f32_e32 v7, v7, v60
	v_add_f32_e32 v7, v7, v61
	ds_read2_b32 v[46:47], v11 offset0:16 offset1:20
	ds_read2_b32 v[58:59], v11 offset0:24 offset1:28
	ds_read2_b32 v[60:61], v11 offset0:32 offset1:36
	ds_read2_b32 v[62:63], v11 offset0:40 offset1:44
	ds_read2_b32 v[64:65], v11 offset0:48 offset1:52
	s_nop 1
	v_add_f32_dpp v7, v7, v7 quad_perm:[1,0,3,2] row_mask:0xf bank_mask:0xf
	s_nop 1
	v_add_f32_dpp v7, v7, v7 quad_perm:[2,3,0,1] row_mask:0xf bank_mask:0xf
	v_sub_f32_e32 v7, 0, v7
	v_cndmask_b32_e32 v44, v43, v7, vcc
	s_waitcnt lgkmcnt(4)
	v_fma_f32 v7, v46, v10, 0
	v_fmac_f32_e32 v7, v12, v47
	s_waitcnt lgkmcnt(3)
	v_fmac_f32_e32 v7, v14, v58
	v_fmac_f32_e32 v7, v16, v59
	v_mov_b32_e32 v39, v40
	s_waitcnt lgkmcnt(2)
	v_fmac_f32_e32 v7, v34, v60
	s_waitcnt lgkmcnt(1)
	v_pk_mul_f32 v[62:63], v[38:39], v[62:63]
	v_fmac_f32_e32 v7, v36, v61
	v_mov_b32_e32 v43, v44
	v_add_f32_e32 v7, v7, v62
	s_waitcnt lgkmcnt(0)
	v_pk_mul_f32 v[64:65], v[42:43], v[64:65]
	v_add_f32_e32 v7, v7, v63
	v_add_f32_e32 v7, v7, v64
	v_add_f32_e32 v7, v7, v65
	ds_read2_b32 v[46:47], v11 offset0:80 offset1:84
	ds_read2_b32 v[58:59], v11 offset0:88 offset1:92
	ds_read2_b32 v[60:61], v11 offset0:96 offset1:100
	ds_read2_b32 v[62:63], v11 offset0:104 offset1:108
	ds_read2_b32 v[64:65], v11 offset0:112 offset1:116
	ds_read_b32 v67, v56 offset:32224
	s_nop 1
	v_add_f32_dpp v7, v7, v7 quad_perm:[1,0,3,2] row_mask:0xf bank_mask:0xf
	s_nop 1
	v_add_f32_dpp v7, v7, v7 quad_perm:[2,3,0,1] row_mask:0xf bank_mask:0xf
	v_sub_f32_e32 v7, 0, v7
	v_cndmask_b32_e64 v45, v5, v7, s[42:43]
	s_waitcnt lgkmcnt(5)
	v_fma_f32 v5, v46, v10, 0
	v_fmac_f32_e32 v5, v12, v47
	s_waitcnt lgkmcnt(4)
	v_fmac_f32_e32 v5, v14, v58
	v_fmac_f32_e32 v5, v16, v59
	s_waitcnt lgkmcnt(3)
	v_fmac_f32_e32 v5, v34, v60
	v_mov_b32_e32 v41, v42
	s_waitcnt lgkmcnt(2)
	v_mov_b32_e32 v68, v63
	s_waitcnt lgkmcnt(1)
	v_mov_b32_e32 v69, v64
	v_fmac_f32_e32 v5, v36, v61
	v_pk_mul_f32 v[46:47], v[40:41], v[68:69]
	v_fmac_f32_e32 v5, v38, v62
	v_mov_b32_e32 v66, v65
	v_add_f32_e32 v5, v5, v46
	s_waitcnt lgkmcnt(0)
	v_pk_mul_f32 v[64:65], v[44:45], v[66:67]
	v_add_f32_e32 v5, v5, v47
	v_add_f32_e32 v5, v5, v64
	v_add_f32_e32 v5, v5, v65
	v_add_u32_e32 v9, 0x8000, v56
	s_waitcnt lgkmcnt(0)
; #define LAS __attribute__((address_space(3)))
; template <int W> __device__ __forceinline__ void dn_solve(const LAS float* Mf, float (&t)[16], int lane) {
;     const int j = 16 * W + (lane >> 2), q = lane & 3;
; #pragma unroll
;     for (int s = 0; s < 16; ++s) t[s] = 0.f;
; #pragma unroll
;     for (int i = 16 * W; i < 64; ++i) {
;         float acc = 0.f;
; #pragma unroll
;         for (int s = 4 * W; s <= (i - 1) / 4 && i > 16 * W; ++s) acc += Mf[i * 64 + 4 * s + q] * t[s];
;         acc += __shfl_xor(acc, 1); acc += __shfl_xor(acc, 2);
;         const float val = (i == j ? 1.f : 0.f) - acc;
;         if (q == (i & 3)) t[i >> 2] = val;
;         asm volatile("" : "+v"(t[0]), "+v"(t[1]), "+v"(t[2]), "+v"(t[3]), "+v"(t[4]), "+v"(t[5]), "+v"(t[6]), "+v"(t[7]), "+v"(t[8]), "+v"(t[9]), "+v"(t[10]), "+v"(t[11]), "+v"(t[12]), "+v"(t[13]), "+v"(t[14]), "+v"(t[15]));
;     }
; }
	ds_read2_b32 v[46:47], v11 offset0:144 offset1:148
	ds_read2_b32 v[58:59], v11 offset0:152 offset1:156
	ds_read2_b32 v[60:61], v11 offset0:160 offset1:164
	ds_read2_b32 v[62:63], v11 offset0:168 offset1:172
	ds_read2_b32 v[64:65], v11 offset0:176 offset1:180
	ds_read_b32 v67, v56 offset:32480
	s_nop 1
	v_add_f32_dpp v5, v5, v5 quad_perm:[1,0,3,2] row_mask:0xf bank_mask:0xf
	s_nop 1
	v_add_f32_dpp v5, v5, v5 quad_perm:[2,3,0,1] row_mask:0xf bank_mask:0xf
	v_sub_f32_e32 v5, 0, v5
	v_cndmask_b32_e64 v45, v45, v5, s[46:47]
	s_waitcnt lgkmcnt(5)
	v_fma_f32 v5, v46, v10, 0
	v_fmac_f32_e32 v5, v12, v47
	s_waitcnt lgkmcnt(4)
	v_fmac_f32_e32 v5, v14, v58
	v_fmac_f32_e32 v5, v16, v59
	s_waitcnt lgkmcnt(3)
	v_fmac_f32_e32 v5, v34, v60
	v_mov_b32_e32 v41, v42
	s_waitcnt lgkmcnt(2)
	v_mov_b32_e32 v68, v63
	s_waitcnt lgkmcnt(1)
	v_mov_b32_e32 v69, v64
	v_fmac_f32_e32 v5, v36, v61
	v_pk_mul_f32 v[46:47], v[40:41], v[68:69]
	v_fmac_f32_e32 v5, v38, v62
	v_mov_b32_e32 v66, v65
	v_add_f32_e32 v5, v5, v46
	s_waitcnt lgkmcnt(0)
	v_pk_mul_f32 v[64:65], v[44:45], v[66:67]
	v_add_f32_e32 v5, v5, v47
	v_add_f32_e32 v5, v5, v64
	v_add_f32_e32 v5, v5, v65
	ds_read2_b32 v[46:47], v11 offset0:208 offset1:212
	ds_read2_b32 v[58:59], v11 offset0:216 offset1:220
	ds_read2_b32 v[60:61], v11 offset0:224 offset1:228
	ds_read2_b32 v[62:63], v11 offset0:232 offset1:236
	ds_read2_b32 v[64:65], v11 offset0:240 offset1:244
	ds_read_b32 v67, v56 offset:32736
	s_nop 1
	v_add_f32_dpp v5, v5, v5 quad_perm:[1,0,3,2] row_mask:0xf bank_mask:0xf
	s_nop 1
	v_add_f32_dpp v5, v5, v5 quad_perm:[2,3,0,1] row_mask:0xf bank_mask:0xf
	v_sub_f32_e32 v5, 0, v5
	v_cndmask_b32_e64 v45, v45, v5, s[44:45]
	s_waitcnt lgkmcnt(5)
	v_fma_f32 v5, v46, v10, 0
	v_fmac_f32_e32 v5, v12, v47
	s_waitcnt lgkmcnt(4)
	v_fmac_f32_e32 v5, v14, v58
	v_fmac_f32_e32 v5, v16, v59
	s_waitcnt lgkmcnt(3)
	v_fmac_f32_e32 v5, v34, v60
	v_mov_b32_e32 v41, v42
	s_waitcnt lgkmcnt(2)
	v_mov_b32_e32 v68, v63
	s_waitcnt lgkmcnt(1)
	v_mov_b32_e32 v69, v64
	v_fmac_f32_e32 v5, v36, v61
	v_pk_mul_f32 v[46:47], v[40:41], v[68:69]
	v_fmac_f32_e32 v5, v38, v62
	v_mov_b32_e32 v66, v65
	v_add_f32_e32 v5, v5, v46
	s_waitcnt lgkmcnt(0)
	v_pk_mul_f32 v[64:65], v[44:45], v[66:67]
	v_add_f32_e32 v5, v5, v47
	v_add_f32_e32 v5, v5, v64
	v_add_f32_e32 v5, v5, v65
	ds_read2_b32 v[58:59], v9 offset0:16 offset1:20
	ds_read2_b32 v[60:61], v9 offset0:24 offset1:28
	ds_read2_b32 v[62:63], v9 offset0:32 offset1:36
	ds_read2_b32 v[64:65], v9 offset0:40 offset1:44
	ds_read2_b32 v[66:67], v9 offset0:48 offset1:52
	ds_read_b32 v57, v56 offset:32992
	s_nop 1
	v_add_f32_dpp v5, v5, v5 quad_perm:[1,0,3,2] row_mask:0xf bank_mask:0xf
	s_nop 1
	v_add_f32_dpp v5, v5, v5 quad_perm:[2,3,0,1] row_mask:0xf bank_mask:0xf
	v_sub_f32_e32 v5, 0, v5
	v_cndmask_b32_e32 v46, v45, v5, vcc
	s_waitcnt lgkmcnt(5)
	v_fma_f32 v5, v58, v10, 0
	v_fmac_f32_e32 v5, v12, v59
	s_waitcnt lgkmcnt(4)
	v_fmac_f32_e32 v5, v14, v60
	v_fmac_f32_e32 v5, v16, v61
	s_waitcnt lgkmcnt(3)
	v_fmac_f32_e32 v5, v34, v62
	v_mov_b32_e32 v41, v42
	s_waitcnt lgkmcnt(2)
	v_mov_b32_e32 v68, v65
	s_waitcnt lgkmcnt(1)
	v_mov_b32_e32 v69, v66
	v_fmac_f32_e32 v5, v36, v63
	v_pk_mul_f32 v[58:59], v[40:41], v[68:69]
	v_fmac_f32_e32 v5, v38, v64
	v_mov_b32_e32 v45, v46
	v_mov_b32_e32 v56, v67
	v_add_f32_e32 v5, v5, v58
	s_waitcnt lgkmcnt(0)
; #define LAS __attribute__((address_space(3)))
; template <int W> __device__ __forceinline__ void dn_solve(const LAS float* Mf, float (&t)[16], int lane) {
;     const int j = 16 * W + (lane >> 2), q = lane & 3;
; #pragma unroll
;     for (int s = 0; s < 16; ++s) t[s] = 0.f;
; #pragma unroll
;     for (int i = 16 * W; i < 64; ++i) {
;         float acc = 0.f;
; #pragma unroll
;         for (int s = 4 * W; s <= (i - 1) / 4 && i > 16 * W; ++s) acc += Mf[i * 64 + 4 * s + q] * t[s];
;         acc += __shfl_xor(acc, 1); acc += __shfl_xor(acc, 2);
;         const float val = (i == j ? 1.f : 0.f) - acc;
;         if (q == (i & 3)) t[i >> 2] = val;
;         asm volatile("" : "+v"(t[0]), "+v"(t[1]), "+v"(t[2]), "+v"(t[3]), "+v"(t[4]), "+v"(t[5]), "+v"(t[6]), "+v"(t[7]), "+v"(t[8]), "+v"(t[9]), "+v"(t[10]), "+v"(t[11]), "+v"(t[12]), "+v"(t[13]), "+v"(t[14]), "+v"(t[15]));
;     }
; }
	v_pk_mul_f32 v[56:57], v[44:45], v[56:57]
	v_add_f32_e32 v5, v5, v59
	v_add_f32_e32 v5, v5, v56
	v_add_f32_e32 v5, v5, v57
	ds_read2_b32 v[56:57], v9 offset0:80 offset1:84
	ds_read2_b32 v[58:59], v9 offset0:88 offset1:92
	ds_read2_b32 v[60:61], v9 offset0:96 offset1:100
	ds_read2_b32 v[62:63], v9 offset0:112 offset1:116
	ds_read2_b32 v[64:65], v9 offset0:120 offset1:124
	ds_read2_b32 v[66:67], v9 offset0:104 offset1:108
	s_nop 1
	v_add_f32_dpp v5, v5, v5 quad_perm:[1,0,3,2] row_mask:0xf bank_mask:0xf
	s_nop 1
	v_add_f32_dpp v5, v5, v5 quad_perm:[2,3,0,1] row_mask:0xf bank_mask:0xf
	v_sub_f32_e32 v5, 0, v5
	v_cndmask_b32_e64 v47, v3, v5, s[42:43]
	s_waitcnt lgkmcnt(5)
	v_fma_f32 v3, v56, v10, 0
	v_fmac_f32_e32 v3, v12, v57
	s_waitcnt lgkmcnt(4)
	v_fmac_f32_e32 v3, v14, v58
	v_fmac_f32_e32 v3, v16, v59
	s_waitcnt lgkmcnt(3)
	v_fmac_f32_e32 v3, v34, v60
	v_fmac_f32_e32 v3, v36, v61
	v_mov_b32_e32 v43, v44
	s_waitcnt lgkmcnt(0)
	v_fmac_f32_e32 v3, v38, v66
	v_pk_mul_f32 v[62:63], v[42:43], v[62:63]
	v_fmac_f32_e32 v3, v40, v67
	v_add_f32_e32 v3, v3, v62
	v_pk_mul_f32 v[64:65], v[46:47], v[64:65]
	v_add_f32_e32 v3, v3, v63
	v_add_f32_e32 v3, v3, v64
	v_add_f32_e32 v3, v3, v65
	ds_read2_b32 v[56:57], v9 offset0:144 offset1:148
	ds_read2_b32 v[58:59], v9 offset0:152 offset1:156
	ds_read2_b32 v[60:61], v9 offset0:160 offset1:164
	ds_read2_b32 v[62:63], v9 offset0:176 offset1:180
	ds_read2_b32 v[64:65], v9 offset0:184 offset1:188
	ds_read2_b32 v[66:67], v9 offset0:168 offset1:172
	s_nop 1
	v_add_f32_dpp v3, v3, v3 quad_perm:[1,0,3,2] row_mask:0xf bank_mask:0xf
	s_nop 1
	v_add_f32_dpp v3, v3, v3 quad_perm:[2,3,0,1] row_mask:0xf bank_mask:0xf
	v_sub_f32_e32 v3, 0, v3
	v_cndmask_b32_e64 v47, v47, v3, s[46:47]
	s_waitcnt lgkmcnt(5)
	v_fma_f32 v3, v56, v10, 0
	v_fmac_f32_e32 v3, v12, v57
	s_waitcnt lgkmcnt(4)
	v_fmac_f32_e32 v3, v14, v58
	v_fmac_f32_e32 v3, v16, v59
	s_waitcnt lgkmcnt(3)
	v_fmac_f32_e32 v3, v34, v60
	v_fmac_f32_e32 v3, v36, v61
	v_mov_b32_e32 v43, v44
	s_waitcnt lgkmcnt(0)
	v_fmac_f32_e32 v3, v38, v66
	v_pk_mul_f32 v[62:63], v[42:43], v[62:63]
	v_fmac_f32_e32 v3, v40, v67
	v_add_f32_e32 v3, v3, v62
	v_pk_mul_f32 v[64:65], v[46:47], v[64:65]
	v_add_f32_e32 v3, v3, v63
	v_add_f32_e32 v3, v3, v64
	v_add_f32_e32 v3, v3, v65
	ds_read2_b32 v[56:57], v9 offset0:208 offset1:212
	ds_read2_b32 v[58:59], v9 offset0:216 offset1:220
	ds_read2_b32 v[60:61], v9 offset0:224 offset1:228
	ds_read2_b32 v[62:63], v9 offset0:232 offset1:236
	ds_read2_b32 v[64:65], v9 offset0:240 offset1:244
	ds_read2_b32 v[66:67], v9 offset0:248 offset1:252
	s_nop 1
	v_add_f32_dpp v3, v3, v3 quad_perm:[1,0,3,2] row_mask:0xf bank_mask:0xf
	s_nop 1
	v_add_f32_dpp v3, v3, v3 quad_perm:[2,3,0,1] row_mask:0xf bank_mask:0xf
	v_sub_f32_e32 v3, 0, v3
	v_cndmask_b32_e64 v47, v47, v3, s[44:45]
	s_waitcnt lgkmcnt(5)
	v_fma_f32 v3, v56, v10, 0
	v_fmac_f32_e32 v3, v12, v57
	v_mov_b32_e32 v35, v36
	s_waitcnt lgkmcnt(4)
	v_fmac_f32_e32 v3, v14, v58
	s_waitcnt lgkmcnt(3)
	v_pk_mul_f32 v[60:61], v[34:35], v[60:61]
	v_fmac_f32_e32 v3, v16, v59
	v_mov_b32_e32 v39, v40
	v_add_f32_e32 v3, v3, v60
	s_waitcnt lgkmcnt(2)
	v_pk_mul_f32 v[62:63], v[38:39], v[62:63]
	v_add_f32_e32 v3, v3, v61
	v_mov_b32_e32 v43, v44
	v_add_f32_e32 v3, v3, v62
	s_waitcnt lgkmcnt(1)
	v_pk_mul_f32 v[64:65], v[42:43], v[64:65]
	v_add_f32_e32 v3, v3, v63
	v_add_f32_e32 v3, v3, v64
	v_add_f32_e32 v3, v3, v65
	s_waitcnt lgkmcnt(0)
	v_pk_mul_f32 v[56:57], v[46:47], v[66:67]
	s_nop 0
	v_add_f32_e32 v3, v3, v56
	v_add_f32_e32 v3, v3, v57
	s_nop 1
	v_add_f32_dpp v3, v3, v3 quad_perm:[1,0,3,2] row_mask:0xf bank_mask:0xf
	s_nop 1
	v_add_f32_dpp v3, v3, v3 quad_perm:[2,3,0,1] row_mask:0xf bank_mask:0xf
	v_sub_f32_e32 v3, 0, v3
	v_cndmask_b32_e32 v3, v47, v3, vcc

; __device__ __forceinline__ bf16_t f2bf(float f) { return (bf16_t)(cvtpk_s(f, 0.f) & 0xffffu); }
; __device__ __forceinline__ float wave_sum(float v) {
; #pragma unroll
;     for (int o = 1; o < 64; o <<= 1) v += __shfl_xor(v, o);
;     return v;
; }
; __global__ void __launch_bounds__(512, 2) mega(Args args) {
;     ...
;                 for (int q = 0; q < 2; ++q) {
;                     if (q == 1 && rowa + NGW >= MROWS) break;
;                     const int row = rws[q];
;                     const bool lat = row < NLAT; const int b = lat ? row / SEQ : (row - NLAT) / CTXL; const int tpos = lat ? row % SEQ : (row - NLAT) % CTXL;
;                     float cs = 1.f, sn = 0.f;
;                     if (lat) { const float pos = (float)(hf == 0 ? tpos / 64 : tpos % 64); const float ang = pos * inv_freq; sn = sinf(ang); cs = cosf(ang); }
;                     const int kpos = lat ? tpos : SEQ + tpos;
; #pragma unroll
;                     for (int hd = 0; hd < 10; ++hd) {
;                         const float a1 = x1[q][hd], a2 = x2[q][hd];
;                         const float rinv = rsqrtf(wave_sum(a1 * a1 + a2 * a2) * (1.f / 128.f) + EPS);
;                         const float y1 = a1 * rinv * (hd < 8 ? gq1 : gk1), y2 = a2 * rinv * (hd < 8 ? gq2 : gk2);
;                         const float o1 = y1 * cs - y2 * sn, o2 = y1 * sn + y2 * cs;
;                         bf16_t* dst = hd < 8 ? QR + (size_t)row * 1024 + hd * 128 : KR + ((size_t)(b * 2 + (hd - 8)) * SKV + kpos) * 128;
;                         dst[e1] = f2bf(o1); dst[e2] = f2bf(o2);
;                     }
.LBB0_199:
	s_waitcnt vmcnt(46)
	v_lshlrev_b32_e32 v35, 16, v33
	v_lshlrev_b32_e32 v34, 16, v31
	s_waitcnt vmcnt(44)
	v_lshlrev_b32_e32 v33, 16, v32
	v_lshlrev_b32_e32 v32, 16, v30
	s_waitcnt vmcnt(41)
	v_lshlrev_b32_e32 v28, 16, v52
	s_waitcnt vmcnt(39)
	v_lshlrev_b32_e32 v26, 16, v53
	v_pk_mul_f32 v[16:17], v[34:35], v[34:35]
	v_pk_mul_f32 v[52:53], v[32:33], v[32:33]
	s_waitcnt vmcnt(37)
	v_lshlrev_b32_e32 v24, 16, v54
	s_waitcnt vmcnt(35)
	v_lshlrev_b32_e32 v20, 16, v55
	v_mov_b32_e32 v54, v52
	v_mov_b32_e32 v55, v16
	v_mov_b32_e32 v16, v53
	v_pk_add_f32 v[16:17], v[54:55], v[16:17]
	s_add_i32 s19, s47, 0x4000
	s_and_b64 s[0:1], exec, s[56:57]
	s_cselect_b32 s19, s47, s19
	s_lshl_b64 s[0:1], s[54:55], 11
	s_waitcnt lgkmcnt(0)
	s_nop 1
	v_add_f32_dpp v16, v16, v16 quad_perm:[1,0,3,2] row_mask:0xf bank_mask:0xf
	v_add_f32_dpp v17, v17, v17 quad_perm:[1,0,3,2] row_mask:0xf bank_mask:0xf
	v_lshl_add_u64 v[22:23], v[10:11], 0, s[0:1]
	s_mov_b32 s0, 0x358637bd
	s_brev_b32 s54, 60
	v_lshlrev_b32_e32 v30, 16, v51
	s_waitcnt lgkmcnt(0)
	s_nop 1
	v_add_f32_dpp v16, v16, v16 quad_perm:[2,3,0,1] row_mask:0xf bank_mask:0xf
	v_add_f32_dpp v17, v17, v17 quad_perm:[2,3,0,1] row_mask:0xf bank_mask:0xf
	v_lshlrev_b32_e32 v31, 16, v59
	v_lshlrev_b32_e32 v29, 16, v60
	v_lshlrev_b32_e32 v27, 16, v61
	v_lshlrev_b32_e32 v25, 16, v62
	s_waitcnt lgkmcnt(0)
	s_nop 1
	v_add_f32_dpp v16, v16, v16 row_half_mirror row_mask:0xf bank_mask:0xf
	v_add_f32_dpp v17, v17, v17 row_half_mirror row_mask:0xf bank_mask:0xf
	s_waitcnt vmcnt(34)
	v_lshlrev_b32_e32 v21, 16, v63
	s_waitcnt vmcnt(32)
	v_lshlrev_b32_e32 v19, 16, v64
	v_lshlrev_b32_e32 v18, 16, v56
	s_waitcnt vmcnt(30)
	v_lshlrev_b32_e32 v15, 16, v65
	s_waitcnt lgkmcnt(0)
	s_nop 1
	v_add_f32_dpp v16, v16, v16 row_mirror row_mask:0xf bank_mask:0xf
	v_add_f32_dpp v17, v17, v17 row_mirror row_mask:0xf bank_mask:0xf
	ds_bpermute_b32 v53, v45, v17
	ds_bpermute_b32 v52, v45, v16
	v_lshlrev_b32_e32 v14, 16, v57
	s_waitcnt vmcnt(28)
	v_lshlrev_b32_e32 v13, 16, v66
	v_lshlrev_b32_e32 v12, 16, v58
	s_lshl_b32 s45, s18, 1
	s_waitcnt lgkmcnt(0)
	v_pk_add_f32 v[16:17], v[16:17], v[52:53]
	ds_bpermute_b32 v53, v46, v17
	ds_bpermute_b32 v52, v46, v16
	s_ashr_i32 s44, s19, 31
	s_waitcnt lgkmcnt(0)
	v_pk_add_f32 v[52:53], v[16:17], v[52:53]
	v_mov_b64_e32 v[16:17], s[0:1]
	v_pk_fma_f32 v[52:53], v[52:53], s[54:55], v[16:17] op_sel_hi:[1,0,0]
	s_nop 0
	v_mul_f32_e32 v51, 0x4b800000, v53
	v_cmp_gt_f32_e64 s[0:1], s39, v53
	v_cmp_gt_f32_e32 vcc, s39, v52
	s_nop 0
	v_cndmask_b32_e64 v51, v53, v51, s[0:1]
	v_rsq_f32_e32 v51, v51
	s_nop 0
	v_mul_f32_e32 v53, 0x45800000, v51
	v_cndmask_b32_e64 v51, v51, v53, s[0:1]
	v_mul_f32_e32 v35, v51, v35
	v_mul_f32_e32 v34, v51, v34
	v_mul_f32_e32 v35, v37, v35
	v_mul_f32_e32 v34, v36, v34
	v_mul_f32_e32 v51, v0, v35
	v_fma_f32 v51, v67, v34, -v51
	v_mul_f32_e32 v35, v67, v35
	v_fmac_f32_e32 v35, v0, v34
	v_cvt_pk_bf16_f32 v34, v51, s0
	global_store_short v[22:23], v34, off
	v_cvt_pk_bf16_f32 v34, v35, s0
	global_store_short v[22:23], v34, off offset:64
	v_mul_f32_e32 v34, 0x4b800000, v52
	v_cndmask_b32_e32 v34, v52, v34, vcc
	v_rsq_f32_e32 v34, v34
	s_nop 0
	v_mul_f32_e32 v35, 0x45800000, v34
	v_cndmask_b32_e32 v34, v34, v35, vcc
	v_mul_f32_e32 v33, v34, v33
	v_mul_f32_e32 v32, v34, v32
	v_mul_f32_e32 v33, v37, v33
	v_mul_f32_e32 v32, v36, v32
	v_mul_f32_e32 v34, v0, v33
	v_fma_f32 v34, v67, v32, -v34
	v_mul_f32_e32 v33, v67, v33
	v_fmac_f32_e32 v33, v0, v32
	v_cvt_pk_bf16_f32 v32, v34, s0
	global_store_short v[22:23], v32, off offset:256
	v_cvt_pk_bf16_f32 v32, v33, s0
	global_store_short v[22:23], v32, off offset:320
	v_pk_mul_f32 v[32:33], v[30:31], v[30:31]
	v_pk_mul_f32 v[34:35], v[28:29], v[28:29]
	v_mov_b32_e32 v53, v32
	v_mov_b32_e32 v52, v34
	v_mov_b32_e32 v32, v35
	v_pk_add_f32 v[32:33], v[52:53], v[32:33]
	s_waitcnt lgkmcnt(0)
	s_nop 1
	v_add_f32_dpp v32, v32, v32 quad_perm:[1,0,3,2] row_mask:0xf bank_mask:0xf
	v_add_f32_dpp v33, v33, v33 quad_perm:[1,0,3,2] row_mask:0xf bank_mask:0xf
	s_waitcnt lgkmcnt(0)
	s_nop 1
	v_add_f32_dpp v32, v32, v32 quad_perm:[2,3,0,1] row_mask:0xf bank_mask:0xf
	v_add_f32_dpp v33, v33, v33 quad_perm:[2,3,0,1] row_mask:0xf bank_mask:0xf
	s_waitcnt lgkmcnt(0)
	s_nop 1
	v_add_f32_dpp v32, v32, v32 row_half_mirror row_mask:0xf bank_mask:0xf
	v_add_f32_dpp v33, v33, v33 row_half_mirror row_mask:0xf bank_mask:0xf
	s_waitcnt lgkmcnt(0)
	s_nop 1
	v_add_f32_dpp v32, v32, v32 row_mirror row_mask:0xf bank_mask:0xf
	v_add_f32_dpp v33, v33, v33 row_mirror row_mask:0xf bank_mask:0xf
	ds_bpermute_b32 v35, v45, v33
	ds_bpermute_b32 v34, v45, v32
	s_waitcnt lgkmcnt(0)
	v_pk_add_f32 v[32:33], v[32:33], v[34:35]
	ds_bpermute_b32 v35, v46, v33
	ds_bpermute_b32 v34, v46, v32
	s_waitcnt lgkmcnt(0)
	v_pk_add_f32 v[32:33], v[32:33], v[34:35]
	s_nop 0
	v_pk_fma_f32 v[32:33], v[32:33], s[54:55], v[16:17] op_sel_hi:[1,0,0]
	s_nop 0
	v_mul_f32_e32 v34, 0x4b800000, v33
	v_cmp_gt_f32_e64 s[0:1], s39, v33
	v_cmp_gt_f32_e32 vcc, s39, v32
	s_nop 0
	v_cndmask_b32_e64 v33, v33, v34, s[0:1]
	v_rsq_f32_e32 v33, v33
	s_nop 0
	v_mul_f32_e32 v34, 0x45800000, v33
	v_cndmask_b32_e64 v33, v33, v34, s[0:1]
	v_mul_f32_e32 v31, v33, v31
	v_mul_f32_e32 v30, v33, v30
	v_mul_f32_e32 v31, v37, v31
	v_mul_f32_e32 v30, v36, v30
	v_mul_f32_e32 v33, v0, v31
	v_fma_f32 v33, v67, v30, -v33
	v_mul_f32_e32 v31, v67, v31
	v_fmac_f32_e32 v31, v0, v30
	v_cvt_pk_bf16_f32 v30, v33, s0
	global_store_short v[22:23], v30, off offset:512
	v_cvt_pk_bf16_f32 v30, v31, s0
	global_store_short v[22:23], v30, off offset:576
	v_mul_f32_e32 v30, 0x4b800000, v32
	v_cndmask_b32_e32 v30, v32, v30, vcc
	v_rsq_f32_e32 v30, v30
	s_nop 0
	v_mul_f32_e32 v31, 0x45800000, v30
	v_cndmask_b32_e32 v30, v30, v31, vcc
	v_mul_f32_e32 v29, v30, v29
	v_mul_f32_e32 v28, v30, v28
	v_mul_f32_e32 v29, v37, v29
	v_mul_f32_e32 v28, v36, v28
	v_mul_f32_e32 v30, v0, v29
	v_fma_f32 v30, v67, v28, -v30
	v_mul_f32_e32 v29, v67, v29
	v_fmac_f32_e32 v29, v0, v28
	v_cvt_pk_bf16_f32 v28, v30, s0
	global_store_short v[22:23], v28, off offset:768
	v_cvt_pk_bf16_f32 v28, v29, s0
	global_store_short v[22:23], v28, off offset:832
	v_pk_mul_f32 v[28:29], v[26:27], v[26:27]
	v_pk_mul_f32 v[30:31], v[24:25], v[24:25]
	v_mov_b32_e32 v33, v28
	v_mov_b32_e32 v32, v30
	v_mov_b32_e32 v28, v31
	v_pk_add_f32 v[28:29], v[32:33], v[28:29]
	s_waitcnt lgkmcnt(0)
; __device__ __forceinline__ bf16_t f2bf(float f) { return (bf16_t)(cvtpk_s(f, 0.f) & 0xffffu); }
; __device__ __forceinline__ float wave_sum(float v) {
; #pragma unroll
;     for (int o = 1; o < 64; o <<= 1) v += __shfl_xor(v, o);
;     return v;
; }
; __global__ void __launch_bounds__(512, 2) mega(Args args) {
;     ...
; #pragma unroll
;                     for (int hd = 0; hd < 10; ++hd) {
;                         const float a1 = x1[q][hd], a2 = x2[q][hd];
;                         const float rinv = rsqrtf(wave_sum(a1 * a1 + a2 * a2) * (1.f / 128.f) + EPS);
;                         const float y1 = a1 * rinv * (hd < 8 ? gq1 : gk1), y2 = a2 * rinv * (hd < 8 ? gq2 : gk2);
;                         const float o1 = y1 * cs - y2 * sn, o2 = y1 * sn + y2 * cs;
;                         bf16_t* dst = hd < 8 ? QR + (size_t)row * 1024 + hd * 128 : KR + ((size_t)(b * 2 + (hd - 8)) * SKV + kpos) * 128;
;                         dst[e1] = f2bf(o1); dst[e2] = f2bf(o2);
;                     }
	s_nop 1
	v_add_f32_dpp v28, v28, v28 quad_perm:[1,0,3,2] row_mask:0xf bank_mask:0xf
	v_add_f32_dpp v29, v29, v29 quad_perm:[1,0,3,2] row_mask:0xf bank_mask:0xf
	s_waitcnt lgkmcnt(0)
	s_nop 1
	v_add_f32_dpp v28, v28, v28 quad_perm:[2,3,0,1] row_mask:0xf bank_mask:0xf
	v_add_f32_dpp v29, v29, v29 quad_perm:[2,3,0,1] row_mask:0xf bank_mask:0xf
	s_waitcnt lgkmcnt(0)
	s_nop 1
	v_add_f32_dpp v28, v28, v28 row_half_mirror row_mask:0xf bank_mask:0xf
	v_add_f32_dpp v29, v29, v29 row_half_mirror row_mask:0xf bank_mask:0xf
	s_waitcnt lgkmcnt(0)
	s_nop 1
	v_add_f32_dpp v28, v28, v28 row_mirror row_mask:0xf bank_mask:0xf
	v_add_f32_dpp v29, v29, v29 row_mirror row_mask:0xf bank_mask:0xf
	ds_bpermute_b32 v31, v45, v29
	ds_bpermute_b32 v30, v45, v28
	s_waitcnt lgkmcnt(0)
	v_pk_add_f32 v[28:29], v[28:29], v[30:31]
	ds_bpermute_b32 v31, v46, v29
	ds_bpermute_b32 v30, v46, v28
	s_waitcnt lgkmcnt(0)
	v_pk_add_f32 v[28:29], v[28:29], v[30:31]
	s_nop 0
	v_pk_fma_f32 v[28:29], v[28:29], s[54:55], v[16:17] op_sel_hi:[1,0,0]
	s_nop 0
	v_mul_f32_e32 v30, 0x4b800000, v29
	v_cmp_gt_f32_e64 s[0:1], s39, v29
	v_cmp_gt_f32_e32 vcc, s39, v28
	s_nop 0
	v_cndmask_b32_e64 v29, v29, v30, s[0:1]
	v_rsq_f32_e32 v29, v29
	s_nop 0
	v_mul_f32_e32 v30, 0x45800000, v29
	v_cndmask_b32_e64 v29, v29, v30, s[0:1]
	v_mul_f32_e32 v27, v29, v27
	v_mul_f32_e32 v26, v29, v26
	v_mul_f32_e32 v27, v37, v27
	v_mul_f32_e32 v26, v36, v26
	v_mul_f32_e32 v29, v0, v27
	v_fma_f32 v29, v67, v26, -v29
	v_mul_f32_e32 v27, v67, v27
	v_fmac_f32_e32 v27, v0, v26
	v_cvt_pk_bf16_f32 v26, v29, s0
	global_store_short v[22:23], v26, off offset:1024
	v_cvt_pk_bf16_f32 v26, v27, s0
	global_store_short v[22:23], v26, off offset:1088
	v_mul_f32_e32 v26, 0x4b800000, v28
	v_cndmask_b32_e32 v26, v28, v26, vcc
	v_rsq_f32_e32 v26, v26
	s_nop 0
	v_mul_f32_e32 v27, 0x45800000, v26
	v_cndmask_b32_e32 v26, v26, v27, vcc
	v_mul_f32_e32 v25, v26, v25
	v_mul_f32_e32 v24, v26, v24
	v_mul_f32_e32 v25, v37, v25
	v_mul_f32_e32 v24, v36, v24
	v_mul_f32_e32 v26, v0, v25
	v_fma_f32 v26, v67, v24, -v26
	v_mul_f32_e32 v25, v67, v25
	v_fmac_f32_e32 v25, v0, v24
	v_cvt_pk_bf16_f32 v24, v26, s0
	global_store_short v[22:23], v24, off offset:1280
	v_cvt_pk_bf16_f32 v24, v25, s0
	global_store_short v[22:23], v24, off offset:1344
	v_pk_mul_f32 v[24:25], v[20:21], v[20:21]
	v_pk_mul_f32 v[26:27], v[18:19], v[18:19]
	v_mov_b32_e32 v29, v24
	v_mov_b32_e32 v28, v26
	v_mov_b32_e32 v24, v27
	v_pk_add_f32 v[24:25], v[28:29], v[24:25]
	s_waitcnt lgkmcnt(0)
	s_nop 1
	v_add_f32_dpp v24, v24, v24 quad_perm:[1,0,3,2] row_mask:0xf bank_mask:0xf
	v_add_f32_dpp v25, v25, v25 quad_perm:[1,0,3,2] row_mask:0xf bank_mask:0xf
	s_waitcnt lgkmcnt(0)
	s_nop 1
	v_add_f32_dpp v24, v24, v24 quad_perm:[2,3,0,1] row_mask:0xf bank_mask:0xf
	v_add_f32_dpp v25, v25, v25 quad_perm:[2,3,0,1] row_mask:0xf bank_mask:0xf
	s_waitcnt lgkmcnt(0)
	s_nop 1
	v_add_f32_dpp v24, v24, v24 row_half_mirror row_mask:0xf bank_mask:0xf
	v_add_f32_dpp v25, v25, v25 row_half_mirror row_mask:0xf bank_mask:0xf
	s_waitcnt lgkmcnt(0)
	s_nop 1
	v_add_f32_dpp v24, v24, v24 row_mirror row_mask:0xf bank_mask:0xf
	v_add_f32_dpp v25, v25, v25 row_mirror row_mask:0xf bank_mask:0xf
	ds_bpermute_b32 v27, v45, v25
	ds_bpermute_b32 v26, v45, v24
	s_waitcnt lgkmcnt(0)
	v_pk_add_f32 v[24:25], v[24:25], v[26:27]
	ds_bpermute_b32 v27, v46, v25
	ds_bpermute_b32 v26, v46, v24
	s_waitcnt lgkmcnt(0)
; __device__ __forceinline__ bf16_t f2bf(float f) { return (bf16_t)(cvtpk_s(f, 0.f) & 0xffffu); }
; __device__ __forceinline__ float wave_sum(float v) {
; #pragma unroll
;     for (int o = 1; o < 64; o <<= 1) v += __shfl_xor(v, o);
;     return v;
; }
; __global__ void __launch_bounds__(512, 2) mega(Args args) {
;     ...
; #pragma unroll
;                     for (int hd = 0; hd < 10; ++hd) {
;                         const float a1 = x1[q][hd], a2 = x2[q][hd];
;                         const float rinv = rsqrtf(wave_sum(a1 * a1 + a2 * a2) * (1.f / 128.f) + EPS);
;                         const float y1 = a1 * rinv * (hd < 8 ? gq1 : gk1), y2 = a2 * rinv * (hd < 8 ? gq2 : gk2);
;                         const float o1 = y1 * cs - y2 * sn, o2 = y1 * sn + y2 * cs;
;                         bf16_t* dst = hd < 8 ? QR + (size_t)row * 1024 + hd * 128 : KR + ((size_t)(b * 2 + (hd - 8)) * SKV + kpos) * 128;
;                         dst[e1] = f2bf(o1); dst[e2] = f2bf(o2);
;                     }
; #pragma unroll
;                     for (int kv = 0; kv < 2; ++kv) { bf16_t* dst = VR + ((size_t)(b * 2 + kv) * SKV + kpos) * 128; dst[e1] = va[q][2 * kv]; dst[e2] = va[q][2 * kv + 1]; }
	v_pk_add_f32 v[24:25], v[24:25], v[26:27]
	s_nop 0
	v_pk_fma_f32 v[24:25], v[24:25], s[54:55], v[16:17] op_sel_hi:[1,0,0]
	s_nop 0
	v_mul_f32_e32 v26, 0x4b800000, v25
	v_cmp_gt_f32_e64 s[0:1], s39, v25
	v_cmp_gt_f32_e32 vcc, s39, v24
	s_nop 0
	v_cndmask_b32_e64 v25, v25, v26, s[0:1]
	v_rsq_f32_e32 v25, v25
	s_nop 0
	v_mul_f32_e32 v26, 0x45800000, v25
	v_cndmask_b32_e64 v25, v25, v26, s[0:1]
	v_mul_f32_e32 v21, v25, v21
	v_mul_f32_e32 v20, v25, v20
	v_mul_f32_e32 v21, v37, v21
	v_mul_f32_e32 v20, v36, v20
	v_mul_f32_e32 v25, v0, v21
	v_fma_f32 v25, v67, v20, -v25
	v_mul_f32_e32 v21, v67, v21
	v_fmac_f32_e32 v21, v0, v20
	v_cvt_pk_bf16_f32 v20, v25, s0
	global_store_short v[22:23], v20, off offset:1536
	v_cvt_pk_bf16_f32 v20, v21, s0
	global_store_short v[22:23], v20, off offset:1600
	v_mul_f32_e32 v20, 0x4b800000, v24
	v_cndmask_b32_e32 v20, v24, v20, vcc
	v_rsq_f32_e32 v20, v20
	s_mul_hi_i32 s1, s45, 0x4100
	v_mul_f32_e32 v21, 0x45800000, v20
	v_cndmask_b32_e32 v20, v20, v21, vcc
	v_mul_f32_e32 v19, v20, v19
	v_mul_f32_e32 v18, v20, v18
	v_mul_f32_e32 v19, v37, v19
	v_mul_f32_e32 v18, v36, v18
	v_mul_f32_e32 v20, v0, v19
	v_fma_f32 v20, v67, v18, -v20
	v_mul_f32_e32 v19, v67, v19
	v_fmac_f32_e32 v19, v0, v18
	v_cvt_pk_bf16_f32 v18, v20, s0
	global_store_short v[22:23], v18, off offset:1792
	v_cvt_pk_bf16_f32 v18, v19, s0
	global_store_short v[22:23], v18, off offset:1856
	v_pk_mul_f32 v[18:19], v[14:15], v[14:15]
	v_pk_mul_f32 v[22:23], v[12:13], v[12:13]
	v_mov_b32_e32 v25, v18
	v_mov_b32_e32 v24, v22
	v_mov_b32_e32 v18, v23
	v_pk_add_f32 v[18:19], v[24:25], v[18:19]
	s_mul_i32 s0, s18, 0x8200
	s_add_u32 s0, s0, s19
	s_addc_u32 s1, s1, s44
	s_lshl_b64 s[42:43], s[0:1], 8
	s_waitcnt lgkmcnt(0)
	s_nop 1
	v_add_f32_dpp v18, v18, v18 quad_perm:[1,0,3,2] row_mask:0xf bank_mask:0xf
	v_add_f32_dpp v19, v19, v19 quad_perm:[1,0,3,2] row_mask:0xf bank_mask:0xf
	v_lshl_add_u64 v[20:21], v[6:7], 0, s[42:43]
	s_waitcnt lgkmcnt(0)
	s_nop 1
	v_add_f32_dpp v18, v18, v18 quad_perm:[2,3,0,1] row_mask:0xf bank_mask:0xf
	v_add_f32_dpp v19, v19, v19 quad_perm:[2,3,0,1] row_mask:0xf bank_mask:0xf
	s_waitcnt lgkmcnt(0)
	s_nop 1
	v_add_f32_dpp v18, v18, v18 row_half_mirror row_mask:0xf bank_mask:0xf
	v_add_f32_dpp v19, v19, v19 row_half_mirror row_mask:0xf bank_mask:0xf
	s_waitcnt lgkmcnt(0)
	s_nop 1
	v_add_f32_dpp v18, v18, v18 row_mirror row_mask:0xf bank_mask:0xf
	v_add_f32_dpp v19, v19, v19 row_mirror row_mask:0xf bank_mask:0xf
	ds_bpermute_b32 v23, v45, v19
	ds_bpermute_b32 v22, v45, v18
	s_waitcnt lgkmcnt(0)
	v_pk_add_f32 v[18:19], v[18:19], v[22:23]
	ds_bpermute_b32 v23, v46, v19
	ds_bpermute_b32 v22, v46, v18
	s_waitcnt lgkmcnt(0)
	v_pk_add_f32 v[18:19], v[18:19], v[22:23]
	s_nop 0
	v_pk_fma_f32 v[16:17], v[18:19], s[54:55], v[16:17] op_sel_hi:[1,0,0]
	s_nop 0
	v_mul_f32_e32 v18, 0x4b800000, v17
	v_cmp_gt_f32_e64 s[0:1], s39, v17
	v_cmp_gt_f32_e32 vcc, s39, v16
	s_nop 0
	v_cndmask_b32_e64 v17, v17, v18, s[0:1]
	v_rsq_f32_e32 v17, v17
	s_nop 0
	v_mul_f32_e32 v18, 0x45800000, v17
	v_cndmask_b32_e64 v17, v17, v18, s[0:1]
	v_mul_f32_e32 v15, v17, v15
	v_mul_f32_e32 v14, v17, v14
	v_mul_f32_e32 v15, v38, v15
	v_mul_f32_e32 v14, v39, v14
	v_mul_f32_e32 v17, v0, v15
	v_fma_f32 v17, v67, v14, -v17
	v_mul_f32_e32 v15, v67, v15
	v_fmac_f32_e32 v15, v0, v14
	v_cvt_pk_bf16_f32 v14, v17, s0
	global_store_short v[20:21], v14, off
	v_cvt_pk_bf16_f32 v14, v15, s0
	global_store_short v[20:21], v14, off offset:64
	v_mul_f32_e32 v14, 0x4b800000, v16
	v_cndmask_b32_e32 v14, v16, v14, vcc
	v_rsq_f32_e32 v14, v14
	s_or_b32 s0, s45, 1
	s_mul_hi_i32 s1, s0, 0x4100
	s_mulk_i32 s0, 0x4100
	v_mul_f32_e32 v15, 0x45800000, v14
	v_cndmask_b32_e32 v14, v14, v15, vcc
	v_mul_f32_e32 v13, v14, v13
	v_mul_f32_e32 v12, v14, v12
	v_mul_f32_e32 v13, v38, v13
	s_add_u32 s0, s0, s19
	v_mul_f32_e32 v12, v39, v12
	v_mul_f32_e32 v14, v0, v13
	s_addc_u32 s1, s1, s44
	v_fma_f32 v14, v67, v12, -v14
	v_mul_f32_e32 v15, v67, v13
	s_lshl_b64 s[0:1], s[0:1], 8
	v_fmac_f32_e32 v15, v0, v12
	v_cvt_pk_bf16_f32 v0, v14, s0
	v_lshl_add_u64 v[12:13], v[6:7], 0, s[0:1]
	global_store_short v[12:13], v0, off
	v_cvt_pk_bf16_f32 v0, v15, s0
	global_store_short v[12:13], v0, off offset:64
	v_lshl_add_u64 v[12:13], v[8:9], 0, s[42:43]
	s_waitcnt vmcnt(47)
	global_store_short v[12:13], v49, off
	s_waitcnt vmcnt(47)
	global_store_short v[12:13], v50, off offset:64
	v_lshl_add_u64 v[12:13], v[8:9], 0, s[0:1]
	s_waitcnt vmcnt(47)
	global_store_short v[12:13], v47, off
	s_waitcnt vmcnt(47)
	global_store_short v[12:13], v48, off offset:64

; __device__ __forceinline__ bf16_t f2bf(float f) { return (bf16_t)(cvtpk_s(f, 0.f) & 0xffffu); }
; __device__ __forceinline__ float wave_sum(float v) {
; #pragma unroll
;     for (int o = 1; o < 64; o <<= 1) v += __shfl_xor(v, o);
;     return v;
; }
; __global__ void __launch_bounds__(512, 2) mega(Args args) {
;     ...
;                 for (int q = 0; q < 2; ++q) {
;                     if (q == 1 && rowa + NGW >= MROWS) break;
;                     const int row = rws[q];
;                     const bool lat = row < NLAT; const int b = lat ? row / SEQ : (row - NLAT) / CTXL; const int tpos = lat ? row % SEQ : (row - NLAT) % CTXL;
;                     float cs = 1.f, sn = 0.f;
;                     if (lat) { const float pos = (float)(hf == 0 ? tpos / 64 : tpos % 64); const float ang = pos * inv_freq; sn = sinf(ang); cs = cosf(ang); }
;                     const int kpos = lat ? tpos : SEQ + tpos;
; #pragma unroll
;                     for (int hd = 0; hd < 10; ++hd) {
;                         const float a1 = x1[q][hd], a2 = x2[q][hd];
;                         const float rinv = rsqrtf(wave_sum(a1 * a1 + a2 * a2) * (1.f / 128.f) + EPS);
;                         const float y1 = a1 * rinv * (hd < 8 ? gq1 : gk1), y2 = a2 * rinv * (hd < 8 ? gq2 : gk2);
;                         const float o1 = y1 * cs - y2 * sn, o2 = y1 * sn + y2 * cs;
;                         bf16_t* dst = hd < 8 ? QR + (size_t)row * 1024 + hd * 128 : KR + ((size_t)(b * 2 + (hd - 8)) * SKV + kpos) * 128;
;                         dst[e1] = f2bf(o1); dst[e2] = f2bf(o2);
;                     }
.LBB0_224:
	s_waitcnt vmcnt(46)
	v_lshlrev_b32_e32 v73, 16, v71
	v_lshlrev_b32_e32 v72, 16, v29
	s_waitcnt vmcnt(44)
	v_lshlrev_b32_e32 v71, 16, v70
	v_lshlrev_b32_e32 v70, 16, v27
	s_waitcnt vmcnt(42)
	v_lshlrev_b32_e32 v75, 16, v28
	s_waitcnt vmcnt(41)
	v_lshlrev_b32_e32 v28, 16, v22
	s_waitcnt vmcnt(38)
	v_lshlrev_b32_e32 v27, 16, v23
	v_pk_mul_f32 v[22:23], v[72:73], v[72:73]
	v_pk_mul_f32 v[76:77], v[70:71], v[70:71]
	v_mov_b32_e32 v79, v22
	v_mov_b32_e32 v78, v76
	v_mov_b32_e32 v22, v77
	v_pk_add_f32 v[76:77], v[78:79], v[22:23]
	ds_bpermute_b32 v79, v41, v77
	ds_bpermute_b32 v78, v41, v76
	v_lshlrev_b32_e32 v74, 16, v25
	s_waitcnt vmcnt(35)
	v_lshlrev_b32_e32 v22, 16, v17
	s_waitcnt vmcnt(32)
	v_lshlrev_b32_e32 v17, 16, v24
	v_lshlrev_b32_e32 v29, 16, v26
	s_waitcnt lgkmcnt(0)
	v_pk_add_f32 v[24:25], v[76:77], v[78:79]
	ds_bpermute_b32 v77, v42, v25
	ds_bpermute_b32 v76, v42, v24
	v_lshlrev_b32_e32 v26, 16, v20
	v_lshlrev_b32_e32 v20, 16, v16
	v_lshlrev_b32_e32 v23, 16, v19
	v_lshlrev_b32_e32 v16, 16, v13
	s_waitcnt vmcnt(28)
	v_lshlrev_b32_e32 v13, 16, v18
	s_waitcnt lgkmcnt(0)
	v_pk_add_f32 v[18:19], v[24:25], v[76:77]
	s_ashr_i32 s55, s54, 31
	s_add_i32 s42, s47, 0x4000
	s_and_b64 s[0:1], s[56:57], exec
	s_cselect_b32 s42, s47, s42
	s_waitcnt lgkmcnt(0)
	s_nop 1
	v_add_f32_dpp v18, v18, v18 row_half_mirror row_mask:0xf bank_mask:0xf
	v_add_f32_dpp v19, v19, v19 row_half_mirror row_mask:0xf bank_mask:0xf
	s_lshl_b32 s43, s18, 1
	s_ashr_i32 s44, s42, 31
	s_mul_i32 s0, s18, 0x8200
	s_mul_hi_i32 s1, s43, 0x4100
	s_waitcnt lgkmcnt(0)
	s_nop 1
	v_add_f32_dpp v18, v18, v18 row_mirror row_mask:0xf bank_mask:0xf
	v_add_f32_dpp v19, v19, v19 row_mirror row_mask:0xf bank_mask:0xf
	ds_bpermute_b32 v25, v45, v19
	ds_bpermute_b32 v24, v45, v18
	s_add_u32 s0, s0, s42
	s_addc_u32 s1, s1, s44
	s_or_b32 s18, s43, 1
	s_lshl_b64 s[0:1], s[0:1], 8
	s_waitcnt lgkmcnt(0)
	v_pk_add_f32 v[18:19], v[18:19], v[24:25]
	ds_bpermute_b32 v25, v46, v19
	ds_bpermute_b32 v24, v46, v18
	s_mul_hi_i32 s43, s18, 0x4100
	s_mulk_i32 s18, 0x4100
	s_add_u32 s42, s18, s42
	s_mov_b32 s18, 0x358637bd
	s_addc_u32 s43, s43, s44
	s_waitcnt lgkmcnt(0)
	v_pk_add_f32 v[24:25], v[18:19], v[24:25]
	v_mov_b64_e32 v[18:19], s[18:19]
	s_brev_b32 s44, 60
	v_pk_fma_f32 v[76:77], v[24:25], s[44:45], v[18:19] op_sel_hi:[1,0,0]
	s_mov_b32 s18, 0xd800000
	v_mul_f32_e32 v24, 0x4b800000, v77
	v_cmp_gt_f32_e32 vcc, s39, v77
	v_lshlrev_b32_e32 v21, 16, v21
	v_lshlrev_b32_e32 v15, 16, v15
	v_cndmask_b32_e32 v24, v77, v24, vcc
	v_rsq_f32_e32 v77, v24
	v_lshl_add_u64 v[24:25], s[48:49], 0, v[2:3]
	v_lshlrev_b32_e32 v14, 16, v14
	v_lshlrev_b32_e32 v12, 16, v12
	v_mul_f32_e32 v78, 0x45800000, v77
	v_cndmask_b32_e32 v77, v77, v78, vcc
	v_mul_f32_e32 v72, v77, v72
	v_mul_f32_e32 v82, v36, v72
	v_mul_f32_e32 v72, v77, v73
	v_mul_f32_e32 v77, v37, v72
	v_pk_mul_f32 v[72:73], v[74:75], v[74:75]
	v_pk_mul_f32 v[78:79], v[28:29], v[28:29]
	v_mov_b32_e32 v81, v72
	v_mov_b32_e32 v80, v78
	v_mov_b32_e32 v72, v79
	v_pk_add_f32 v[72:73], v[80:81], v[72:73]
	v_mul_f32_e32 v83, v0, v77
	v_fma_f32 v80, v69, v82, -v83
	v_mul_f32_e32 v77, v69, v77
	v_add_co_u32_e32 v24, vcc, s18, v24
	s_waitcnt lgkmcnt(0)
	s_nop 1
	v_add_f32_dpp v72, v72, v72 quad_perm:[1,0,3,2] row_mask:0xf bank_mask:0xf
	v_add_f32_dpp v73, v73, v73 quad_perm:[1,0,3,2] row_mask:0xf bank_mask:0xf
	v_fmac_f32_e32 v77, v0, v82
	v_cvt_pk_bf16_f32 v80, v80, s0
	v_addc_co_u32_e32 v25, vcc, 0, v25, vcc
	s_waitcnt lgkmcnt(0)
	s_nop 1
	v_add_f32_dpp v72, v72, v72 quad_perm:[2,3,0,1] row_mask:0xf bank_mask:0xf
	v_add_f32_dpp v73, v73, v73 quad_perm:[2,3,0,1] row_mask:0xf bank_mask:0xf
	global_store_short v[24:25], v80, off
	v_cvt_pk_bf16_f32 v80, v77, s0
	v_mul_f32_e32 v77, 0x4b800000, v76
	v_cmp_gt_f32_e32 vcc, s39, v76
	s_waitcnt lgkmcnt(0)
	s_nop 1
	v_add_f32_dpp v72, v72, v72 row_half_mirror row_mask:0xf bank_mask:0xf
	v_add_f32_dpp v73, v73, v73 row_half_mirror row_mask:0xf bank_mask:0xf
	global_store_short v[24:25], v80, off offset:64
	v_cndmask_b32_e32 v76, v76, v77, vcc
	v_rsq_f32_e32 v81, v76
	s_lshl_b64 s[42:43], s[42:43], 8
	v_mul_f32_e32 v78, 0x45800000, v81
	v_cndmask_b32_e32 v78, v81, v78, vcc
	v_mul_f32_e32 v70, v78, v70
	s_waitcnt lgkmcnt(0)
	s_nop 1
	v_add_f32_dpp v72, v72, v72 row_mirror row_mask:0xf bank_mask:0xf
	v_add_f32_dpp v73, v73, v73 row_mirror row_mask:0xf bank_mask:0xf
	ds_bpermute_b32 v77, v45, v73
	ds_bpermute_b32 v76, v45, v72
	v_mul_f32_e32 v79, v36, v70
	v_mul_f32_e32 v70, v78, v71
	v_mul_f32_e32 v78, v37, v70
	v_mul_f32_e32 v80, v0, v78
	s_waitcnt lgkmcnt(0)
	v_pk_add_f32 v[70:71], v[72:73], v[76:77]
	ds_bpermute_b32 v73, v46, v71
	ds_bpermute_b32 v72, v46, v70
	v_mul_f32_e32 v77, v69, v78
	v_fmac_f32_e32 v77, v0, v79
	v_fma_f32 v76, v69, v79, -v80
	v_cvt_pk_bf16_f32 v76, v76, s0
	s_waitcnt lgkmcnt(0)
	v_pk_add_f32 v[70:71], v[70:71], v[72:73]
	global_store_short v[24:25], v76, off offset:256
	v_pk_fma_f32 v[70:71], v[70:71], s[44:45], v[18:19] op_sel_hi:[1,0,0]
	s_cmp_gt_i32 s19, 0x81ff
	v_mul_f32_e32 v72, 0x4b800000, v71
	v_cmp_gt_f32_e32 vcc, s39, v71
	s_nop 1
	v_cndmask_b32_e32 v71, v71, v72, vcc
	v_rsq_f32_e32 v71, v71
	v_cvt_pk_bf16_f32 v72, v77, s0
	global_store_short v[24:25], v72, off offset:320
	v_mul_f32_e32 v72, 0x45800000, v71
	v_cndmask_b32_e32 v71, v71, v72, vcc
	v_mul_f32_e32 v72, v71, v74
	v_mul_f32_e32 v78, v36, v72
	v_mul_f32_e32 v71, v71, v75
	v_pk_mul_f32 v[72:73], v[26:27], v[26:27]
	v_pk_mul_f32 v[74:75], v[20:21], v[20:21]
	v_mov_b32_e32 v77, v72
	v_mov_b32_e32 v76, v74
	v_mov_b32_e32 v72, v75
	v_pk_add_f32 v[72:73], v[76:77], v[72:73]
	v_mul_f32_e32 v71, v37, v71
	v_mul_f32_e32 v76, v0, v71
	v_fma_f32 v76, v69, v78, -v76
	v_mul_f32_e32 v71, v69, v71
	s_waitcnt lgkmcnt(0)
; __device__ __forceinline__ bf16_t f2bf(float f) { return (bf16_t)(cvtpk_s(f, 0.f) & 0xffffu); }
; __device__ __forceinline__ float wave_sum(float v) {
; #pragma unroll
;     for (int o = 1; o < 64; o <<= 1) v += __shfl_xor(v, o);
;     return v;
; }
; __global__ void __launch_bounds__(512, 2) mega(Args args) {
;     ...
; #pragma unroll
;                     for (int hd = 0; hd < 10; ++hd) {
;                         const float a1 = x1[q][hd], a2 = x2[q][hd];
;                         const float rinv = rsqrtf(wave_sum(a1 * a1 + a2 * a2) * (1.f / 128.f) + EPS);
;                         const float y1 = a1 * rinv * (hd < 8 ? gq1 : gk1), y2 = a2 * rinv * (hd < 8 ? gq2 : gk2);
;                         const float o1 = y1 * cs - y2 * sn, o2 = y1 * sn + y2 * cs;
;                         bf16_t* dst = hd < 8 ? QR + (size_t)row * 1024 + hd * 128 : KR + ((size_t)(b * 2 + (hd - 8)) * SKV + kpos) * 128;
;                         dst[e1] = f2bf(o1); dst[e2] = f2bf(o2);
;                     }
	s_nop 1
	v_add_f32_dpp v72, v72, v72 quad_perm:[1,0,3,2] row_mask:0xf bank_mask:0xf
	v_add_f32_dpp v73, v73, v73 quad_perm:[1,0,3,2] row_mask:0xf bank_mask:0xf
	v_fmac_f32_e32 v71, v0, v78
	v_cvt_pk_bf16_f32 v76, v76, s0
	global_store_short v[24:25], v76, off offset:512
	v_cvt_pk_bf16_f32 v76, v71, s0
	s_waitcnt lgkmcnt(0)
	s_nop 1
	v_add_f32_dpp v72, v72, v72 quad_perm:[2,3,0,1] row_mask:0xf bank_mask:0xf
	v_add_f32_dpp v73, v73, v73 quad_perm:[2,3,0,1] row_mask:0xf bank_mask:0xf
	ds_bpermute_b32 v75, v43, v73
	ds_bpermute_b32 v74, v43, v72
	v_mul_f32_e32 v71, 0x4b800000, v70
	v_cmp_gt_f32_e32 vcc, s39, v70
	global_store_short v[24:25], v76, off offset:576
	s_nop 0
	v_cndmask_b32_e32 v70, v70, v71, vcc
	v_rsq_f32_e32 v77, v70
	s_waitcnt lgkmcnt(0)
	v_pk_add_f32 v[70:71], v[72:73], v[74:75]
	v_mul_f32_e32 v74, 0x45800000, v77
	v_cndmask_b32_e32 v74, v77, v74, vcc
	v_mul_f32_e32 v28, v74, v28
	v_mul_f32_e32 v75, v36, v28
	s_waitcnt lgkmcnt(0)
	s_nop 1
	v_add_f32_dpp v70, v70, v70 row_mirror row_mask:0xf bank_mask:0xf
	v_add_f32_dpp v71, v71, v71 row_mirror row_mask:0xf bank_mask:0xf
	ds_bpermute_b32 v73, v45, v71
	ds_bpermute_b32 v72, v45, v70
	v_mul_f32_e32 v28, v74, v29
	v_mul_f32_e32 v74, v37, v28
	v_mul_f32_e32 v76, v0, v74
	s_waitcnt lgkmcnt(0)
	v_pk_add_f32 v[28:29], v[70:71], v[72:73]
	ds_bpermute_b32 v71, v46, v29
	ds_bpermute_b32 v70, v46, v28
	v_mul_f32_e32 v73, v69, v74
	v_fmac_f32_e32 v73, v0, v75
	v_fma_f32 v72, v69, v75, -v76
	v_cvt_pk_bf16_f32 v72, v72, s0
	s_waitcnt lgkmcnt(0)
	v_pk_add_f32 v[28:29], v[28:29], v[70:71]
	global_store_short v[24:25], v72, off offset:768
	v_pk_fma_f32 v[28:29], v[28:29], s[44:45], v[18:19] op_sel_hi:[1,0,0]
	s_nop 0
	v_mul_f32_e32 v70, 0x4b800000, v29
	v_cmp_gt_f32_e32 vcc, s39, v29
	s_nop 1
	v_cndmask_b32_e32 v29, v29, v70, vcc
	v_rsq_f32_e32 v29, v29
	v_cvt_pk_bf16_f32 v70, v73, s0
	global_store_short v[24:25], v70, off offset:832
	v_mul_f32_e32 v70, 0x45800000, v29
	v_cndmask_b32_e32 v29, v29, v70, vcc
	v_mul_f32_e32 v26, v29, v26
	v_mul_f32_e32 v74, v36, v26
	v_mul_f32_e32 v29, v29, v27
	v_pk_mul_f32 v[26:27], v[22:23], v[22:23]
	v_pk_mul_f32 v[70:71], v[16:17], v[16:17]
	v_mov_b32_e32 v73, v26
	v_mov_b32_e32 v72, v70
	v_mov_b32_e32 v26, v71
	v_pk_add_f32 v[26:27], v[72:73], v[26:27]
	v_mul_f32_e32 v29, v37, v29
	v_mul_f32_e32 v72, v0, v29
	v_fma_f32 v72, v69, v74, -v72
	v_mul_f32_e32 v29, v69, v29
	s_waitcnt lgkmcnt(0)
	s_nop 1
	v_add_f32_dpp v26, v26, v26 quad_perm:[1,0,3,2] row_mask:0xf bank_mask:0xf
	v_add_f32_dpp v27, v27, v27 quad_perm:[1,0,3,2] row_mask:0xf bank_mask:0xf
	v_fmac_f32_e32 v29, v0, v74
	v_cvt_pk_bf16_f32 v72, v72, s0
	global_store_short v[24:25], v72, off offset:1024
	v_cvt_pk_bf16_f32 v72, v29, s0
	s_waitcnt lgkmcnt(0)
	s_nop 1
	v_add_f32_dpp v26, v26, v26 quad_perm:[2,3,0,1] row_mask:0xf bank_mask:0xf
	v_add_f32_dpp v27, v27, v27 quad_perm:[2,3,0,1] row_mask:0xf bank_mask:0xf
	v_mul_f32_e32 v29, 0x4b800000, v28
	v_cmp_gt_f32_e32 vcc, s39, v28
	global_store_short v[24:25], v72, off offset:1088
	s_waitcnt lgkmcnt(0)
	s_nop 1
	v_add_f32_dpp v26, v26, v26 row_half_mirror row_mask:0xf bank_mask:0xf
	v_add_f32_dpp v27, v27, v27 row_half_mirror row_mask:0xf bank_mask:0xf
	v_cndmask_b32_e32 v28, v28, v29, vcc
	v_rsq_f32_e32 v73, v28
	v_mul_f32_e32 v70, 0x45800000, v73
	v_cndmask_b32_e32 v70, v73, v70, vcc
	v_mul_f32_e32 v20, v70, v20
	s_waitcnt lgkmcnt(0)
	s_nop 1
	v_add_f32_dpp v26, v26, v26 row_mirror row_mask:0xf bank_mask:0xf
	v_add_f32_dpp v27, v27, v27 row_mirror row_mask:0xf bank_mask:0xf
	ds_bpermute_b32 v29, v45, v27
	ds_bpermute_b32 v28, v45, v26
	v_mul_f32_e32 v71, v36, v20
	v_mul_f32_e32 v20, v70, v21
	v_mul_f32_e32 v70, v37, v20
	v_mul_f32_e32 v72, v0, v70
	s_waitcnt lgkmcnt(0)
	v_pk_add_f32 v[20:21], v[26:27], v[28:29]
	ds_bpermute_b32 v27, v46, v21
	ds_bpermute_b32 v26, v46, v20
	v_mul_f32_e32 v29, v69, v70
	v_fmac_f32_e32 v29, v0, v71
	v_fma_f32 v28, v69, v71, -v72
	v_cvt_pk_bf16_f32 v28, v28, s0
	s_waitcnt lgkmcnt(0)
; __device__ __forceinline__ bf16_t f2bf(float f) { return (bf16_t)(cvtpk_s(f, 0.f) & 0xffffu); }
; __device__ __forceinline__ float wave_sum(float v) {
; #pragma unroll
;     for (int o = 1; o < 64; o <<= 1) v += __shfl_xor(v, o);
;     return v;
; }
; __global__ void __launch_bounds__(512, 2) mega(Args args) {
;     ...
; #pragma unroll
;                     for (int hd = 0; hd < 10; ++hd) {
;                         const float a1 = x1[q][hd], a2 = x2[q][hd];
;                         const float rinv = rsqrtf(wave_sum(a1 * a1 + a2 * a2) * (1.f / 128.f) + EPS);
;                         const float y1 = a1 * rinv * (hd < 8 ? gq1 : gk1), y2 = a2 * rinv * (hd < 8 ? gq2 : gk2);
;                         const float o1 = y1 * cs - y2 * sn, o2 = y1 * sn + y2 * cs;
;                         bf16_t* dst = hd < 8 ? QR + (size_t)row * 1024 + hd * 128 : KR + ((size_t)(b * 2 + (hd - 8)) * SKV + kpos) * 128;
;                         dst[e1] = f2bf(o1); dst[e2] = f2bf(o2);
;                     }
; #pragma unroll
;                     for (int kv = 0; kv < 2; ++kv) { bf16_t* dst = VR + ((size_t)(b * 2 + kv) * SKV + kpos) * 128; dst[e1] = va[q][2 * kv]; dst[e2] = va[q][2 * kv + 1]; }
	v_pk_add_f32 v[20:21], v[20:21], v[26:27]
	global_store_short v[24:25], v28, off offset:1280
	v_pk_fma_f32 v[20:21], v[20:21], s[44:45], v[18:19] op_sel_hi:[1,0,0]
	s_nop 0
	v_mul_f32_e32 v26, 0x4b800000, v21
	v_cmp_gt_f32_e32 vcc, s39, v21
	s_nop 1
	v_cndmask_b32_e32 v21, v21, v26, vcc
	v_rsq_f32_e32 v21, v21
	v_cvt_pk_bf16_f32 v26, v29, s0
	global_store_short v[24:25], v26, off offset:1344
	v_mul_f32_e32 v26, 0x45800000, v21
	v_cndmask_b32_e32 v21, v21, v26, vcc
	v_mul_f32_e32 v22, v21, v22
	v_mul_f32_e32 v70, v36, v22
	v_mul_f32_e32 v21, v21, v23
	v_pk_mul_f32 v[22:23], v[14:15], v[14:15]
	v_pk_mul_f32 v[26:27], v[12:13], v[12:13]
	v_mov_b32_e32 v29, v22
	v_mov_b32_e32 v28, v26
	v_mov_b32_e32 v22, v27
	v_pk_add_f32 v[22:23], v[28:29], v[22:23]
	v_mul_f32_e32 v21, v37, v21
	v_mul_f32_e32 v28, v0, v21
	v_mul_f32_e32 v21, v69, v21
	v_fmac_f32_e32 v21, v0, v70
	s_waitcnt lgkmcnt(0)
	s_nop 1
	v_add_f32_dpp v22, v22, v22 quad_perm:[1,0,3,2] row_mask:0xf bank_mask:0xf
	v_add_f32_dpp v23, v23, v23 quad_perm:[1,0,3,2] row_mask:0xf bank_mask:0xf
	v_cvt_pk_bf16_f32 v21, v21, s0
	v_fma_f32 v28, v69, v70, -v28
	global_store_short v[24:25], v21, off offset:1600
	v_mul_f32_e32 v21, 0x4b800000, v20
	s_waitcnt lgkmcnt(0)
	s_nop 1
	v_add_f32_dpp v22, v22, v22 quad_perm:[2,3,0,1] row_mask:0xf bank_mask:0xf
	v_add_f32_dpp v23, v23, v23 quad_perm:[2,3,0,1] row_mask:0xf bank_mask:0xf
	ds_bpermute_b32 v27, v43, v23
	ds_bpermute_b32 v26, v43, v22
	v_cmp_gt_f32_e32 vcc, s39, v20
	v_cvt_pk_bf16_f32 v28, v28, s0
	global_store_short v[24:25], v28, off offset:1536
	v_cndmask_b32_e32 v20, v20, v21, vcc
	v_rsq_f32_e32 v28, v20
	s_waitcnt lgkmcnt(0)
	v_pk_add_f32 v[20:21], v[22:23], v[26:27]
	v_mul_f32_e32 v26, 0x45800000, v28
	v_cndmask_b32_e32 v26, v28, v26, vcc
	v_mul_f32_e32 v16, v26, v16
	v_mul_f32_e32 v27, v36, v16
	s_waitcnt lgkmcnt(0)
	s_nop 1
	v_add_f32_dpp v20, v20, v20 row_mirror row_mask:0xf bank_mask:0xf
	v_add_f32_dpp v21, v21, v21 row_mirror row_mask:0xf bank_mask:0xf
	ds_bpermute_b32 v23, v45, v21
	ds_bpermute_b32 v22, v45, v20
	v_mul_f32_e32 v16, v26, v17
	v_mul_f32_e32 v26, v37, v16
	v_mul_f32_e32 v16, v0, v26
	v_fma_f32 v28, v69, v27, -v16
	s_waitcnt lgkmcnt(0)
	v_pk_add_f32 v[16:17], v[20:21], v[22:23]
	ds_bpermute_b32 v21, v46, v17
	ds_bpermute_b32 v20, v46, v16
	v_mul_f32_e32 v22, v69, v26
	v_fmac_f32_e32 v22, v0, v27
	v_cvt_pk_bf16_f32 v23, v28, s0
	global_store_short v[24:25], v23, off offset:1792
	s_waitcnt lgkmcnt(0)
	v_pk_add_f32 v[16:17], v[16:17], v[20:21]
	s_nop 0
	v_pk_fma_f32 v[16:17], v[16:17], s[44:45], v[18:19] op_sel_hi:[1,0,0]
	s_nop 0
	v_mul_f32_e32 v18, 0x4b800000, v17
	v_cmp_gt_f32_e32 vcc, s39, v17
	s_nop 1
	v_cndmask_b32_e32 v17, v17, v18, vcc
	v_rsq_f32_e32 v17, v17
	v_cvt_pk_bf16_f32 v18, v22, s0
	global_store_short v[24:25], v18, off offset:1856
	v_lshl_add_u64 v[18:19], v[6:7], 0, s[0:1]
	v_mul_f32_e32 v20, 0x45800000, v17
	v_cndmask_b32_e32 v17, v17, v20, vcc
	v_mul_f32_e32 v15, v17, v15
	v_mul_f32_e32 v14, v17, v14
	v_mul_f32_e32 v15, v38, v15
	v_mul_f32_e32 v14, v39, v14
	v_mul_f32_e32 v17, v0, v15
	v_fma_f32 v17, v69, v14, -v17
	v_mul_f32_e32 v15, v69, v15
	v_fmac_f32_e32 v15, v0, v14
	v_cvt_pk_bf16_f32 v14, v17, s0
	v_mul_f32_e32 v17, 0x4b800000, v16
	v_cmp_gt_f32_e32 vcc, s39, v16
	global_store_short v[18:19], v14, off
	v_cvt_pk_bf16_f32 v14, v15, s0
	v_cndmask_b32_e32 v16, v16, v17, vcc
	v_rsq_f32_e32 v16, v16
	global_store_short v[18:19], v14, off offset:64
	v_mul_f32_e32 v14, 0x45800000, v16
	v_cndmask_b32_e32 v14, v16, v14, vcc
	v_mul_f32_e32 v13, v14, v13
	v_mul_f32_e32 v12, v14, v12
	v_mul_f32_e32 v13, v38, v13
	v_mul_f32_e32 v12, v39, v12
	v_mul_f32_e32 v14, v0, v13
	v_fma_f32 v14, v69, v12, -v14
	v_mul_f32_e32 v15, v69, v13
	v_fmac_f32_e32 v15, v0, v12
	v_cvt_pk_bf16_f32 v0, v14, s0
	v_lshl_add_u64 v[12:13], v[6:7], 0, s[42:43]
	global_store_short v[12:13], v0, off
	v_cvt_pk_bf16_f32 v0, v15, s0
	global_store_short v[12:13], v0, off offset:64
	v_lshl_add_u64 v[12:13], v[8:9], 0, s[0:1]
	s_waitcnt vmcnt(47)
	global_store_short v[12:13], v67, off
	s_waitcnt vmcnt(47)
	global_store_short v[12:13], v68, off offset:64
	v_lshl_add_u64 v[12:13], v[8:9], 0, s[42:43]
	s_waitcnt vmcnt(47)
	global_store_short v[12:13], v34, off
	s_waitcnt vmcnt(47)
	global_store_short v[12:13], v35, off offset:64
	s_cbranch_scc1 .LBB0_200
	s_cmp_lt_i32 s19, 0x8000
	s_cselect_b64 s[56:57], -1, 0
	s_cmpk_gt_i32 s19, 0x7fff
	s_cselect_b64 s[0:1], -1, 0
	s_mov_b64 s[42:43], -1
	s_and_b64 vcc, exec, s[56:57]
	s_cbranch_vccnz .LBB0_240
	s_add_i32 s18, s19, 0xffff8000
	s_lshr_b32 s18, s18, 8
	s_cbranch_execz .LBB0_241

; __device__ __forceinline__ int opaque_tid() { int t = threadIdx.x; asm volatile("" : "+v"(t)); return t; }
; template <int VAR> __device__ __forceinline__ void dn_scan3(LAS unsigned char* lds, const bf16_t* P, const float* AB, const bf16_t* TP, bf16_t* OB) {
;     ...
;                 {
;                     int rb; bool f_; dn_step_rb(0, dir, b, rb, f_);
;                     const int lane = opaque_tid() & 63, r0 = lane >> 4, c8 = 8 * (lane & 15);
; #pragma unroll
;                     for (int v = 0; v < 16; ++v) { const int ip = r0 + 4 * v, i = dir ? 63 - ip : ip; v16[v] = *(const u32x4*)(P + (size_t)(rb * 64 + i) * 4096 + 2048 + vh * 128 + c8); }
;                     const bf16_t* tp = TP + (size_t)((rb * 16 + vh) * 2 + dir) * 3072;
; #pragma unroll
;                     for (int v = 0; v < 6; ++v) t6[v] = *(const u32x4*)(tp + (lane + 64 * v) * 8);
;                     const int tl = dir ? 63 - lane : lane; const float* ab = AB + (size_t)(rb * 64 + tl) * 64; gcp = ab[dir * 16 + vh]; betap = ab[32 + dir * 16 + vh];
.LBB0_448:
	s_and_b64 vcc, exec, s[42:43]
	s_cbranch_vccz .LBB0_374
	v_mov_b32_e32 v90, v188
	s_lshl_b32 s42, s59, 6
	v_bfe_u32 v60, v90, 4, 2
	v_xor_b32_e32 v0, 63, v60
	v_cndmask_b32_e64 v0, v0, v60, s[40:41]
	v_or_b32_e32 v2, s42, v0
	v_or_b32_e32 v4, 4, v60
	v_xor_b32_e32 v5, 59, v60
	v_ashrrev_i32_e32 v3, 31, v2
	v_cndmask_b32_e64 v4, v5, v4, s[40:41]
	v_lshlrev_b64 v[2:3], 13, v[2:3]
	v_or_b32_e32 v4, s42, v4
	v_or_b32_e32 v10, 8, v60
	v_xor_b32_e32 v11, 55, v60
	v_lshl_add_u64 v[2:3], s[96:97], 0, v[2:3]
	s_lshl_b32 s80, s57, 8
	v_lshlrev_b32_e32 v0, 4, v90
	v_ashrrev_i32_e32 v5, 31, v4
	v_cndmask_b32_e64 v10, v11, v10, s[40:41]
	v_lshl_add_u64 v[2:3], v[2:3], 0, s[80:81]
	v_and_b32_e32 v0, 0xf0, v0
	v_lshlrev_b64 v[4:5], 13, v[4:5]
	v_or_b32_e32 v10, s42, v10
	v_or_b32_e32 v12, 12, v60
	v_xor_b32_e32 v13, 51, v60
	v_lshl_add_u64 v[2:3], v[2:3], 0, v[0:1]
	v_lshl_add_u64 v[4:5], s[96:97], 0, v[4:5]
	v_ashrrev_i32_e32 v11, 31, v10
	v_cndmask_b32_e64 v12, v13, v12, s[40:41]
	v_add_co_u32_e32 v2, vcc, s33, v2
	v_lshl_add_u64 v[4:5], v[4:5], 0, s[80:81]
	v_lshlrev_b64 v[10:11], 13, v[10:11]
	v_or_b32_e32 v12, s42, v12
	s_waitcnt lgkmcnt(14)
	v_or_b32_e32 v18, 16, v60
	v_xor_b32_e32 v19, 47, v60
	v_addc_co_u32_e32 v3, vcc, 0, v3, vcc
	v_lshl_add_u64 v[4:5], v[4:5], 0, v[0:1]
	v_lshl_add_u64 v[10:11], s[96:97], 0, v[10:11]
	v_ashrrev_i32_e32 v13, 31, v12
	v_cndmask_b32_e64 v18, v19, v18, s[40:41]
	v_add_co_u32_e32 v6, vcc, s33, v4
	v_lshl_add_u64 v[10:11], v[10:11], 0, s[80:81]
	v_lshlrev_b64 v[12:13], 13, v[12:13]
	v_or_b32_e32 v18, s42, v18
	v_or_b32_e32 v20, 20, v60
	v_xor_b32_e32 v21, 43, v60
	v_addc_co_u32_e32 v7, vcc, 0, v5, vcc
	v_lshl_add_u64 v[10:11], v[10:11], 0, v[0:1]
	v_lshl_add_u64 v[12:13], s[96:97], 0, v[12:13]
	v_ashrrev_i32_e32 v19, 31, v18
	v_cndmask_b32_e64 v20, v21, v20, s[40:41]
	v_add_co_u32_e32 v10, vcc, s33, v10
	v_lshl_add_u64 v[12:13], v[12:13], 0, s[80:81]
	v_lshlrev_b64 v[18:19], 13, v[18:19]
	v_or_b32_e32 v20, s42, v20
	v_or_b32_e32 v26, 24, v60
	v_xor_b32_e32 v27, 39, v60
	v_addc_co_u32_e32 v11, vcc, 0, v11, vcc
	v_lshl_add_u64 v[12:13], v[12:13], 0, v[0:1]
	v_lshl_add_u64 v[18:19], s[96:97], 0, v[18:19]
	v_ashrrev_i32_e32 v21, 31, v20
	v_cndmask_b32_e64 v26, v27, v26, s[40:41]
	v_add_co_u32_e32 v14, vcc, s33, v12
	v_lshl_add_u64 v[18:19], v[18:19], 0, s[80:81]
	v_lshlrev_b64 v[20:21], 13, v[20:21]
	v_or_b32_e32 v26, s42, v26
	v_or_b32_e32 v28, 28, v60
	v_xor_b32_e32 v29, 35, v60
	v_addc_co_u32_e32 v15, vcc, 0, v13, vcc
	v_lshl_add_u64 v[18:19], v[18:19], 0, v[0:1]
	v_lshl_add_u64 v[20:21], s[96:97], 0, v[20:21]
	v_ashrrev_i32_e32 v27, 31, v26
	v_cndmask_b32_e64 v28, v29, v28, s[40:41]
	v_add_co_u32_e32 v18, vcc, s33, v18
	v_lshl_add_u64 v[20:21], v[20:21], 0, s[80:81]
	v_lshlrev_b64 v[26:27], 13, v[26:27]
	v_or_b32_e32 v28, s42, v28
	v_or_b32_e32 v34, 32, v60
	v_xor_b32_e32 v35, 31, v60
	v_addc_co_u32_e32 v19, vcc, 0, v19, vcc
	v_lshl_add_u64 v[20:21], v[20:21], 0, v[0:1]
	v_lshl_add_u64 v[26:27], s[96:97], 0, v[26:27]
	v_ashrrev_i32_e32 v29, 31, v28
	v_cndmask_b32_e64 v34, v35, v34, s[40:41]
	v_add_co_u32_e32 v22, vcc, s33, v20
	v_lshl_add_u64 v[26:27], v[26:27], 0, s[80:81]
	v_lshlrev_b64 v[28:29], 13, v[28:29]
	v_or_b32_e32 v34, s42, v34
	v_or_b32_e32 v36, 36, v60
	v_xor_b32_e32 v37, 27, v60
	v_addc_co_u32_e32 v23, vcc, 0, v21, vcc
	v_lshl_add_u64 v[26:27], v[26:27], 0, v[0:1]
	v_lshl_add_u64 v[28:29], s[96:97], 0, v[28:29]
	v_ashrrev_i32_e32 v35, 31, v34
	v_cndmask_b32_e64 v36, v37, v36, s[40:41]
	v_add_co_u32_e32 v26, vcc, s33, v26
	v_lshl_add_u64 v[28:29], v[28:29], 0, s[80:81]
	v_lshlrev_b64 v[34:35], 13, v[34:35]
	v_or_b32_e32 v36, s42, v36
	v_or_b32_e32 v42, 40, v60
	v_xor_b32_e32 v43, 23, v60
	v_addc_co_u32_e32 v27, vcc, 0, v27, vcc
	v_lshl_add_u64 v[28:29], v[28:29], 0, v[0:1]
	v_lshl_add_u64 v[34:35], s[96:97], 0, v[34:35]
	v_ashrrev_i32_e32 v37, 31, v36
	v_cndmask_b32_e64 v42, v43, v42, s[40:41]
	v_add_co_u32_e32 v30, vcc, s33, v28
	v_lshl_add_u64 v[34:35], v[34:35], 0, s[80:81]
	v_lshlrev_b64 v[36:37], 13, v[36:37]
	v_or_b32_e32 v42, s42, v42
	v_or_b32_e32 v44, 44, v60
	v_xor_b32_e32 v45, 19, v60
	v_addc_co_u32_e32 v31, vcc, 0, v29, vcc
	v_lshl_add_u64 v[34:35], v[34:35], 0, v[0:1]
	v_lshl_add_u64 v[36:37], s[96:97], 0, v[36:37]
	v_ashrrev_i32_e32 v43, 31, v42
	v_cndmask_b32_e64 v44, v45, v44, s[40:41]
	v_add_co_u32_e32 v34, vcc, s33, v34
	v_lshl_add_u64 v[36:37], v[36:37], 0, s[80:81]
	v_lshlrev_b64 v[42:43], 13, v[42:43]
	v_or_b32_e32 v44, s42, v44
	v_or_b32_e32 v50, 48, v60
	v_xor_b32_e32 v51, 15, v60
	v_addc_co_u32_e32 v35, vcc, 0, v35, vcc
	v_lshl_add_u64 v[36:37], v[36:37], 0, v[0:1]
	v_lshl_add_u64 v[42:43], s[96:97], 0, v[42:43]
	v_ashrrev_i32_e32 v45, 31, v44
	v_cndmask_b32_e64 v50, v51, v50, s[40:41]
	v_add_co_u32_e32 v38, vcc, s33, v36
	v_lshl_add_u64 v[42:43], v[42:43], 0, s[80:81]
	v_lshlrev_b64 v[44:45], 13, v[44:45]
	v_or_b32_e32 v50, s42, v50
	v_or_b32_e32 v52, 52, v60
	v_xor_b32_e32 v53, 11, v60
	v_addc_co_u32_e32 v39, vcc, 0, v37, vcc
	v_lshl_add_u64 v[42:43], v[42:43], 0, v[0:1]
	v_lshl_add_u64 v[44:45], s[96:97], 0, v[44:45]
	v_ashrrev_i32_e32 v51, 31, v50
	v_cndmask_b32_e64 v52, v53, v52, s[40:41]
	v_add_co_u32_e32 v42, vcc, s33, v42
	v_lshl_add_u64 v[44:45], v[44:45], 0, s[80:81]
	v_lshlrev_b64 v[50:51], 13, v[50:51]
	v_or_b32_e32 v52, s42, v52
	v_or_b32_e32 v58, 56, v60
	v_xor_b32_e32 v59, 7, v60
	v_addc_co_u32_e32 v43, vcc, 0, v43, vcc
	v_lshl_add_u64 v[44:45], v[44:45], 0, v[0:1]
	v_lshl_add_u64 v[50:51], s[96:97], 0, v[50:51]
	v_ashrrev_i32_e32 v53, 31, v52
	v_cndmask_b32_e64 v58, v59, v58, s[40:41]
	v_add_co_u32_e32 v46, vcc, s33, v44
	v_lshl_add_u64 v[50:51], v[50:51], 0, s[80:81]
; __device__ __forceinline__ int opaque_tid() { int t = threadIdx.x; asm volatile("" : "+v"(t)); return t; }
; template <int VAR> __device__ __forceinline__ void dn_scan3(LAS unsigned char* lds, const bf16_t* P, const float* AB, const bf16_t* TP, bf16_t* OB) {
;     ...
;                     int rb; bool f_; dn_step_rb(0, dir, b, rb, f_);
;                     const int lane = opaque_tid() & 63, r0 = lane >> 4, c8 = 8 * (lane & 15);
; #pragma unroll
;                     for (int v = 0; v < 16; ++v) { const int ip = r0 + 4 * v, i = dir ? 63 - ip : ip; v16[v] = *(const u32x4*)(P + (size_t)(rb * 64 + i) * 4096 + 2048 + vh * 128 + c8); }
;                     const bf16_t* tp = TP + (size_t)((rb * 16 + vh) * 2 + dir) * 3072;
; #pragma unroll
;                     for (int v = 0; v < 6; ++v) t6[v] = *(const u32x4*)(tp + (lane + 64 * v) * 8);
;                     const int tl = dir ? 63 - lane : lane; const float* ab = AB + (size_t)(rb * 64 + tl) * 64; gcp = ab[dir * 16 + vh]; betap = ab[32 + dir * 16 + vh];
	v_lshlrev_b64 v[52:53], 13, v[52:53]
	v_or_b32_e32 v58, s42, v58
	v_or_b32_e32 v61, 60, v60
	v_xor_b32_e32 v60, 3, v60
	v_addc_co_u32_e32 v47, vcc, 0, v45, vcc
	v_lshl_add_u64 v[50:51], v[50:51], 0, v[0:1]
	v_lshl_add_u64 v[52:53], s[96:97], 0, v[52:53]
	v_ashrrev_i32_e32 v59, 31, v58
	v_cndmask_b32_e64 v60, v60, v61, s[40:41]
	v_add_co_u32_e32 v50, vcc, s33, v50
	v_lshl_add_u64 v[52:53], v[52:53], 0, s[80:81]
	v_lshlrev_b64 v[58:59], 13, v[58:59]
	v_or_b32_e32 v60, s42, v60
	v_addc_co_u32_e32 v51, vcc, 0, v51, vcc
	v_lshl_add_u64 v[52:53], v[52:53], 0, v[0:1]
	v_lshl_add_u64 v[58:59], s[96:97], 0, v[58:59]
	v_ashrrev_i32_e32 v61, 31, v60
	v_add_co_u32_e32 v54, vcc, s33, v52
	v_lshl_add_u64 v[58:59], v[58:59], 0, s[80:81]
	v_lshlrev_b64 v[60:61], 13, v[60:61]
	s_lshl_b32 s43, s59, 5
	s_lshl_b32 s44, s57, 1
	v_addc_co_u32_e32 v55, vcc, 0, v53, vcc
	v_lshl_add_u64 v[58:59], v[58:59], 0, v[0:1]
	v_lshl_add_u64 v[60:61], s[96:97], 0, v[60:61]
	s_or_b32 s43, s43, s44
	v_add_co_u32_e32 v58, vcc, s33, v58
	v_lshl_add_u64 v[60:61], v[60:61], 0, s[80:81]
	s_or_b32 s43, s43, s58
	s_lshl_b32 s48, s57, 7
	v_addc_co_u32_e32 v59, vcc, 0, v59, vcc
	v_lshl_add_u64 v[60:61], v[60:61], 0, v[0:1]
	s_mul_hi_i32 s45, s43, 0x1800
	s_mulk_i32 s43, 0x1800
	v_and_b32_e32 v91, 63, v90
	v_add_co_u32_e32 v62, vcc, s33, v60
	s_add_u32 s44, s4, s43
	s_nop 0
	v_addc_co_u32_e32 v63, vcc, 0, v61, vcc
	s_addc_u32 s45, s5, s45
	v_lshlrev_b32_e32 v0, 4, v91
	global_load_dwordx4 v[2:5], v[2:3], off
	s_nop 0
	global_load_dwordx4 v[6:9], v[6:7], off
	s_nop 0
	global_load_dwordx4 v[10:13], v[10:11], off
	s_nop 0
	global_load_dwordx4 v[14:17], v[14:15], off
	s_nop 0
	global_load_dwordx4 v[18:21], v[18:19], off
	s_nop 0
	global_load_dwordx4 v[22:25], v[22:23], off
	s_nop 0
	global_load_dwordx4 v[26:29], v[26:27], off
	s_nop 0
	global_load_dwordx4 v[30:33], v[30:31], off
	s_nop 0
	global_load_dwordx4 v[34:37], v[34:35], off
	s_nop 0
	global_load_dwordx4 v[38:41], v[38:39], off
	s_nop 0
	global_load_dwordx4 v[42:45], v[42:43], off
	s_nop 0
	global_load_dwordx4 v[46:49], v[46:47], off
	s_nop 0
	global_load_dwordx4 v[50:53], v[50:51], off
	s_nop 0
	global_load_dwordx4 v[54:57], v[54:55], off
	s_nop 0
	global_load_dwordx4 v[58:61], v[58:59], off
	s_nop 0
	global_load_dwordx4 v[62:65], v[62:63], off
	v_lshl_add_u64 v[82:83], s[44:45], 0, v[0:1]
	global_load_dwordx4 v[78:81], v0, s[44:45]
	global_load_dwordx4 v[74:77], v0, s[44:45] offset:1024
	global_load_dwordx4 v[70:73], v0, s[44:45] offset:2048
	global_load_dwordx4 v[66:69], v0, s[44:45] offset:3072
	v_bitop3_b32 v0, v90, 63, v90 bitop3:0xc
	v_cndmask_b32_e64 v0, v0, v91, s[40:41]
	v_or_b32_e32 v90, s42, v0
	v_ashrrev_i32_e32 v91, 31, v90
	v_readlane_b32 s60, v251, 12
	v_lshlrev_b64 v[90:91], 8, v[90:91]
	v_readlane_b32 s61, v251, 13
	s_lshl_b32 s42, s57, 2
	s_lshl_b32 s43, s58, 6
	v_add_co_u32_e32 v82, vcc, s33, v82
	v_lshl_add_u64 v[90:91], s[60:61], 0, v[90:91]
	s_or_b32 s44, s43, s42
	s_mov_b32 s45, s81
	v_addc_co_u32_e32 v83, vcc, 0, v83, vcc
	v_lshl_add_u64 v[90:91], v[90:91], 0, s[44:45]
	global_load_dwordx4 v[86:89], v[82:83], off
	s_nop 0
	global_load_dwordx4 v[82:85], v[82:83], off offset:1024
	s_nop 0
	global_load_dword v92, v[90:91], off
	global_load_dword v93, v[90:91], off offset:128
	s_and_b32 s58, s54, 31
	s_lshl_b32 s56, s56, 8
	s_add_u32 s42, s8, s80
	s_addc_u32 s43, s9, 0
	s_add_u32 s44, s60, s44
	s_mov_b32 s57, 0
	s_addc_u32 s45, s61, 0
	s_mov_b32 s59, -2
	s_lshl_b32 s80, s48, 1
	v_bfe_u32 v156, v188, 4, 2
	v_lshlrev_b32_e32 v157, 4, v188
	v_and_b32_e32 v157, 0xf0, v157
	v_mov_b32_e32 v158, v156
	v_xor_b32_e32 v159, 63, v158
	v_cndmask_b32_e64 v158, v159, v158, s[40:41]
	v_lshl_add_u32 v140, v158, 13, v157
	v_or_b32_e32 v158, 4, v156
	v_xor_b32_e32 v159, 63, v158
	v_cndmask_b32_e64 v158, v159, v158, s[40:41]
	v_lshl_add_u32 v141, v158, 13, v157
	v_or_b32_e32 v158, 8, v156
	v_xor_b32_e32 v159, 63, v158
	v_cndmask_b32_e64 v158, v159, v158, s[40:41]
	v_lshl_add_u32 v142, v158, 13, v157
	v_or_b32_e32 v158, 12, v156
	v_xor_b32_e32 v159, 63, v158
	v_cndmask_b32_e64 v158, v159, v158, s[40:41]
	v_lshl_add_u32 v143, v158, 13, v157
	v_or_b32_e32 v158, 16, v156
	v_xor_b32_e32 v159, 63, v158
	v_cndmask_b32_e64 v158, v159, v158, s[40:41]
	v_lshl_add_u32 v144, v158, 13, v157
	v_or_b32_e32 v158, 20, v156
	v_xor_b32_e32 v159, 63, v158
	v_cndmask_b32_e64 v158, v159, v158, s[40:41]
	v_lshl_add_u32 v145, v158, 13, v157
	v_or_b32_e32 v158, 24, v156
	v_xor_b32_e32 v159, 63, v158
	v_cndmask_b32_e64 v158, v159, v158, s[40:41]
	v_lshl_add_u32 v146, v158, 13, v157
	v_or_b32_e32 v158, 28, v156
	v_xor_b32_e32 v159, 63, v158
	v_cndmask_b32_e64 v158, v159, v158, s[40:41]
	v_lshl_add_u32 v147, v158, 13, v157
	v_or_b32_e32 v158, 32, v156
	v_xor_b32_e32 v159, 63, v158
	v_cndmask_b32_e64 v158, v159, v158, s[40:41]
	v_lshl_add_u32 v148, v158, 13, v157
	v_or_b32_e32 v158, 36, v156
	v_xor_b32_e32 v159, 63, v158
	v_cndmask_b32_e64 v158, v159, v158, s[40:41]
	v_lshl_add_u32 v149, v158, 13, v157
	v_or_b32_e32 v158, 40, v156
	v_xor_b32_e32 v159, 63, v158
	v_cndmask_b32_e64 v158, v159, v158, s[40:41]
	v_lshl_add_u32 v150, v158, 13, v157
	v_or_b32_e32 v158, 44, v156
	v_xor_b32_e32 v159, 63, v158
	v_cndmask_b32_e64 v158, v159, v158, s[40:41]
	v_lshl_add_u32 v151, v158, 13, v157
	v_or_b32_e32 v158, 48, v156
	v_xor_b32_e32 v159, 63, v158
	v_cndmask_b32_e64 v158, v159, v158, s[40:41]
	v_lshl_add_u32 v152, v158, 13, v157
	v_or_b32_e32 v158, 52, v156
	v_xor_b32_e32 v159, 63, v158
	v_cndmask_b32_e64 v158, v159, v158, s[40:41]
	v_lshl_add_u32 v153, v158, 13, v157
	v_or_b32_e32 v158, 56, v156
	v_xor_b32_e32 v159, 63, v158
	v_cndmask_b32_e64 v158, v159, v158, s[40:41]
	v_lshl_add_u32 v154, v158, 13, v157
	v_or_b32_e32 v158, 60, v156
	v_xor_b32_e32 v159, 63, v158
	v_cndmask_b32_e64 v158, v159, v158, s[40:41]
	v_lshl_add_u32 v155, v158, 13, v157
	s_branch .LBB0_451
; template <int VAR> __device__ __forceinline__ void dn_scan3(LAS unsigned char* lds, const bf16_t* P, const float* AB, const bf16_t* TP, bf16_t* OB) {
;     ...
;                     if (j + 1 < 260) {
;                         int rb; bool f_; dn_step_rb(j + 1, dir, b, rb, f_);
; #pragma unroll
;                         for (int v = 0; v < 16; ++v) { const int ip = r0 + 4 * v, i = dir ? 63 - ip : ip; v16[v] = *(const u32x4*)(P + (size_t)(rb * 64 + i) * 4096 + 2048 + vh * 128 + c8); }
;                         const bf16_t* tp = TP + (size_t)((rb * 16 + vh) * 2 + dir) * 3072;
; #pragma unroll
;                         for (int v = 0; v < 6; ++v) t6[v] = *(const u32x4*)(tp + (lane + 64 * v) * 8);
;                         const int tl = dir ? 63 - lane : lane; const float* ab = AB + (size_t)(rb * 64 + tl) * 64; gcp = ab[dir * 16 + vh]; betap = ab[32 + dir * 16 + vh];
;                     }
.LBB0_450:
	s_or_b64 exec, exec, s[48:49]
	s_add_i32 s48, s60, 1
	s_add_i32 s49, s60, -3
	s_cmp_lt_u32 s60, 3
	s_cselect_b32 s60, 2, 0x102
	s_cselect_b32 s49, s48, s49
	s_cselect_b32 s62, s55, s56
	s_add_i32 s63, s60, s57
	s_and_b64 s[60:61], s[40:41], exec
	s_cselect_b32 s60, s49, s63
	s_add_i32 s60, s60, s62
	s_lshl_b32 s49, s60, 6
	s_lshl_b32 s60, s60, 5
	s_or_b32 s60, s60, s58
	s_mul_hi_i32 s61, s60, 0x1800
	s_mulk_i32 s60, 0x1800
	s_add_u32 s60, s4, s60
	s_addc_u32 s61, s5, s61
	s_lshl_b32 s62, s49, 13
	s_add_u32 s62, s96, s62
	s_addc_u32 s63, s97, 0
	s_add_u32 s62, s62, s80
	s_addc_u32 s63, s63, s81
	s_add_u32 s62, s62, s33
	s_addc_u32 s63, s63, 0
	global_load_dwordx4 v[2:5], v140, s[62:63]
	global_load_dwordx4 v[6:9], v141, s[62:63]
	global_load_dwordx4 v[10:13], v142, s[62:63]
	global_load_dwordx4 v[14:17], v143, s[62:63]
	global_load_dwordx4 v[18:21], v144, s[62:63]
	global_load_dwordx4 v[22:25], v145, s[62:63]
	global_load_dwordx4 v[26:29], v146, s[62:63]
	global_load_dwordx4 v[30:33], v147, s[62:63]
	global_load_dwordx4 v[34:37], v148, s[62:63]
	global_load_dwordx4 v[38:41], v149, s[62:63]
	global_load_dwordx4 v[42:45], v150, s[62:63]
	global_load_dwordx4 v[46:49], v151, s[62:63]
	global_load_dwordx4 v[50:53], v152, s[62:63]
	global_load_dwordx4 v[54:57], v153, s[62:63]
	global_load_dwordx4 v[58:61], v154, s[62:63]
	global_load_dwordx4 v[62:65], v155, s[62:63]
	v_lshlrev_b32_e32 v0, 4, v90
	v_lshl_add_u64 v[82:83], s[60:61], 0, v[0:1]
	global_load_dwordx4 v[78:81], v0, s[60:61]
	global_load_dwordx4 v[74:77], v0, s[60:61] offset:1024
	global_load_dwordx4 v[70:73], v0, s[60:61] offset:2048
	global_load_dwordx4 v[66:69], v0, s[60:61] offset:3072
	v_xor_b32_e32 v0, 63, v90
	v_cndmask_b32_e64 v0, v0, v90, s[40:41]
	v_or_b32_e32 v90, s49, v0
	v_ashrrev_i32_e32 v91, 31, v90
	v_add_co_u32_e32 v82, vcc, s33, v82
	v_lshlrev_b64 v[90:91], 8, v[90:91]
	s_nop 0
	v_addc_co_u32_e32 v83, vcc, 0, v83, vcc
	v_lshl_add_u64 v[90:91], s[44:45], 0, v[90:91]
	global_load_dwordx4 v[86:89], v[82:83], off
	s_nop 0
	global_load_dwordx4 v[82:85], v[82:83], off offset:1024
	s_nop 0
	global_load_dword v92, v[90:91], off
	global_load_dword v93, v[90:91], off offset:128
	s_waitcnt lgkmcnt(0)
	s_barrier
	s_add_i32 s59, s59, 1
	s_add_i32 s57, s57, -1
	s_cmpk_eq_i32 s48, 0x103
	s_cbranch_scc1 .LBB0_457
